# experiment: NSA phase v_pk_add_f32 (softmax row sums) split into two v_add_f32 each
# baseline (speedup 1.0000x reference)
.LBB0_1720:
	v_add_u32_e32 v41, s52, v140
	v_subrev_u32_e32 v42, 31, v41
	v_cmp_gt_u32_e32 vcc, 2.0, v42
	v_cvt_f32_u32_e32 v42, v42
	s_nop 0
	v_cndmask_b32_e32 v74, v1, v42, vcc
	v_subrev_u32_e32 v42, 47, v41
	v_cmp_gt_u32_e32 vcc, 2.0, v42
	v_cvt_f32_u32_e32 v42, v42
	s_nop 0
	v_cndmask_b32_e32 v75, v1, v42, vcc
	v_subrev_u32_e32 v42, 63, v41
	v_cmp_gt_u32_e32 vcc, 2.0, v42
	v_cvt_f32_u32_e32 v42, v42
	s_nop 0
	v_cndmask_b32_e32 v76, v1, v42, vcc
	v_add_u32_e32 v42, 0xffffffb1, v41
	v_cmp_gt_u32_e32 vcc, 2.0, v42
	v_cvt_f32_u32_e32 v42, v42
	s_nop 0
	v_cndmask_b32_e32 v77, v1, v42, vcc
	v_add_u32_e32 v42, 0xffffffa1, v41
	v_cmp_gt_u32_e32 vcc, 2.0, v42
	v_cvt_f32_u32_e32 v42, v42
	s_nop 0
	v_cndmask_b32_e32 v78, v1, v42, vcc
	v_add_u32_e32 v42, 0xffffff91, v41
	v_cmp_gt_u32_e32 vcc, 2.0, v42
	v_cvt_f32_u32_e32 v42, v42
	s_nop 0
	v_cndmask_b32_e32 v79, v1, v42, vcc
	v_add_u32_e32 v42, 0xffffff81, v41
	v_cmp_gt_u32_e32 vcc, 2.0, v42
	v_cvt_f32_u32_e32 v42, v42
	v_add_u32_e32 v41, 0xffffff71, v41
	v_cndmask_b32_e32 v80, v1, v42, vcc
	v_cmp_gt_u32_e32 vcc, 2.0, v41
	v_cvt_f32_u32_e32 v41, v41
	s_nop 0
	v_cndmask_b32_e32 v41, v1, v41, vcc
	s_setprio 1
	ds_read_b128 v[42:45], v158
	ds_read_b128 v[46:49], v158 offset:64
	s_waitcnt vmcnt(3) lgkmcnt(1)
	v_mfma_f32_16x16x32_bf16 v[50:53], v[32:35], v[42:45], 0
	s_waitcnt vmcnt(1)
	v_mfma_f32_16x16x32_bf16 v[42:45], v[28:31], v[42:45], 0
	s_waitcnt lgkmcnt(0)
	v_mfma_f32_16x16x32_bf16 v[50:53], v[20:23], v[46:49], v[50:53]
	s_waitcnt vmcnt(0)
	v_mfma_f32_16x16x32_bf16 v[42:45], v[24:27], v[46:49], v[42:45]
	ds_read_b128 v[46:49], v158 offset:136
	ds_read_b128 v[54:57], v158 offset:200
	s_waitcnt lgkmcnt(1)
	v_mfma_f32_16x16x32_bf16 v[58:61], v[32:35], v[46:49], 0
	v_mfma_f32_16x16x32_bf16 v[46:49], v[28:31], v[46:49], 0
	s_waitcnt lgkmcnt(0)
	v_mfma_f32_16x16x32_bf16 v[58:61], v[20:23], v[54:57], v[58:61]
	v_mfma_f32_16x16x32_bf16 v[46:49], v[24:27], v[54:57], v[46:49]
	ds_read_b128 v[54:57], v158 offset:272
	ds_read_b128 v[62:65], v158 offset:336
	s_waitcnt lgkmcnt(1)
	v_mfma_f32_16x16x32_bf16 v[66:69], v[32:35], v[54:57], 0
	v_mfma_f32_16x16x32_bf16 v[54:57], v[28:31], v[54:57], 0
	s_waitcnt lgkmcnt(0)
	v_mfma_f32_16x16x32_bf16 v[66:69], v[20:23], v[62:65], v[66:69]
	v_mfma_f32_16x16x32_bf16 v[54:57], v[24:27], v[62:65], v[54:57]
	ds_read_b128 v[62:65], v158 offset:408
	ds_read_b128 v[70:73], v158 offset:472
	s_waitcnt lgkmcnt(1)
	v_mfma_f32_16x16x32_bf16 v[32:35], v[32:35], v[62:65], 0
	v_mfma_f32_16x16x32_bf16 v[28:31], v[28:31], v[62:65], 0
	s_waitcnt lgkmcnt(0)
	v_mfma_f32_16x16x32_bf16 v[20:23], v[20:23], v[70:73], v[32:35]
	v_mfma_f32_16x16x32_bf16 v[24:27], v[24:27], v[70:73], v[28:31]
	s_setprio 0
	s_nop 3
	v_fma_f32 v28, -v154, v74, v50
	v_exp_f32_e32 v29, v28
	v_fma_f32 v28, -v154, v75, v51
	v_exp_f32_e32 v31, v28
	v_fma_f32 v28, -v154, v76, v52
	v_exp_f32_e32 v33, v28
	v_fma_f32 v28, -v154, v77, v53
	v_exp_f32_e32 v35, v28
	v_fma_f32 v28, -v154, v78, v42
	v_exp_f32_e32 v51, v28
	v_fma_f32 v28, -v154, v79, v43
	v_exp_f32_e32 v43, v28
	v_fma_f32 v28, -v154, v80, v44
	v_exp_f32_e32 v53, v28
	v_fma_f32 v28, -v154, v41, v45
	v_exp_f32_e32 v45, v28
	v_fma_f32 v28, -v155, v74, v58
	v_exp_f32_e32 v28, v28
	v_fma_f32 v30, -v155, v75, v59
	v_exp_f32_e32 v30, v30
	v_fma_f32 v32, -v155, v76, v60
	v_exp_f32_e32 v32, v32
	v_fma_f32 v34, -v155, v77, v61
	v_exp_f32_e32 v34, v34
	v_fma_f32 v42, -v155, v78, v46
	v_exp_f32_e32 v50, v42
	v_fma_f32 v42, -v155, v79, v47
	v_add_f32_e32 v28, 0, v28
	v_add_f32_e32 v29, 0, v29
	v_exp_f32_e32 v42, v42
	v_fma_f32 v44, -v155, v80, v48
	v_add_f32_e32 v28, v30, v28
	v_add_f32_e32 v29, v31, v29
	v_exp_f32_e32 v52, v44
	v_fma_f32 v44, -v155, v41, v49
	v_add_f32_e32 v28, v32, v28
	v_add_f32_e32 v29, v33, v29
	v_exp_f32_e32 v44, v44
	v_add_f32_e32 v28, v34, v28
	v_add_f32_e32 v29, v35, v29
	v_fma_f32 v20, -v157, v74, v20
	v_add_f32_e32 v28, v50, v28
	v_add_f32_e32 v29, v51, v29
	s_addk_i32 s52, 0xfe00
	v_add_f32_e32 v28, v42, v28
	v_add_f32_e32 v29, v43, v29
	s_add_u32 s16, s16, 0x1000
	v_add_f32_e32 v28, v52, v28
	v_add_f32_e32 v29, v53, v29
	s_addc_u32 s17, s17, 0
	v_add_f32_e32 v28, v44, v28
	v_add_f32_e32 v29, v45, v29
	s_add_i32 s22, s51, s52
	v_add_f32_e32 v38, v38, v28
	v_add_f32_e32 v39, v39, v29
	v_fma_f32 v28, -v156, v74, v66
	v_exp_f32_e32 v29, v28
	v_fma_f32 v28, -v156, v75, v67
	v_exp_f32_e32 v31, v28
	v_fma_f32 v28, -v156, v76, v68
	v_exp_f32_e32 v33, v28
	v_fma_f32 v28, -v156, v77, v69
	v_exp_f32_e32 v35, v28
	v_fma_f32 v28, -v156, v78, v54
	v_exp_f32_e32 v43, v28
	v_fma_f32 v28, -v156, v79, v55
	v_exp_f32_e32 v45, v28
	v_fma_f32 v28, -v156, v80, v56
	v_exp_f32_e32 v47, v28
	v_fma_f32 v28, -v156, v41, v57
	v_exp_f32_e32 v49, v28
	v_exp_f32_e32 v28, v20
	v_fma_f32 v20, -v157, v75, v21
	v_exp_f32_e32 v30, v20
	v_fma_f32 v20, -v157, v76, v22
	v_exp_f32_e32 v32, v20
	v_fma_f32 v20, -v157, v77, v23
	v_exp_f32_e32 v34, v20
	v_fma_f32 v20, -v157, v78, v24
	v_exp_f32_e32 v42, v20
	v_fma_f32 v20, -v157, v79, v25
	v_exp_f32_e32 v44, v20
	v_fma_f32 v20, -v157, v80, v26
	v_exp_f32_e32 v46, v20
	v_fma_f32 v20, -v157, v41, v27
	v_exp_f32_e32 v48, v20
	v_add_f32_e32 v20, 0, v28
	v_add_f32_e32 v21, 0, v29
	s_add_i32 s50, s50, 1
	v_add_f32_e32 v20, v30, v20
	v_add_f32_e32 v21, v31, v21
	v_mov_b64_e32 v[26:27], v[18:19]
	v_add_f32_e32 v20, v32, v20
	v_add_f32_e32 v21, v33, v21
	v_mov_b64_e32 v[30:31], v[14:15]
	v_add_f32_e32 v20, v34, v20
	v_add_f32_e32 v21, v35, v21
	v_mov_b64_e32 v[34:35], v[6:7]
	v_add_f32_e32 v20, v42, v20
	v_add_f32_e32 v21, v43, v21
	s_cmp_eq_u32 s22, 0
	v_add_f32_e32 v20, v44, v20
	v_add_f32_e32 v21, v45, v21
	v_mov_b64_e32 v[24:25], v[16:17]
	v_add_f32_e32 v20, v46, v20
	v_add_f32_e32 v21, v47, v21
	v_mov_b64_e32 v[28:29], v[12:13]
	v_add_f32_e32 v20, v48, v20
	v_add_f32_e32 v21, v49, v21
	v_mov_b64_e32 v[32:33], v[4:5]
	v_add_f32_e32 v36, v36, v20
	v_add_f32_e32 v37, v37, v21
	v_mov_b64_e32 v[22:23], v[10:11]
	v_mov_b64_e32 v[20:21], v[8:9]
	s_cbranch_scc1 .LBB0_1724

.LBB0_1724:
	v_mov_b32_e32 v4, v39
	s_nop 1
	v_permlane16_swap_b32 v39, v4
	v_mov_b32_e32 v8, v37
	v_add_f32_e32 v5, v39, v4
	v_mov_b32_e32 v7, v5
	v_mov_b32_e32 v4, v38
	s_nop 1
	v_permlane32_swap_b32 v7, v5
	s_nop 1
	v_permlane16_swap_b32 v38, v4
	s_and_b64 vcc, exec, s[14:15]
	v_add_f32_e32 v4, v38, v4
	v_mov_b32_e32 v6, v4
	s_nop 1
	v_permlane32_swap_b32 v6, v4
	s_nop 1
	v_permlane16_swap_b32 v37, v8
	v_mul_u32_u24_e32 v141, 0x210, v159
	v_add_f32_e32 v9, v37, v8
	v_mov_b32_e32 v11, v9
	v_mov_b32_e32 v8, v36
	s_nop 1
	v_permlane32_swap_b32 v9, v11
	s_nop 1
	v_permlane16_swap_b32 v36, v8
	s_nop 0
	v_add_f32_e32 v10, v36, v8
	v_mov_b32_e32 v8, v10
	s_nop 1
	v_permlane32_swap_b32 v8, v10
	s_cbranch_vccz .LBB0_1865
	v_add_f32_e32 v8, v8, v10
	v_add_f32_e32 v9, v9, v11
	v_add_f32_e32 v4, v6, v4
	v_add_f32_e32 v5, v7, v5
	v_div_scale_f32 v10, s[14:15], v8, v8, 1.0
	v_rcp_f32_e32 v11, v10
	v_readlane_b32 s14, v254, 46
	s_add_u32 s8, s14, s8
	v_readlane_b32 s14, v254, 48
	v_fma_f32 v12, -v10, v11, 1.0
	v_fmac_f32_e32 v11, v12, v11
	v_div_scale_f32 v12, vcc, 1.0, v8, 1.0
	v_mul_f32_e32 v13, v12, v11
	v_fma_f32 v14, -v10, v13, v12
	v_fmac_f32_e32 v13, v14, v11
	v_fma_f32 v10, -v10, v13, v12
	s_addc_u32 s9, s14, s9
	v_div_fmas_f32 v10, v10, v11, v13
	v_div_scale_f32 v11, s[14:15], v9, v9, 1.0
	v_rcp_f32_e32 v12, v11
	v_div_fixup_f32 v10, v10, v8, 1.0
	v_cmp_lt_f32_e32 vcc, 0, v8
	v_div_scale_f32 v6, s[14:15], v4, v4, 1.0
	v_fma_f32 v8, -v11, v12, 1.0
	v_cndmask_b32_e32 v132, 0, v10, vcc
	v_fmac_f32_e32 v12, v8, v12
	v_div_scale_f32 v8, vcc, 1.0, v9, 1.0
	v_mul_f32_e32 v10, v8, v12
	v_fma_f32 v13, -v11, v10, v8
	v_fmac_f32_e32 v10, v13, v12
	v_rcp_f32_e32 v7, v6
	v_fma_f32 v8, -v11, v10, v8
	v_div_fmas_f32 v8, v8, v12, v10
	v_div_fixup_f32 v8, v8, v9, 1.0
	v_cmp_lt_f32_e32 vcc, 0, v9
	v_mov_b32_e32 v20, 0
	v_mul_u32_u24_e32 v162, 0x210, v159
	v_cndmask_b32_e32 v134, 0, v8, vcc
	v_fma_f32 v8, -v6, v7, 1.0
	v_fmac_f32_e32 v7, v8, v7
	v_div_scale_f32 v8, vcc, 1.0, v4, 1.0
	v_mul_f32_e32 v9, v8, v7
	v_fma_f32 v10, -v6, v9, v8
	v_fmac_f32_e32 v9, v10, v7
	v_fma_f32 v6, -v6, v9, v8
	v_div_fmas_f32 v6, v6, v7, v9
	v_div_scale_f32 v7, s[14:15], v5, v5, 1.0
	v_rcp_f32_e32 v8, v7
	v_div_fixup_f32 v6, v6, v4, 1.0
	v_cmp_lt_f32_e32 vcc, 0, v4
	s_mov_b32 s14, 1
	v_fma_f32 v4, -v7, v8, 1.0
	v_cndmask_b32_e32 v136, 0, v6, vcc
	v_fmac_f32_e32 v8, v4, v8
	v_div_scale_f32 v4, vcc, 1.0, v5, 1.0
	v_mul_f32_e32 v6, v4, v8
	v_fma_f32 v9, -v7, v6, v4
	v_fmac_f32_e32 v6, v9, v8
	v_fma_f32 v4, -v7, v6, v4
	v_and_or_b32 v7, v149, 24, v148
	v_lshl_add_u32 v142, v7, 7, v145
	v_mov_b32_e32 v7, v2
	v_mov_b32_e32 v9, v142
	v_div_fmas_f32 v4, v4, v8, v6
	v_add_u32_e32 v10, 64, v9
	v_add_u32_e32 v11, 0x200, v9
	global_load_dwordx4 v[116:119], v10, s[6:7]
	global_load_dwordx4 v[120:123], v11, s[6:7]
	v_add_u32_e32 v10, 0x240, v9
	global_load_dwordx4 v[124:127], v9, s[6:7]
	global_load_dwordx4 v[100:103], v7, s[8:9]
	v_add_u32_e32 v9, 0x4000, v7
	global_load_dwordx4 v[128:131], v10, s[6:7]
	global_load_dwordx4 v[104:107], v9, s[8:9]
	v_add_u32_e32 v9, 0x8000, v7
	v_add_u32_e32 v7, 0xc000, v7
	global_load_dwordx4 v[108:111], v9, s[8:9]
	global_load_dwordx4 v[112:115], v7, s[8:9]
	v_div_fixup_f32 v4, v4, v5, 1.0
	v_cmp_lt_f32_e32 vcc, 0, v5
	v_readlane_b32 s6, v254, 25
	v_readlane_b32 s8, v254, 58
	v_cndmask_b32_e32 v138, 0, v4, vcc
	v_mov_b32_e32 v133, v132
	v_mov_b32_e32 v135, v134
	v_mov_b32_e32 v137, v136
	v_mov_b32_e32 v139, v138
	v_lshl_add_u32 v143, v144, 3, v161
	s_lshl_b32 s15, s27, 9
	s_mov_b32 s16, 0
	v_readlane_b32 s7, v254, 26
	v_readlane_b32 s9, v254, 59
	v_mov_b32_e32 v21, v20
	v_mov_b32_e32 v22, v20
	v_mov_b32_e32 v23, v20
	v_mov_b32_e32 v64, v20
	v_mov_b32_e32 v65, v20
	v_mov_b32_e32 v66, v20
	v_mov_b32_e32 v67, v20
	v_mov_b32_e32 v60, v20
	v_mov_b32_e32 v61, v20
	v_mov_b32_e32 v62, v20
	v_mov_b32_e32 v63, v20
	v_mov_b32_e32 v56, v20
	v_mov_b32_e32 v57, v20
	v_mov_b32_e32 v58, v20
	v_mov_b32_e32 v59, v20
	v_mov_b32_e32 v52, v20
	v_mov_b32_e32 v53, v20
	v_mov_b32_e32 v54, v20
	v_mov_b32_e32 v55, v20
	v_mov_b32_e32 v48, v20
	v_mov_b32_e32 v49, v20
	v_mov_b32_e32 v50, v20
	v_mov_b32_e32 v51, v20
	v_mov_b32_e32 v44, v20
	v_mov_b32_e32 v45, v20
	v_mov_b32_e32 v46, v20
	v_mov_b32_e32 v47, v20
	v_mov_b32_e32 v40, v20
	v_mov_b32_e32 v41, v20
	v_mov_b32_e32 v42, v20
	v_mov_b32_e32 v43, v20
	v_mov_b32_e32 v36, v20
	v_mov_b32_e32 v37, v20
	v_mov_b32_e32 v38, v20
	v_mov_b32_e32 v39, v20
	v_mov_b32_e32 v32, v20
	v_mov_b32_e32 v33, v20
	v_mov_b32_e32 v34, v20
	v_mov_b32_e32 v35, v20
	v_mov_b32_e32 v28, v20
	v_mov_b32_e32 v29, v20
	v_mov_b32_e32 v30, v20
	v_mov_b32_e32 v31, v20
	v_mov_b32_e32 v24, v20
	v_mov_b32_e32 v25, v20
	v_mov_b32_e32 v26, v20
	v_mov_b32_e32 v27, v20
	v_mov_b32_e32 v4, v20
	v_mov_b32_e32 v5, v20
	v_mov_b32_e32 v6, v20
	v_mov_b32_e32 v7, v20
	v_mov_b32_e32 v8, v20
	v_mov_b32_e32 v9, v20
	v_mov_b32_e32 v10, v20
	v_mov_b32_e32 v11, v20
	v_mov_b32_e32 v12, v20
	v_mov_b32_e32 v13, v20
	v_mov_b32_e32 v14, v20
	v_mov_b32_e32 v15, v20
	v_mov_b32_e32 v16, v20
	v_mov_b32_e32 v17, v20
	v_mov_b32_e32 v18, v20
	v_mov_b32_e32 v19, v20
	s_cmp_ge_u32 s14, s27
	s_cbranch_scc1 .LBB0_1728
	s_branch .LBB0_1727

.LBB0_1877:
	s_lshr_b32 s6, s82, 5
	s_cmp_lt_u32 s82, 32
	s_cselect_b64 vcc, -1, 0
	s_cmp_eq_u32 s6, 1
	s_cselect_b64 s[4:5], -1, 0
	s_cmp_eq_u32 s6, 2
	s_cselect_b64 s[6:7], -1, 0
	v_cndmask_b32_e64 v168, v166, v165, s[6:7]
	v_cndmask_b32_e64 v168, v168, v164, s[4:5]
	v_cndmask_b32_e32 v168, v168, v163, vcc
	s_lshl_b32 s4, s82, 6
	s_lshl_b32 s5, s85, 5
	v_lshrrev_b32_e32 v168, s82, v168
	v_and_b32_e32 v168, 1, v168
	s_add_i32 s4, s4, s5
	v_cmp_eq_u32_e32 vcc, 1, v168
	v_add_u32_e32 v168, s4, v162
	v_sub_u32_e32 v169, v167, v168
	v_cmp_gt_u32_e64 s[4:5], 2.0, v169
	v_cvt_f32_i32_e32 v169, v169
	s_and_b64 s[4:5], s[4:5], vcc
	v_cndmask_b32_e64 v200, v1, v169, s[4:5]
	v_xad_u32 v169, v168, -1, v167
	v_cmp_gt_u32_e64 s[4:5], 2.0, v169
	v_cvt_f32_i32_e32 v169, v169
	s_and_b64 s[4:5], s[4:5], vcc
	v_cndmask_b32_e64 v201, v1, v169, s[4:5]
	v_or_b32_e32 v169, 2, v168
	v_sub_u32_e32 v169, v167, v169
	v_cmp_gt_u32_e64 s[4:5], 2.0, v169
	v_cvt_f32_i32_e32 v169, v169
	s_and_b64 s[4:5], s[4:5], vcc
	v_cndmask_b32_e64 v202, v1, v169, s[4:5]
	v_or_b32_e32 v169, 3, v168
	v_sub_u32_e32 v169, v167, v169
	v_cmp_gt_u32_e64 s[4:5], 2.0, v169
	v_cvt_f32_i32_e32 v169, v169
	s_and_b64 s[4:5], s[4:5], vcc
	v_cndmask_b32_e64 v203, v1, v169, s[4:5]
	v_or_b32_e32 v169, 4, v168
	v_sub_u32_e32 v169, v167, v169
	v_cmp_gt_u32_e64 s[4:5], 2.0, v169
	v_cvt_f32_i32_e32 v169, v169
	s_and_b64 s[4:5], s[4:5], vcc
	v_cndmask_b32_e64 v204, v1, v169, s[4:5]
	v_or_b32_e32 v169, 5, v168
	v_sub_u32_e32 v169, v167, v169
	v_cmp_gt_u32_e64 s[4:5], 2.0, v169
	v_cvt_f32_i32_e32 v169, v169
	s_and_b64 s[4:5], s[4:5], vcc
	v_cndmask_b32_e64 v205, v1, v169, s[4:5]
	v_or_b32_e32 v169, 6, v168
	v_sub_u32_e32 v169, v167, v169
	v_cmp_gt_u32_e64 s[4:5], 2.0, v169
	v_cvt_f32_i32_e32 v169, v169
	v_or_b32_e32 v168, 7, v168
	s_and_b64 s[4:5], s[4:5], vcc
	v_sub_u32_e32 v168, v167, v168
	v_cndmask_b32_e64 v206, v1, v169, s[4:5]
	v_cmp_gt_u32_e64 s[4:5], 2.0, v168
	v_cvt_f32_i32_e32 v168, v168
	s_and_b64 vcc, s[4:5], vcc
	v_cndmask_b32_e32 v207, v1, v168, vcc
	s_setprio 1
	ds_read_b128 v[168:171], v158
	ds_read_b128 v[172:175], v158 offset:64
	s_waitcnt vmcnt(7) lgkmcnt(1)
	v_mfma_f32_16x16x32_bf16 v[176:179], v[116:119], v[168:171], 0
	s_waitcnt vmcnt(5)
	v_mfma_f32_16x16x32_bf16 v[168:171], v[124:127], v[168:171], 0
	s_waitcnt lgkmcnt(0)
	v_mfma_f32_16x16x32_bf16 v[176:179], v[120:123], v[172:175], v[176:179]
	s_waitcnt vmcnt(4)
	v_mfma_f32_16x16x32_bf16 v[168:171], v[128:131], v[172:175], v[168:171]
	ds_read_b128 v[172:175], v158 offset:136
	ds_read_b128 v[180:183], v158 offset:200
	s_waitcnt lgkmcnt(1)
	v_mfma_f32_16x16x32_bf16 v[184:187], v[116:119], v[172:175], 0
	v_mfma_f32_16x16x32_bf16 v[172:175], v[124:127], v[172:175], 0
	s_waitcnt lgkmcnt(0)
	v_mfma_f32_16x16x32_bf16 v[184:187], v[120:123], v[180:183], v[184:187]
	v_mfma_f32_16x16x32_bf16 v[172:175], v[128:131], v[180:183], v[172:175]
	ds_read_b128 v[180:183], v158 offset:272
	ds_read_b128 v[188:191], v158 offset:336
	s_waitcnt lgkmcnt(1)
	v_mfma_f32_16x16x32_bf16 v[192:195], v[116:119], v[180:183], 0
	v_mfma_f32_16x16x32_bf16 v[180:183], v[124:127], v[180:183], 0
	s_waitcnt lgkmcnt(0)
	v_mfma_f32_16x16x32_bf16 v[192:195], v[120:123], v[188:191], v[192:195]
	v_mfma_f32_16x16x32_bf16 v[180:183], v[128:131], v[188:191], v[180:183]
	ds_read_b128 v[188:191], v158 offset:408
	ds_read_b128 v[196:199], v158 offset:472
	s_waitcnt lgkmcnt(1)
	v_mfma_f32_16x16x32_bf16 v[116:119], v[116:119], v[188:191], 0
	s_waitcnt lgkmcnt(0)
	v_mfma_f32_16x16x32_bf16 v[116:119], v[120:123], v[196:199], v[116:119]
	v_mfma_f32_16x16x32_bf16 v[120:123], v[124:127], v[188:191], 0
	v_mfma_f32_16x16x32_bf16 v[120:123], v[128:131], v[196:199], v[120:123]
	s_setprio 0
	v_fma_f32 v124, -v154, v200, v176
	v_exp_f32_e32 v129, v124
	v_fma_f32 v124, -v154, v201, v177
	v_exp_f32_e32 v131, v124
	v_fma_f32 v124, -v154, v202, v178
	v_fma_f32 v128, -v155, v200, v184
	v_exp_f32_e32 v177, v124
	v_fma_f32 v124, -v154, v203, v179
	v_exp_f32_e32 v128, v128
	v_fma_f32 v130, -v155, v201, v185
	v_exp_f32_e32 v179, v124
	v_fma_f32 v124, -v154, v204, v168
	v_exp_f32_e32 v130, v130
	v_fma_f32 v168, -v155, v202, v186
	v_exp_f32_e32 v176, v168
	v_fma_f32 v168, -v155, v203, v187
	v_exp_f32_e32 v178, v168
	v_fma_f32 v168, -v155, v204, v172
	v_exp_f32_e32 v189, v124
	v_fma_f32 v124, -v154, v205, v169
	v_exp_f32_e32 v188, v168
	v_fma_f32 v168, -v155, v205, v173
	v_add_f32_e32 v172, 0, v128
	v_add_f32_e32 v173, 0, v129
	v_exp_f32_e32 v169, v124
	v_fma_f32 v124, -v154, v206, v170
	v_exp_f32_e32 v168, v168
	v_fma_f32 v170, -v155, v206, v174
	v_add_f32_e32 v172, v130, v172
	v_add_f32_e32 v173, v131, v173
	v_exp_f32_e32 v191, v124
	v_fma_f32 v124, -v154, v207, v171
	v_exp_f32_e32 v190, v170
	v_fma_f32 v170, -v155, v207, v175
	v_add_f32_e32 v172, v176, v172
	v_add_f32_e32 v173, v177, v173
	v_exp_f32_e32 v171, v124
	v_exp_f32_e32 v170, v170
	v_add_f32_e32 v172, v178, v172
	v_add_f32_e32 v173, v179, v173
	v_fma_f32 v116, -v157, v200, v116
	v_add_f32_e32 v172, v188, v172
	v_add_f32_e32 v173, v189, v173
	v_cvt_pk_bf16_f32 v128, v128, v130
	v_add_f32_e32 v172, v168, v172
	v_add_f32_e32 v173, v169, v173
	v_cvt_pk_bf16_f32 v130, v188, v168
	v_add_f32_e32 v172, v190, v172
	v_add_f32_e32 v173, v191, v173
	v_fma_f32 v168, -v156, v200, v192
	v_add_f32_e32 v172, v170, v172
	v_add_f32_e32 v173, v171, v173
	v_cvt_pk_bf16_f32 v124, v129, v131
	v_add_f32_e32 v148, v148, v172
	v_add_f32_e32 v149, v149, v173
	v_exp_f32_e32 v172, v116
	v_fma_f32 v116, -v157, v201, v117
	v_exp_f32_e32 v174, v116
	v_fma_f32 v116, -v157, v202, v118
	v_cvt_pk_bf16_f32 v129, v176, v178
	v_exp_f32_e32 v173, v168
	v_fma_f32 v168, -v156, v201, v193
	v_exp_f32_e32 v176, v116
	v_fma_f32 v116, -v157, v203, v119
	v_exp_f32_e32 v175, v168
	v_fma_f32 v168, -v156, v202, v194
	v_exp_f32_e32 v178, v116
	v_fma_f32 v116, -v157, v204, v120
	v_cvt_pk_bf16_f32 v125, v177, v179
	v_exp_f32_e32 v177, v168
	v_fma_f32 v168, -v156, v203, v195
	v_exp_f32_e32 v184, v116
	v_fma_f32 v116, -v157, v205, v121
	v_exp_f32_e32 v179, v168
	v_fma_f32 v168, -v156, v204, v180
	v_exp_f32_e32 v180, v116
	v_fma_f32 v116, -v157, v206, v122
	v_exp_f32_e32 v185, v168
	v_fma_f32 v168, -v156, v205, v181
	v_exp_f32_e32 v186, v116
	v_fma_f32 v116, -v157, v207, v123
	v_exp_f32_e32 v181, v168
	v_fma_f32 v168, -v156, v206, v182
	v_exp_f32_e32 v182, v116
	v_add_f32_e32 v116, 0, v172
	v_add_f32_e32 v117, 0, v173
	v_exp_f32_e32 v187, v168
	v_add_f32_e32 v116, v174, v116
	v_add_f32_e32 v117, v175, v117
	v_fma_f32 v168, -v156, v207, v183
	v_add_f32_e32 v116, v176, v116
	v_add_f32_e32 v117, v177, v117
	v_exp_f32_e32 v183, v168
	v_add_f32_e32 v116, v178, v116
	v_add_f32_e32 v117, v179, v117
	v_cvt_pk_bf16_f32 v126, v189, v169
	v_add_f32_e32 v116, v184, v116
	v_add_f32_e32 v117, v185, v117
	v_cvt_pk_bf16_f32 v127, v191, v171
	v_add_f32_e32 v116, v180, v116
	v_add_f32_e32 v117, v181, v117
	v_cvt_pk_bf16_f32 v131, v190, v170
	v_add_f32_e32 v116, v186, v116
	v_add_f32_e32 v117, v187, v117
	v_cvt_pk_bf16_f32 v168, v173, v175
	v_add_f32_e32 v116, v182, v116
	v_add_f32_e32 v117, v183, v117
	v_cvt_pk_bf16_f32 v169, v177, v179
	v_add_f32_e32 v144, v144, v116
	v_add_f32_e32 v145, v145, v117
	v_cvt_pk_bf16_f32 v170, v185, v181
	v_cvt_pk_bf16_f32 v171, v187, v183
	v_cvt_pk_bf16_f32 v116, v172, v174
	v_cvt_pk_bf16_f32 v117, v176, v178
	v_cvt_pk_bf16_f32 v118, v184, v180
	v_cvt_pk_bf16_f32 v119, v186, v182
	s_setprio 1
	s_waitcnt vmcnt(3)
	v_mfma_f32_16x16x32_bf16 v[60:63], v[68:71], v[124:127], v[60:63]
	s_waitcnt vmcnt(2)
	v_mfma_f32_16x16x32_bf16 v[64:67], v[72:75], v[124:127], v[64:67]
	s_waitcnt vmcnt(1)
	v_mfma_f32_16x16x32_bf16 v[56:59], v[76:79], v[124:127], v[56:59]
	s_waitcnt vmcnt(0)
	v_mfma_f32_16x16x32_bf16 v[52:55], v[80:83], v[124:127], v[52:55]
	v_mfma_f32_16x16x32_bf16 v[48:51], v[68:71], v[128:131], v[48:51]
	v_mfma_f32_16x16x32_bf16 v[44:47], v[72:75], v[128:131], v[44:47]
	v_mfma_f32_16x16x32_bf16 v[40:43], v[76:79], v[128:131], v[40:43]
	v_mfma_f32_16x16x32_bf16 v[36:39], v[80:83], v[128:131], v[36:39]
	v_mfma_f32_16x16x32_bf16 v[32:35], v[68:71], v[168:171], v[32:35]
	v_mfma_f32_16x16x32_bf16 v[28:31], v[72:75], v[168:171], v[28:31]
	v_mfma_f32_16x16x32_bf16 v[24:27], v[76:79], v[168:171], v[24:27]
	v_mfma_f32_16x16x32_bf16 v[20:23], v[80:83], v[168:171], v[20:23]
	v_mfma_f32_16x16x32_bf16 v[16:19], v[68:71], v[116:119], v[16:19]
	v_mfma_f32_16x16x32_bf16 v[12:15], v[72:75], v[116:119], v[12:15]
	v_mfma_f32_16x16x32_bf16 v[8:11], v[76:79], v[116:119], v[8:11]
	v_mfma_f32_16x16x32_bf16 v[4:7], v[80:83], v[116:119], v[4:7]
	s_setprio 0
	s_and_b64 vcc, exec, s[8:9]
	s_cbranch_vccnz .LBB0_1883
	v_mov_b64_e32 v[118:119], v[86:87]
	v_mov_b64_e32 v[122:123], v[90:91]
	v_mov_b64_e32 v[126:127], v[94:95]
	v_mov_b64_e32 v[130:131], v[98:99]
	v_mov_b64_e32 v[68:69], v[100:101]
	v_mov_b64_e32 v[72:73], v[104:105]
	v_mov_b64_e32 v[76:77], v[108:109]
	v_mov_b64_e32 v[80:81], v[112:113]
	s_mov_b32 s85, s83
	s_mov_b32 s82, s84
	v_mov_b64_e32 v[116:117], v[84:85]
	v_mov_b64_e32 v[120:121], v[88:89]
	v_mov_b64_e32 v[124:125], v[92:93]
	v_mov_b64_e32 v[128:129], v[96:97]
	v_mov_b64_e32 v[70:71], v[102:103]
	v_mov_b64_e32 v[74:75], v[106:107]
	v_mov_b64_e32 v[78:79], v[110:111]
	v_mov_b64_e32 v[82:83], v[114:115]
	s_cmp_lg_u32 s85, 1
	s_mov_b32 s83, 1
	s_cbranch_scc1 .LBB0_1875

.LBB0_1887:
	v_add_u32_e32 v162, 7, v159
	v_cvt_f32_i32_e32 v163, v162
	v_add_u32_e32 v164, 6, v159
	v_cvt_f32_i32_e32 v165, v164
	v_cmp_gt_u32_e32 vcc, s46, v162
	v_add_u32_e32 v162, 5, v159
	s_nop 0
	v_cndmask_b32_e32 v194, v1, v163, vcc
	v_cvt_f32_i32_e32 v163, v162
	v_cmp_gt_u32_e32 vcc, s46, v164
	v_add_u32_e32 v164, 3, v159
	s_nop 0
	v_cndmask_b32_e32 v195, v1, v165, vcc
	v_cmp_gt_u32_e32 vcc, s46, v162
	v_add_u32_e32 v162, 4, v159
	v_cvt_f32_i32_e32 v165, v164
	v_cndmask_b32_e32 v196, v1, v163, vcc
	v_cvt_f32_i32_e32 v163, v162
	v_cmp_gt_u32_e32 vcc, s46, v162
	v_add_u32_e32 v162, 2, v159
	s_nop 0
	v_cndmask_b32_e32 v197, v1, v163, vcc
	v_cmp_gt_u32_e32 vcc, s46, v164
	v_cvt_f32_i32_e32 v163, v162
	v_add_u32_e32 v164, 1, v159
	v_cndmask_b32_e32 v198, v1, v165, vcc
	v_cvt_f32_i32_e32 v165, v164
	v_cmp_gt_u32_e32 vcc, s46, v162
	v_cvt_f32_i32_e32 v162, v159
	s_nop 0
	v_cndmask_b32_e32 v199, v1, v163, vcc
	v_cmp_gt_u32_e32 vcc, s46, v164
	s_nop 1
	v_cndmask_b32_e32 v200, v1, v165, vcc
	v_cmp_gt_u32_e32 vcc, s46, v159
	s_nop 1
	v_cndmask_b32_e32 v201, v1, v162, vcc
	s_setprio 1
	ds_read_b128 v[162:165], v158
	ds_read_b128 v[166:169], v158 offset:64
	s_waitcnt vmcnt(0) lgkmcnt(1)
	v_mfma_f32_16x16x32_bf16 v[170:173], v[128:131], v[162:165], 0
	v_mfma_f32_16x16x32_bf16 v[162:165], v[120:123], v[162:165], 0
	s_waitcnt lgkmcnt(0)
	v_mfma_f32_16x16x32_bf16 v[170:173], v[124:127], v[166:169], v[170:173]
	v_mfma_f32_16x16x32_bf16 v[162:165], v[116:119], v[166:169], v[162:165]
	ds_read_b128 v[166:169], v158 offset:136
	ds_read_b128 v[174:177], v158 offset:200
	s_waitcnt lgkmcnt(1)
	v_mfma_f32_16x16x32_bf16 v[178:181], v[128:131], v[166:169], 0
	v_mfma_f32_16x16x32_bf16 v[166:169], v[120:123], v[166:169], 0
	s_waitcnt lgkmcnt(0)
	v_mfma_f32_16x16x32_bf16 v[178:181], v[124:127], v[174:177], v[178:181]
	v_mfma_f32_16x16x32_bf16 v[166:169], v[116:119], v[174:177], v[166:169]
	ds_read_b128 v[174:177], v158 offset:272
	ds_read_b128 v[182:185], v158 offset:336
	s_waitcnt lgkmcnt(1)
	v_mfma_f32_16x16x32_bf16 v[186:189], v[128:131], v[174:177], 0
	v_mfma_f32_16x16x32_bf16 v[174:177], v[120:123], v[174:177], 0
	s_waitcnt lgkmcnt(0)
	v_mfma_f32_16x16x32_bf16 v[186:189], v[124:127], v[182:185], v[186:189]
	v_mfma_f32_16x16x32_bf16 v[174:177], v[116:119], v[182:185], v[174:177]
	ds_read_b128 v[182:185], v158 offset:408
	ds_read_b128 v[190:193], v158 offset:472
	s_waitcnt lgkmcnt(1)
	v_mfma_f32_16x16x32_bf16 v[128:131], v[128:131], v[182:185], 0
	v_mfma_f32_16x16x32_bf16 v[120:123], v[120:123], v[182:185], 0
	s_waitcnt lgkmcnt(0)
	v_mfma_f32_16x16x32_bf16 v[124:127], v[124:127], v[190:193], v[128:131]
	v_mfma_f32_16x16x32_bf16 v[116:119], v[116:119], v[190:193], v[120:123]
	s_setprio 0
	s_nop 3
	v_fma_f32 v120, -v154, v194, v170
	v_exp_f32_e32 v129, v120
	v_fma_f32 v120, -v154, v195, v171
	v_exp_f32_e32 v131, v120
	v_fma_f32 v120, -v154, v196, v172
	v_fma_f32 v128, -v155, v194, v178
	v_exp_f32_e32 v171, v120
	v_fma_f32 v120, -v154, v197, v173
	v_exp_f32_e32 v128, v128
	v_fma_f32 v130, -v155, v195, v179
	v_exp_f32_e32 v173, v120
	v_fma_f32 v120, -v154, v198, v162
	v_exp_f32_e32 v130, v130
	v_fma_f32 v162, -v155, v196, v180
	v_exp_f32_e32 v170, v162
	v_fma_f32 v162, -v155, v197, v181
	v_exp_f32_e32 v172, v162
	v_fma_f32 v162, -v155, v198, v166
	v_exp_f32_e32 v183, v120
	v_fma_f32 v120, -v154, v199, v163
	v_exp_f32_e32 v182, v162
	v_fma_f32 v162, -v155, v199, v167
	v_add_f32_e32 v166, 0, v128
	v_add_f32_e32 v167, 0, v129
	v_exp_f32_e32 v163, v120
	v_fma_f32 v120, -v154, v200, v164
	v_exp_f32_e32 v162, v162
	v_fma_f32 v164, -v155, v200, v168
	v_add_f32_e32 v166, v130, v166
	v_add_f32_e32 v167, v131, v167
	v_exp_f32_e32 v185, v120
	v_fma_f32 v120, -v154, v201, v165
	v_exp_f32_e32 v184, v164
	v_fma_f32 v164, -v155, v201, v169
	v_add_f32_e32 v166, v170, v166
	v_add_f32_e32 v167, v171, v167
	v_exp_f32_e32 v165, v120
	v_exp_f32_e32 v164, v164
	v_add_f32_e32 v166, v172, v166
	v_add_f32_e32 v167, v173, v167
	v_cvt_pk_bf16_f32 v128, v128, v130
	v_add_f32_e32 v166, v182, v166
	v_add_f32_e32 v167, v183, v167
	v_cvt_pk_bf16_f32 v130, v182, v162
	v_add_f32_e32 v166, v162, v166
	v_add_f32_e32 v167, v163, v167
	v_fma_f32 v162, -v156, v194, v186
	v_add_f32_e32 v166, v184, v166
	v_add_f32_e32 v167, v185, v167
	v_fma_f32 v124, -v157, v194, v124
	v_add_f32_e32 v166, v164, v166
	v_add_f32_e32 v167, v165, v167
	v_fma_f32 v116, -v157, v198, v116
	v_add_f32_e32 v148, v148, v166
	v_add_f32_e32 v149, v149, v167
	v_exp_f32_e32 v167, v162
	v_fma_f32 v162, -v156, v195, v187
	v_exp_f32_e32 v169, v162
	v_fma_f32 v162, -v156, v196, v188
	v_exp_f32_e32 v166, v124
	v_fma_f32 v124, -v157, v195, v125
	v_cvt_pk_bf16_f32 v121, v171, v173
	v_exp_f32_e32 v171, v162
	v_fma_f32 v162, -v156, v197, v189
	v_exp_f32_e32 v168, v124
	v_fma_f32 v124, -v157, v196, v126
	v_exp_f32_e32 v178, v116
	v_fma_f32 v116, -v157, v199, v117
	v_cvt_pk_bf16_f32 v120, v129, v131
	v_cvt_pk_bf16_f32 v129, v170, v172
	v_exp_f32_e32 v173, v162
	v_fma_f32 v162, -v156, v198, v174
	v_exp_f32_e32 v170, v124
	v_fma_f32 v124, -v157, v197, v127
	v_exp_f32_e32 v174, v116
	v_fma_f32 v116, -v157, v200, v118
	v_exp_f32_e32 v179, v162
	v_fma_f32 v162, -v156, v199, v175
	v_exp_f32_e32 v172, v124
	v_exp_f32_e32 v180, v116
	v_fma_f32 v116, -v157, v201, v119
	v_exp_f32_e32 v175, v162
	v_fma_f32 v162, -v156, v200, v176
	v_exp_f32_e32 v176, v116
	v_add_f32_e32 v116, 0, v166
	v_add_f32_e32 v117, 0, v167
	v_exp_f32_e32 v181, v162
	v_add_f32_e32 v116, v168, v116
	v_add_f32_e32 v117, v169, v117
	v_fma_f32 v162, -v156, v201, v177
	v_add_f32_e32 v116, v170, v116
	v_add_f32_e32 v117, v171, v117
	v_exp_f32_e32 v177, v162
	v_add_f32_e32 v116, v172, v116
	v_add_f32_e32 v117, v173, v117
	v_cvt_pk_bf16_f32 v122, v183, v163
	v_add_f32_e32 v116, v178, v116
	v_add_f32_e32 v117, v179, v117
	v_cvt_pk_bf16_f32 v123, v185, v165
	v_add_f32_e32 v116, v174, v116
	v_add_f32_e32 v117, v175, v117
	v_cvt_pk_bf16_f32 v131, v184, v164
	v_add_f32_e32 v116, v180, v116
	v_add_f32_e32 v117, v181, v117
	v_cvt_pk_bf16_f32 v162, v167, v169
	v_add_f32_e32 v116, v176, v116
	v_add_f32_e32 v117, v177, v117
	v_cvt_pk_bf16_f32 v163, v171, v173
	v_add_f32_e32 v144, v144, v116
	v_add_f32_e32 v145, v145, v117
	v_cvt_pk_bf16_f32 v164, v179, v175
	v_cvt_pk_bf16_f32 v165, v181, v177
	v_cvt_pk_bf16_f32 v116, v166, v168
	v_cvt_pk_bf16_f32 v117, v170, v172
	v_cvt_pk_bf16_f32 v118, v178, v174
	v_cvt_pk_bf16_f32 v119, v180, v176
	s_setprio 1
	v_mfma_f32_16x16x32_bf16 v[52:55], v[112:115], v[120:123], v[52:55]
	v_mfma_f32_16x16x32_bf16 v[64:67], v[108:111], v[120:123], v[64:67]
	v_mfma_f32_16x16x32_bf16 v[56:59], v[104:107], v[120:123], v[56:59]
	v_mfma_f32_16x16x32_bf16 v[60:63], v[100:103], v[120:123], v[60:63]
	v_mfma_f32_16x16x32_bf16 v[48:51], v[112:115], v[128:131], v[48:51]
	v_mfma_f32_16x16x32_bf16 v[44:47], v[108:111], v[128:131], v[44:47]
	v_mfma_f32_16x16x32_bf16 v[36:39], v[104:107], v[128:131], v[36:39]
	v_mfma_f32_16x16x32_bf16 v[40:43], v[100:103], v[128:131], v[40:43]
	v_mfma_f32_16x16x32_bf16 v[32:35], v[112:115], v[162:165], v[32:35]
	v_mfma_f32_16x16x32_bf16 v[28:31], v[108:111], v[162:165], v[28:31]
	v_mfma_f32_16x16x32_bf16 v[20:23], v[104:107], v[162:165], v[20:23]
	v_mfma_f32_16x16x32_bf16 v[24:27], v[100:103], v[162:165], v[24:27]
	v_mfma_f32_16x16x32_bf16 v[16:19], v[112:115], v[116:119], v[16:19]
	v_mfma_f32_16x16x32_bf16 v[12:15], v[108:111], v[116:119], v[12:15]
	v_mfma_f32_16x16x32_bf16 v[8:11], v[104:107], v[116:119], v[8:11]
	v_mfma_f32_16x16x32_bf16 v[4:7], v[100:103], v[116:119], v[4:7]
	s_setprio 0
	s_add_u32 s10, s10, 64
	s_addc_u32 s11, s11, 0
	s_add_u32 s12, s12, 0x1000
	v_subrev_u32_e32 v159, 32, v159
	s_addc_u32 s13, s13, 0
	s_and_b64 vcc, exec, s[8:9]
	s_cbranch_vccnz .LBB0_1890
	v_mov_b64_e32 v[130:131], v[70:71]
	v_mov_b64_e32 v[126:127], v[74:75]
	v_mov_b64_e32 v[122:123], v[78:79]
	v_mov_b64_e32 v[118:119], v[82:83]
	v_mov_b64_e32 v[114:115], v[86:87]
	v_mov_b64_e32 v[110:111], v[90:91]
	v_mov_b64_e32 v[106:107], v[94:95]
	v_mov_b64_e32 v[102:103], v[98:99]
	v_mov_b64_e32 v[128:129], v[68:69]
	v_mov_b64_e32 v[124:125], v[72:73]
	v_mov_b64_e32 v[120:121], v[76:77]
	v_mov_b64_e32 v[116:117], v[80:81]
	v_mov_b64_e32 v[112:113], v[84:85]
	v_mov_b64_e32 v[108:109], v[88:89]
	v_mov_b64_e32 v[104:105], v[92:93]
	v_mov_b64_e32 v[100:101], v[96:97]
	s_branch .LBB0_1885

.LBB0_2295:
	s_add_i32 s37, s37, 32
	v_or_b32_e32 v19, s37, v105
	v_lshlrev_b32_e32 v19, 8, v19
	v_add3_u32 v19, v103, v19, v107
	ds_write_b128 v19, v[14:17] offset:22848
	ds_write_b128 v19, v[10:13] offset:22912
	ds_write_b128 v19, v[6:9] offset:22976
	ds_write_b128 v19, v[2:5] offset:23040
	v_mov_b32_e32 v2, v18
	s_nop 1
	v_permlane16_swap_b32 v18, v2
	s_nop 0
	v_add_f32_e32 v2, v18, v2
	v_mov_b32_e32 v3, v2
	s_nop 1
	v_permlane32_swap_b32 v2, v3
	s_and_saveexec_b64 s[0:1], s[6:7]
	v_add_f32_e32 v2, v2, v3
	v_lshlrev_b32_e32 v3, 2, v104
	v_add3_u32 v3, v103, s3, v3
	ds_write_b32 v3, v2 offset:22336
	s_or_b64 exec, exec, s[0:1]
	v_lshlrev_b32_e32 v2, 1, v0
	v_readlane_b32 s6, v254, 14
	v_and_b32_e32 v8, 62, v2
	v_lshrrev_b32_e32 v2, 7, v0
	v_readlane_b32 s7, v254, 15
	v_add_u32_e32 v2, s24, v2
	s_movk_i32 s0, 0xc0
	v_mov_b64_e32 v[4:5], s[6:7]
	v_mad_i64_i32 v[4:5], s[0:1], v2, s0, v[4:5]
	v_and_or_b32 v9, v1, 3, s25
	v_ashrrev_i32_e32 v3, 31, v2
	v_readlane_b32 s0, v254, 12
	v_lshlrev_b32_e32 v6, 2, v9
	v_mov_b32_e32 v7, 0
	v_lshlrev_b64 v[2:3], 11, v[2:3]
	v_readlane_b32 s1, v254, 13
	v_lshl_add_u64 v[22:23], v[4:5], 0, v[6:7]
	v_lshlrev_b32_e32 v6, 7, v9
	v_lshl_add_u64 v[2:3], s[0:1], 0, v[2:3]
	v_lshl_add_u64 v[2:3], v[2:3], 0, v[6:7]
	v_lshlrev_b32_e32 v6, 1, v8
	v_lshl_add_u64 v[30:31], v[2:3], 0, v[6:7]
	v_lshl_add_u32 v2, v1, 8, v103
	v_lshl_add_u32 v33, v8, 2, v2
	s_movk_i32 s0, 0xff04
	v_add_u32_e32 v24, 0x140, v33
	s_waitcnt lgkmcnt(0)
	s_barrier
	v_add_u32_e32 v26, 0x5940, v33
	v_mad_i32_i24 v54, v1, s0, v2
	ds_read2st64_b64 v[2:5], v24 offset0:44 offset1:52
	ds_read2st64_b64 v[6:9], v24 offset0:60 offset1:68
	ds_read2st64_b64 v[10:13], v24 offset0:92 offset1:100
	ds_read2st64_b64 v[14:17], v24 offset0:108 offset1:116
	ds_read2st64_b64 v[18:21], v26 offset0:88 offset1:96
	global_load_dword v66, v[22:23], off offset:64
	global_load_dword v32, v[22:23], off
	global_load_dword v67, v[22:23], off offset:128
	v_add_u32_e32 v27, 0x17940, v33
	v_add_u32_e32 v28, 0x1a940, v33
	v_add_u32_e32 v50, 0x5400, v54
	ds_read2_b32 v[34:35], v50 offset0:80 offset1:96
	ds_read2st64_b64 v[22:25], v24 offset0:76 offset1:84
	ds_read2_b32 v[36:37], v50 offset0:112 offset1:128
	ds_read_b64 v[38:39], v26 offset:61440
	ds_read_b64 v[40:41], v27
	ds_read_b64 v[42:43], v28
	ds_read_b64 v[44:45], v33 offset:63808
	ds_read2st64_b64 v[26:29], v26 offset0:104 offset1:112
	ds_read2_b32 v[46:47], v50 offset0:144 offset1:160
	ds_read2_b32 v[48:49], v50 offset0:176 offset1:192
	ds_read2_b32 v[50:51], v50 offset0:208 offset1:224
	v_add_u32_e32 v52, 0x5600, v54
	ds_read2_b32 v[52:53], v52 offset0:112 offset1:128
	v_add_u32_e32 v64, 0x5800, v54
	ds_read2_b32 v[54:55], v64 offset0:16 offset1:32
	v_add_u32_e32 v56, 0x15940, v33
	v_add_u32_e32 v58, 0x18940, v33
	v_add_u32_e32 v60, 0x1b940, v33
	v_add_u32_e32 v62, 0x16940, v33
	s_waitcnt lgkmcnt(2)
	v_add_f32_e32 v50, 0, v50
	ds_read_b64 v[56:57], v56
	ds_read_b64 v[58:59], v58
	ds_read_b64 v[60:61], v60
	ds_read_b64 v[62:63], v62
	ds_read2_b32 v[64:65], v64 offset0:48 offset1:64
	v_add_f32_e32 v50, v50, v51
	s_waitcnt lgkmcnt(6)
	v_add_f32_e32 v50, v50, v52
	v_add_f32_e32 v50, v50, v53
	s_waitcnt lgkmcnt(5)
	v_add_f32_e32 v50, v50, v54
	v_add_f32_e32 v50, v50, v55
	v_add_f32_e32 v34, 0, v34
	s_waitcnt lgkmcnt(0)
	v_add_f32_e32 v50, v50, v64
	v_add_f32_e32 v34, v34, v35
	v_add_f32_e32 v50, v50, v65
	v_add_f32_e32 v34, v34, v36
	v_max_f32_e32 v54, 0xda24260, v50
	v_add_f32_e32 v34, v34, v37
	v_div_scale_f32 v55, s[0:1], v54, v54, 1.0
	v_add_f32_e32 v34, v34, v46
	v_rcp_f32_e32 v64, v55
	v_add_f32_e32 v34, v34, v47
	v_add_f32_e32 v34, v34, v48
	v_add_f32_e32 v34, v34, v49
	v_add_u32_e32 v68, 0x19940, v33
	v_add_u32_e32 v33, 0x1c940, v33
	v_max_f32_e32 v34, 0xda24260, v34
	ds_read_b64 v[50:51], v68
	ds_read_b64 v[52:53], v33
	v_fma_f32 v33, -v55, v64, 1.0
	v_div_scale_f32 v35, s[0:1], v34, v34, 1.0
	v_fmac_f32_e32 v64, v33, v64
	v_div_scale_f32 v33, vcc, 1.0, v54, 1.0
	v_rcp_f32_e32 v36, v35
	v_mul_f32_e32 v65, v33, v64
	v_fma_f32 v68, -v55, v65, v33
	v_fmac_f32_e32 v65, v68, v64
	v_fma_f32 v33, -v55, v65, v33
	v_fma_f32 v37, -v35, v36, 1.0
	v_add_f32_e32 v2, 0, v2
	v_add_f32_e32 v3, 0, v3
	v_div_fmas_f32 v33, v33, v64, v65
	v_fmac_f32_e32 v36, v37, v36
	v_div_scale_f32 v37, vcc, 1.0, v34, 1.0
	v_add_f32_e32 v2, v2, v8
	v_add_f32_e32 v3, v3, v9
	v_add_f32_e32 v4, 0, v4
	v_add_f32_e32 v5, 0, v5
	v_mul_f32_e32 v46, v37, v36
	v_add_f32_e32 v6, 0, v6
	v_add_f32_e32 v7, 0, v7
	v_add_f32_e32 v2, v2, v10
	v_add_f32_e32 v3, v3, v11
	v_add_f32_e32 v4, v4, v22
	v_add_f32_e32 v5, v5, v23
	v_fma_f32 v47, -v35, v46, v37
	v_add_f32_e32 v6, v6, v24
	v_add_f32_e32 v7, v7, v25
	v_add_f32_e32 v2, v2, v16
	v_add_f32_e32 v3, v3, v17
	v_add_f32_e32 v4, v4, v12
	v_add_f32_e32 v5, v5, v13
	v_fmac_f32_e32 v46, v47, v36
	v_add_f32_e32 v6, v6, v14
	v_add_f32_e32 v7, v7, v15
	v_add_f32_e32 v2, v2, v20
	v_add_f32_e32 v3, v3, v21
	v_add_f32_e32 v4, v4, v44
	v_add_f32_e32 v5, v5, v45
	v_fma_f32 v35, -v35, v46, v37
	v_add_f32_e32 v6, v6, v18
	v_add_f32_e32 v7, v7, v19
	v_add_f32_e32 v2, v2, v38
	v_add_f32_e32 v3, v3, v39
	v_add_f32_e32 v4, v4, v26
	v_add_f32_e32 v5, v5, v27
	v_div_fmas_f32 v35, v35, v36, v46
	v_add_f32_e32 v6, v6, v28
	v_add_f32_e32 v7, v7, v29
	v_add_f32_e32 v2, v2, v40
	v_add_f32_e32 v3, v3, v41
	v_add_f32_e32 v4, v4, v56
	v_add_f32_e32 v5, v5, v57
	v_div_fixup_f32 v33, v33, v54, 1.0
	v_div_fixup_f32 v34, v35, v34, 1.0
	v_add_f32_e32 v6, v6, v62
	v_add_f32_e32 v7, v7, v63
	v_add_f32_e32 v2, v2, v42
	v_add_f32_e32 v3, v3, v43
	v_add_f32_e32 v4, v4, v58
	v_add_f32_e32 v5, v5, v59
	s_waitcnt vmcnt(2)
	v_mul_f32_e32 v34, v66, v34
	s_waitcnt lgkmcnt(1)
	v_add_f32_e32 v6, v6, v50
	v_add_f32_e32 v7, v7, v51
	s_waitcnt vmcnt(1)
	v_pk_fma_f32 v[2:3], v[32:33], v[2:3], 0 op_sel_hi:[0,1,0]
	v_add_f32_e32 v4, v4, v60
	v_add_f32_e32 v5, v5, v61
	s_waitcnt vmcnt(0)
	v_mul_f32_e32 v36, v67, v33
	s_waitcnt lgkmcnt(0)
	v_add_f32_e32 v6, v6, v52
	v_add_f32_e32 v7, v7, v53
	v_pk_fma_f32 v[2:3], v[4:5], v[34:35], v[2:3] op_sel_hi:[1,0,1]
	s_nop 0
	v_pk_fma_f32 v[2:3], v[6:7], v[36:37], v[2:3] op_sel_hi:[1,0,1]
	s_nop 0
	v_cvt_pk_bf16_f32 v2, v2, v3
	global_store_dword v[30:31], v2, off
	s_barrier

.LBB0_2309:
	s_or_b32 s51, s52, s16
	s_lshl_b32 s53, s51, 4
	s_cmp_ge_i32 s53, s24
	s_cbranch_scc1 .LBB0_2308
	v_or_b32_e32 v49, s52, v226
	v_mad_u32_u24 v49, v49, s48, v44
	ds_read_b128 v[50:53], v49
	ds_read_b128 v[54:57], v49 offset:64
	ds_read_b128 v[58:61], v49 offset:2304
	ds_read_b128 v[62:65], v49 offset:2368
	v_subrev_u32_e32 v49, s51, v1
	v_lshl_add_u32 v49, v49, 4, v161
	v_cvt_f32_u32_e32 v66, v49
	v_xad_u32 v67, s51, -1, v1
	v_lshl_add_u32 v67, v67, 4, v161
	v_cvt_f32_u32_e32 v68, v67
	v_cmp_gt_u32_e32 vcc, 2.0, v49
	s_nop 1
	v_cndmask_b32_e32 v49, v48, v66, vcc
	v_subrev_u32_e32 v66, s51, v162
	v_cmp_gt_u32_e32 vcc, 2.0, v67
	v_lshl_add_u32 v66, v66, 4, v161
	v_cvt_f32_u32_e32 v67, v66
	v_cndmask_b32_e32 v90, v48, v68, vcc
	v_subrev_u32_e32 v68, s51, v163
	v_lshl_add_u32 v68, v68, 4, v161
	v_cvt_f32_u32_e32 v69, v68
	v_cmp_gt_u32_e32 vcc, 2.0, v66
	v_subrev_u32_e32 v66, s51, v164
	v_lshl_add_u32 v66, v66, 4, v161
	v_cndmask_b32_e32 v91, v48, v67, vcc
	v_cmp_gt_u32_e32 vcc, 2.0, v68
	v_cvt_f32_u32_e32 v67, v66
	v_subrev_u32_e32 v68, s51, v165
	v_lshl_add_u32 v68, v68, 4, v161
	v_cndmask_b32_e32 v92, v48, v69, vcc
	v_cvt_f32_u32_e32 v69, v68
	v_cmp_gt_u32_e32 vcc, 2.0, v66
	v_subrev_u32_e32 v66, s51, v166
	v_lshl_add_u32 v66, v66, 4, v161
	v_cndmask_b32_e32 v93, v48, v67, vcc
	v_cmp_gt_u32_e32 vcc, 2.0, v68
	v_subrev_u32_e32 v68, s51, v167
	v_cvt_f32_u32_e32 v67, v66
	v_lshl_add_u32 v68, v68, 4, v161
	v_cndmask_b32_e32 v94, v48, v69, vcc
	v_cvt_f32_u32_e32 v69, v68
	v_cmp_gt_u32_e32 vcc, 2.0, v66
	s_nop 1
	v_cndmask_b32_e32 v95, v48, v67, vcc
	v_cmp_gt_u32_e32 vcc, 2.0, v68
	s_nop 1
	v_cndmask_b32_e32 v96, v48, v69, vcc
	s_setprio 1
	s_waitcnt lgkmcnt(3)
	v_mfma_f32_16x16x32_bf16 v[66:69], v[50:53], v[2:5], 0
	v_mfma_f32_16x16x32_bf16 v[74:77], v[50:53], v[10:13], 0
	v_mfma_f32_16x16x32_bf16 v[82:85], v[50:53], v[18:21], 0
	v_mfma_f32_16x16x32_bf16 v[50:53], v[50:53], v[26:29], 0
	s_waitcnt lgkmcnt(2)
	v_mfma_f32_16x16x32_bf16 v[66:69], v[54:57], v[6:9], v[66:69]
	s_waitcnt lgkmcnt(1)
	v_mfma_f32_16x16x32_bf16 v[70:73], v[58:61], v[2:5], 0
	v_mfma_f32_16x16x32_bf16 v[74:77], v[54:57], v[14:17], v[74:77]
	v_mfma_f32_16x16x32_bf16 v[78:81], v[58:61], v[10:13], 0
	v_mfma_f32_16x16x32_bf16 v[82:85], v[54:57], v[22:25], v[82:85]
	v_mfma_f32_16x16x32_bf16 v[86:89], v[58:61], v[18:21], 0
	v_mfma_f32_16x16x32_bf16 v[50:53], v[54:57], v[30:33], v[50:53]
	v_mfma_f32_16x16x32_bf16 v[54:57], v[58:61], v[26:29], 0
	s_waitcnt lgkmcnt(0)
	v_mfma_f32_16x16x32_bf16 v[70:73], v[62:65], v[6:9], v[70:73]
	v_mfma_f32_16x16x32_bf16 v[78:81], v[62:65], v[14:17], v[78:81]
	v_mfma_f32_16x16x32_bf16 v[86:89], v[62:65], v[22:25], v[86:89]
	v_mfma_f32_16x16x32_bf16 v[54:57], v[62:65], v[30:33], v[54:57]
	s_setprio 0
	v_fma_f32 v58, -v215, v49, v66
	v_exp_f32_e32 v59, v58
	v_fma_f32 v58, -v215, v90, v67
	v_exp_f32_e32 v61, v58
	v_fma_f32 v58, -v215, v91, v68
	v_exp_f32_e32 v63, v58
	v_fma_f32 v58, -v215, v92, v69
	v_exp_f32_e32 v65, v58
	v_fma_f32 v58, -v215, v93, v70
	v_exp_f32_e32 v67, v58
	v_fma_f32 v58, -v215, v94, v71
	v_exp_f32_e32 v69, v58
	v_fma_f32 v58, -v215, v95, v72
	v_exp_f32_e32 v71, v58
	v_fma_f32 v58, -v215, v96, v73
	v_exp_f32_e32 v73, v58
	v_fma_f32 v58, -v216, v49, v74
	v_exp_f32_e32 v58, v58
	v_fma_f32 v60, -v216, v90, v75
	v_exp_f32_e32 v60, v60
	v_fma_f32 v62, -v216, v91, v76
	v_exp_f32_e32 v62, v62
	v_fma_f32 v64, -v216, v92, v77
	v_exp_f32_e32 v64, v64
	v_fma_f32 v66, -v216, v93, v78
	v_exp_f32_e32 v66, v66
	v_fma_f32 v68, -v216, v94, v79
	v_add_f32_e32 v58, 0, v58
	v_add_f32_e32 v59, 0, v59
	v_exp_f32_e32 v68, v68
	v_fma_f32 v70, -v216, v95, v80
	v_add_f32_e32 v58, v60, v58
	v_add_f32_e32 v59, v61, v59
	v_exp_f32_e32 v70, v70
	v_fma_f32 v72, -v216, v96, v81
	v_add_f32_e32 v58, v62, v58
	v_add_f32_e32 v59, v63, v59
	v_exp_f32_e32 v72, v72
	v_add_f32_e32 v58, v64, v58
	v_add_f32_e32 v59, v65, v59
	s_nop 0
	v_add_f32_e32 v58, v66, v58
	v_add_f32_e32 v59, v67, v59
	s_nop 0
	v_add_f32_e32 v58, v68, v58
	v_add_f32_e32 v59, v69, v59
	s_nop 0
	v_add_f32_e32 v58, v70, v58
	v_add_f32_e32 v59, v71, v59
	s_nop 0
	v_add_f32_e32 v58, v72, v58
	v_add_f32_e32 v59, v73, v59
	s_nop 0
	v_add_f32_e32 v46, v46, v58
	v_add_f32_e32 v47, v47, v59
	v_fma_f32 v58, -v217, v49, v82
	v_exp_f32_e32 v59, v58
	v_fma_f32 v58, -v217, v90, v83
	v_exp_f32_e32 v61, v58
	v_fma_f32 v58, -v217, v91, v84
	v_exp_f32_e32 v63, v58
	v_fma_f32 v58, -v217, v92, v85
	v_exp_f32_e32 v65, v58
	v_fma_f32 v58, -v217, v93, v86
	v_exp_f32_e32 v67, v58
	v_fma_f32 v58, -v217, v94, v87
	v_exp_f32_e32 v69, v58
	v_fma_f32 v58, -v217, v95, v88
	v_exp_f32_e32 v71, v58
	v_fma_f32 v58, -v217, v96, v89
	v_fma_f32 v49, -v218, v49, v50
	v_exp_f32_e32 v73, v58
	v_exp_f32_e32 v58, v49
	v_fma_f32 v49, -v218, v90, v51
	v_exp_f32_e32 v60, v49
	v_fma_f32 v49, -v218, v91, v52
	v_exp_f32_e32 v62, v49
	v_fma_f32 v49, -v218, v92, v53
	v_exp_f32_e32 v64, v49
	v_fma_f32 v49, -v218, v93, v54
	v_exp_f32_e32 v66, v49
	v_fma_f32 v49, -v218, v94, v55
	v_add_f32_e32 v50, 0, v58
	v_add_f32_e32 v51, 0, v59
	v_exp_f32_e32 v68, v49
	v_fma_f32 v49, -v218, v95, v56
	v_add_f32_e32 v50, v60, v50
	v_add_f32_e32 v51, v61, v51
	v_exp_f32_e32 v70, v49
	v_fma_f32 v49, -v218, v96, v57
	v_add_f32_e32 v50, v62, v50
	v_add_f32_e32 v51, v63, v51
	v_exp_f32_e32 v72, v49
	v_add_f32_e32 v50, v64, v50
	v_add_f32_e32 v51, v65, v51
	s_nop 0
	v_add_f32_e32 v50, v66, v50
	v_add_f32_e32 v51, v67, v51
	s_nop 0
	v_add_f32_e32 v50, v68, v50
	v_add_f32_e32 v51, v69, v51
	s_nop 0
	v_add_f32_e32 v50, v70, v50
	v_add_f32_e32 v51, v71, v51
	s_nop 0
	v_add_f32_e32 v50, v72, v50
	v_add_f32_e32 v51, v73, v51
	s_nop 0
	v_add_f32_e32 v42, v42, v50
	v_add_f32_e32 v43, v43, v51
	s_branch .LBB0_2308

.LBB0_2315:
	s_waitcnt vmcnt(0)
	v_mov_b32_e32 v34, v47
	s_nop 1
	v_permlane16_swap_b32 v34, v47
	v_mov_b32_e32 v99, 0
	v_add_f32_e32 v45, v34, v47
	v_mov_b32_e32 v47, v45
	v_mov_b32_e32 v34, v46
	s_nop 1
	v_permlane32_swap_b32 v45, v47
	s_nop 1
	v_permlane16_swap_b32 v46, v34
	v_mov_b32_e32 v98, v99
	v_add_f32_e32 v46, v46, v34
	v_mov_b32_e32 v44, v46
	v_mov_b32_e32 v34, v43
	s_nop 1
	v_permlane32_swap_b32 v44, v46
	s_nop 1
	v_permlane16_swap_b32 v34, v43
	v_mov_b32_e32 v100, v99
	v_add_f32_e32 v43, v34, v43
	v_mov_b32_e32 v49, v43
	v_mov_b32_e32 v34, v42
	s_nop 1
	v_permlane32_swap_b32 v43, v49
	s_nop 1
	v_permlane16_swap_b32 v34, v42
	v_add_f32_e32 v44, v44, v46
	v_add_f32_e32 v45, v45, v47
	v_add_f32_e32 v48, v34, v42
	v_mov_b32_e32 v42, v48
	s_nop 1
	v_permlane32_swap_b32 v42, v48
	global_load_dwordx4 v[34:37], v[142:143], off
	global_load_dwordx4 v[38:41], v[138:139], off
	v_div_scale_f32 v46, s[16:17], v45, v45, 1.0
	v_div_scale_f32 v50, s[16:17], v44, v44, 1.0
	v_rcp_f32_e32 v51, v46
	v_rcp_f32_e32 v52, v50
	v_add_f32_e32 v42, v42, v48
	v_add_f32_e32 v43, v43, v49
	v_div_scale_f32 v47, vcc, 1.0, v45, 1.0
	v_fma_f32 v54, -v46, v51, 1.0
	v_fma_f32 v55, -v50, v52, 1.0
	v_fmac_f32_e32 v51, v54, v51
	v_div_scale_f32 v48, s[18:19], v43, v43, 1.0
	v_div_scale_f32 v53, s[16:17], 1.0, v44, 1.0
	v_fmac_f32_e32 v52, v55, v52
	v_div_scale_f32 v54, s[20:21], v42, v42, 1.0
	v_mul_f32_e32 v56, v47, v51
	v_rcp_f32_e32 v58, v48
	v_mul_f32_e32 v57, v53, v52
	v_rcp_f32_e32 v59, v54
	v_fma_f32 v60, -v46, v56, v47
	v_fma_f32 v61, -v50, v57, v53
	v_fmac_f32_e32 v56, v60, v51
	v_fmac_f32_e32 v57, v61, v52
	v_fma_f32 v46, -v46, v56, v47
	v_fma_f32 v47, -v50, v57, v53
	v_div_fmas_f32 v46, v46, v51, v56
	v_fma_f32 v50, -v48, v58, 1.0
	s_mov_b64 vcc, s[16:17]
	v_div_scale_f32 v49, s[18:19], 1.0, v43, 1.0
	v_fma_f32 v51, -v54, v59, 1.0
	v_div_fixup_f32 v46, v46, v45, 1.0
	v_div_fmas_f32 v47, v47, v52, v57
	v_fmac_f32_e32 v58, v50, v58
	v_cmp_lt_f32_e32 vcc, 0, v45
	v_div_scale_f32 v55, s[20:21], 1.0, v42, 1.0
	v_fmac_f32_e32 v59, v51, v59
	v_cndmask_b32_e32 v150, 0, v46, vcc
	v_mul_f32_e32 v46, v49, v58
	v_div_fixup_f32 v45, v47, v44, 1.0
	v_mul_f32_e32 v47, v55, v59
	v_cmp_lt_f32_e32 vcc, 0, v44
	v_fma_f32 v44, -v48, v46, v49
	v_fmac_f32_e32 v46, v44, v58
	v_cndmask_b32_e32 v152, 0, v45, vcc
	v_fma_f32 v45, -v54, v47, v55
	v_fmac_f32_e32 v47, v45, v59
	v_fma_f32 v44, -v48, v46, v49
	s_mov_b64 vcc, s[18:19]
	v_fma_f32 v45, -v54, v47, v55
	v_div_fmas_f32 v44, v44, v58, v46
	s_mov_b64 vcc, s[20:21]
	v_div_fixup_f32 v44, v44, v43, 1.0
	v_div_fmas_f32 v45, v45, v59, v47
	v_cmp_lt_f32_e32 vcc, 0, v43
	v_div_fixup_f32 v43, v45, v42, 1.0
	v_readlane_b32 s16, v254, 60
	v_cndmask_b32_e32 v154, 0, v44, vcc
	v_cmp_lt_f32_e32 vcc, 0, v42
	v_mov_b32_e32 v101, v99
	v_mov_b64_e32 v[66:67], v[98:99]
	s_waitcnt vmcnt(1)
	ds_write_b128 v230, v[34:37]
	s_waitcnt vmcnt(0)
	ds_write_b128 v231, v[38:41]
	v_mul_u32_u24_e32 v34, 0x210, v226
	v_cndmask_b32_e32 v156, 0, v43, vcc
	v_add3_u32 v125, v131, s16, v34
	v_mov_b64_e32 v[70:71], v[98:99]
	v_mov_b64_e32 v[74:75], v[98:99]
	v_mov_b64_e32 v[78:79], v[98:99]
	v_mov_b64_e32 v[82:83], v[98:99]
	v_mov_b64_e32 v[86:87], v[98:99]
	v_mov_b64_e32 v[90:91], v[98:99]
	v_mov_b64_e32 v[94:95], v[98:99]
	v_mov_b64_e32 v[62:63], v[98:99]
	v_mov_b64_e32 v[58:59], v[98:99]
	v_mov_b64_e32 v[54:55], v[98:99]
	v_mov_b64_e32 v[50:51], v[98:99]
	v_mov_b64_e32 v[46:47], v[98:99]
	v_mov_b64_e32 v[42:43], v[98:99]
	v_mov_b64_e32 v[38:39], v[98:99]
	v_mov_b64_e32 v[34:35], v[98:99]
	s_mov_b32 s65, 0
	s_movk_i32 s20, 0x90
	v_mul_u32_u24_e32 v229, 0x90, v226
	v_add_u32_e32 v168, v125, v144
	v_mov_b32_e32 v157, v156
	v_mov_b32_e32 v155, v154
	v_mov_b32_e32 v153, v152
	v_mov_b32_e32 v151, v150
	v_mov_b32_e32 v169, 0x49742400
	v_mov_b64_e32 v[68:69], v[100:101]
	v_mov_b64_e32 v[72:73], v[100:101]
	v_mov_b64_e32 v[76:77], v[100:101]
	v_mov_b64_e32 v[80:81], v[100:101]
	v_mov_b64_e32 v[84:85], v[100:101]
	v_mov_b64_e32 v[88:89], v[100:101]
	v_mov_b64_e32 v[92:93], v[100:101]
	v_mov_b64_e32 v[96:97], v[100:101]
	v_mov_b64_e32 v[64:65], v[100:101]
	v_mov_b64_e32 v[60:61], v[100:101]
	v_mov_b64_e32 v[56:57], v[100:101]
	v_mov_b64_e32 v[52:53], v[100:101]
	v_mov_b64_e32 v[48:49], v[100:101]
	v_mov_b64_e32 v[44:45], v[100:101]
	v_mov_b64_e32 v[40:41], v[100:101]
	v_mov_b64_e32 v[36:37], v[100:101]
	s_mov_b32 s21, 0
	s_waitcnt lgkmcnt(0)
	s_barrier

.LBB0_2477:
	s_lshl_b32 s21, s20, 5
	v_or_b32_e32 v151, s21, v226
	v_mad_u32_u24 v151, v151, s52, v148
	ds_read_b128 v[152:155], v151
	ds_read_b128 v[156:159], v151 offset:64
	ds_read_b128 v[160:163], v151 offset:2304
	ds_read_b128 v[164:167], v151 offset:2368
	v_lshl_add_u32 v151, s20, 6, v149
	ds_read_b128 v[168:171], v151 offset:9216
	ds_read_b128 v[172:175], v151 offset:11520
	ds_read_b128 v[176:179], v151 offset:13824
	ds_read_b128 v[182:185], v151 offset:16128
	v_add_u32_e32 v151, s21, v150
	v_sub_u32_e32 v180, v227, v151
	v_cmp_gt_u32_e32 vcc, 2.0, v180
	v_cvt_f32_i32_e32 v180, v180
	v_xad_u32 v186, v151, -1, v227
	v_cvt_f32_i32_e32 v187, v186
	s_and_b64 vcc, s[16:17], vcc
	v_cndmask_b32_e32 v180, v235, v180, vcc
	v_cmp_gt_u32_e32 vcc, 2.0, v186
	v_or_b32_e32 v186, 2, v151
	s_and_b64 vcc, s[16:17], vcc
	v_sub_u32_e32 v186, v227, v186
	v_cndmask_b32_e32 v236, v235, v187, vcc
	v_cmp_gt_u32_e32 vcc, 2.0, v186
	v_cvt_f32_i32_e32 v186, v186
	v_or_b32_e32 v187, 3, v151
	v_sub_u32_e32 v187, v227, v187
	v_cvt_f32_i32_e32 v188, v187
	s_and_b64 vcc, s[16:17], vcc
	v_cndmask_b32_e32 v237, v235, v186, vcc
	v_cmp_gt_u32_e32 vcc, 2.0, v187
	v_or_b32_e32 v186, 4, v151
	s_and_b64 vcc, s[16:17], vcc
	v_sub_u32_e32 v186, v227, v186
	v_cndmask_b32_e32 v238, v235, v188, vcc
	v_cmp_gt_u32_e32 vcc, 2.0, v186
	v_cvt_f32_i32_e32 v186, v186
	v_or_b32_e32 v187, 5, v151
	v_sub_u32_e32 v187, v227, v187
	v_cvt_f32_i32_e32 v188, v187
	s_and_b64 vcc, s[16:17], vcc
	v_cndmask_b32_e32 v239, v235, v186, vcc
	v_cmp_gt_u32_e32 vcc, 2.0, v187
	v_or_b32_e32 v186, 6, v151
	s_and_b64 vcc, s[16:17], vcc
	v_sub_u32_e32 v186, v227, v186
	v_cndmask_b32_e32 v240, v235, v188, vcc
	v_cmp_gt_u32_e32 vcc, 2.0, v186
	v_cvt_f32_i32_e32 v186, v186
	v_or_b32_e32 v151, 7, v151
	v_sub_u32_e32 v151, v227, v151
	v_cvt_f32_i32_e32 v187, v151
	s_and_b64 vcc, s[16:17], vcc
	v_cndmask_b32_e32 v241, v235, v186, vcc
	v_cmp_gt_u32_e32 vcc, 2.0, v151
	s_and_b64 vcc, s[16:17], vcc
	s_nop 0
	v_cndmask_b32_e32 v151, v235, v187, vcc
	s_setprio 1
	s_waitcnt lgkmcnt(7)
	v_mfma_f32_16x16x32_bf16 v[186:189], v[152:155], v[2:5], 0
	v_mfma_f32_16x16x32_bf16 v[194:197], v[152:155], v[10:13], 0
	v_mfma_f32_16x16x32_bf16 v[202:205], v[152:155], v[18:21], 0
	v_mfma_f32_16x16x32_bf16 v[152:155], v[152:155], v[26:29], 0
	s_waitcnt lgkmcnt(6)
	v_mfma_f32_16x16x32_bf16 v[186:189], v[156:159], v[6:9], v[186:189]
	s_waitcnt lgkmcnt(5)
	v_mfma_f32_16x16x32_bf16 v[190:193], v[160:163], v[2:5], 0
	v_mfma_f32_16x16x32_bf16 v[194:197], v[156:159], v[14:17], v[194:197]
	v_mfma_f32_16x16x32_bf16 v[198:201], v[160:163], v[10:13], 0
	v_mfma_f32_16x16x32_bf16 v[202:205], v[156:159], v[22:25], v[202:205]
	v_mfma_f32_16x16x32_bf16 v[206:209], v[160:163], v[18:21], 0
	v_mfma_f32_16x16x32_bf16 v[152:155], v[156:159], v[30:33], v[152:155]
	v_mfma_f32_16x16x32_bf16 v[156:159], v[160:163], v[26:29], 0
	s_waitcnt lgkmcnt(4)
	v_mfma_f32_16x16x32_bf16 v[190:193], v[164:167], v[6:9], v[190:193]
	v_mfma_f32_16x16x32_bf16 v[198:201], v[164:167], v[14:17], v[198:201]
	v_mfma_f32_16x16x32_bf16 v[206:209], v[164:167], v[22:25], v[206:209]
	v_mfma_f32_16x16x32_bf16 v[156:159], v[164:167], v[30:33], v[156:159]
	s_setprio 0
	v_fma_f32 v160, -v215, v180, v186
	v_fma_f32 v164, -v216, v180, v194
	v_exp_f32_e32 v165, v160
	v_fma_f32 v160, -v215, v236, v187
	v_exp_f32_e32 v164, v164
	v_fma_f32 v166, -v216, v236, v195
	v_exp_f32_e32 v167, v160
	v_fma_f32 v160, -v215, v237, v188
	v_exp_f32_e32 v166, v166
	v_fma_f32 v186, -v216, v237, v196
	v_exp_f32_e32 v187, v160
	v_fma_f32 v160, -v215, v238, v189
	v_exp_f32_e32 v186, v186
	v_fma_f32 v188, -v216, v238, v197
	v_exp_f32_e32 v189, v160
	v_fma_f32 v160, -v215, v239, v190
	v_exp_f32_e32 v188, v188
	v_fma_f32 v190, -v216, v239, v198
	v_exp_f32_e32 v211, v160
	v_fma_f32 v160, -v215, v240, v191
	v_exp_f32_e32 v210, v190
	v_fma_f32 v190, -v216, v240, v199
	v_add_f32_e32 v194, 0, v164
	v_add_f32_e32 v195, 0, v165
	v_exp_f32_e32 v191, v160
	v_fma_f32 v160, -v215, v241, v192
	v_exp_f32_e32 v190, v190
	v_fma_f32 v192, -v216, v241, v200
	v_add_f32_e32 v194, v166, v194
	v_add_f32_e32 v195, v167, v195
	v_exp_f32_e32 v213, v160
	v_fma_f32 v160, -v215, v151, v193
	v_exp_f32_e32 v212, v192
	v_fma_f32 v192, -v216, v151, v201
	v_add_f32_e32 v194, v186, v194
	v_add_f32_e32 v195, v187, v195
	v_exp_f32_e32 v193, v160
	v_exp_f32_e32 v192, v192
	v_add_f32_e32 v194, v188, v194
	v_add_f32_e32 v195, v189, v195
	v_fma_f32 v152, -v218, v180, v152
	v_add_f32_e32 v194, v210, v194
	v_add_f32_e32 v195, v211, v195
	v_cvt_pk_bf16_f32 v164, v164, v166
	v_add_f32_e32 v194, v190, v194
	v_add_f32_e32 v195, v191, v195
	v_cvt_pk_bf16_f32 v166, v210, v190
	v_add_f32_e32 v194, v212, v194
	v_add_f32_e32 v195, v213, v195
	v_exp_f32_e32 v190, v152
	v_fma_f32 v152, -v218, v236, v153
	v_cvt_pk_bf16_f32 v160, v165, v167
	v_add_f32_e32 v194, v192, v194
	v_add_f32_e32 v195, v193, v195
	v_cvt_pk_bf16_f32 v165, v186, v188
	v_cvt_pk_bf16_f32 v167, v212, v192
	v_fma_f32 v186, -v217, v180, v202
	v_exp_f32_e32 v192, v152
	v_fma_f32 v152, -v218, v237, v154
	v_cvt_pk_bf16_f32 v162, v211, v191
	v_add_f32_e32 v122, v122, v194
	v_add_f32_e32 v123, v123, v195
	v_exp_f32_e32 v191, v186
	v_fma_f32 v186, -v217, v236, v203
	v_exp_f32_e32 v194, v152
	v_fma_f32 v152, -v218, v238, v155
	v_cvt_pk_bf16_f32 v163, v213, v193
	v_exp_f32_e32 v193, v186
	v_fma_f32 v186, -v217, v237, v204
	v_exp_f32_e32 v196, v152
	v_fma_f32 v152, -v218, v239, v156
	v_exp_f32_e32 v195, v186
	v_fma_f32 v186, -v217, v238, v205
	v_exp_f32_e32 v198, v152
	v_fma_f32 v152, -v218, v240, v157
	v_exp_f32_e32 v197, v186
	v_fma_f32 v186, -v217, v239, v206
	v_exp_f32_e32 v200, v152
	v_fma_f32 v152, -v218, v241, v158
	v_exp_f32_e32 v199, v186
	v_fma_f32 v186, -v217, v240, v207
	v_exp_f32_e32 v202, v152
	v_add_f32_e32 v152, 0, v190
	v_add_f32_e32 v153, 0, v191
	v_exp_f32_e32 v201, v186
	v_fma_f32 v186, -v217, v241, v208
	v_add_f32_e32 v152, v192, v152
	v_add_f32_e32 v153, v193, v153
	v_exp_f32_e32 v203, v186
	v_fma_f32 v186, -v217, v151, v209
	v_fma_f32 v151, -v218, v151, v159
	v_add_f32_e32 v152, v194, v152
	v_add_f32_e32 v153, v195, v153
	v_exp_f32_e32 v205, v186
	v_exp_f32_e32 v204, v151
	v_add_f32_e32 v152, v196, v152
	v_add_f32_e32 v153, v197, v153
	v_cvt_pk_bf16_f32 v161, v187, v189
	v_add_f32_e32 v152, v198, v152
	v_add_f32_e32 v153, v199, v153
	v_cvt_pk_bf16_f32 v186, v191, v193
	v_add_f32_e32 v152, v200, v152
	v_add_f32_e32 v153, v201, v153
	v_cvt_pk_bf16_f32 v187, v195, v197
	v_add_f32_e32 v152, v202, v152
	v_add_f32_e32 v153, v203, v153
	v_cvt_pk_bf16_f32 v188, v199, v201
	v_add_f32_e32 v152, v204, v152
	v_add_f32_e32 v153, v205, v153
	v_cvt_pk_bf16_f32 v189, v203, v205
	v_add_f32_e32 v120, v120, v152
	v_add_f32_e32 v121, v121, v153
	v_cvt_pk_bf16_f32 v152, v190, v192
	v_cvt_pk_bf16_f32 v153, v194, v196
	v_cvt_pk_bf16_f32 v154, v198, v200
	v_cvt_pk_bf16_f32 v155, v202, v204
	s_setprio 1
	s_waitcnt lgkmcnt(3)
	v_mfma_f32_16x16x32_bf16 v[34:37], v[168:171], v[160:163], v[34:37]
	s_waitcnt lgkmcnt(2)
	v_mfma_f32_16x16x32_bf16 v[38:41], v[172:175], v[160:163], v[38:41]
	s_waitcnt lgkmcnt(1)
	v_mfma_f32_16x16x32_bf16 v[42:45], v[176:179], v[160:163], v[42:45]
	s_waitcnt lgkmcnt(0)
	v_mfma_f32_16x16x32_bf16 v[46:49], v[182:185], v[160:163], v[46:49]
	v_mfma_f32_16x16x32_bf16 v[50:53], v[168:171], v[164:167], v[50:53]
	v_mfma_f32_16x16x32_bf16 v[54:57], v[172:175], v[164:167], v[54:57]
	v_mfma_f32_16x16x32_bf16 v[58:61], v[176:179], v[164:167], v[58:61]
	v_mfma_f32_16x16x32_bf16 v[62:65], v[182:185], v[164:167], v[62:65]
	v_mfma_f32_16x16x32_bf16 v[66:69], v[168:171], v[186:189], v[66:69]
	v_mfma_f32_16x16x32_bf16 v[70:73], v[172:175], v[186:189], v[70:73]
	v_mfma_f32_16x16x32_bf16 v[74:77], v[176:179], v[186:189], v[74:77]
	v_mfma_f32_16x16x32_bf16 v[78:81], v[182:185], v[186:189], v[78:81]
	v_mfma_f32_16x16x32_bf16 v[82:85], v[168:171], v[152:155], v[82:85]
	v_mfma_f32_16x16x32_bf16 v[86:89], v[172:175], v[152:155], v[86:89]
	v_mfma_f32_16x16x32_bf16 v[90:93], v[176:179], v[152:155], v[90:93]
	v_mfma_f32_16x16x32_bf16 v[94:97], v[182:185], v[152:155], v[94:97]
	s_setprio 0
	s_mov_b32 s20, 1
	s_and_b64 vcc, exec, s[18:19]
	s_mov_b64 s[18:19], 0
	s_cbranch_vccnz .LBB0_2477

.LBB0_2494:
	s_lshl_b32 s57, s52, 5
	s_or_b32 s53, s57, s16
	s_cmp_gt_i32 s53, s46
	s_cselect_b64 s[74:75], -1, 0
	s_or_b32 s59, s53, 31
	s_cmp_lt_i32 s59, s24
	s_cselect_b64 s[76:77], -1, 0
	s_or_b64 s[74:75], s[74:75], s[76:77]
	s_and_b64 vcc, exec, s[74:75]
	s_cbranch_vccnz .LBB0_2493
	v_add_u32_e32 v182, s53, v144
	v_sub_u32_e32 v183, v227, v182
	v_cvt_f32_i32_e32 v184, v183
	v_xad_u32 v185, v182, -1, v227
	v_cvt_f32_i32_e32 v186, v185
	v_cmp_gt_u32_e32 vcc, s50, v183
	v_or_b32_e32 v183, 2, v182
	v_sub_u32_e32 v183, v227, v183
	v_cndmask_b32_e32 v210, v1, v184, vcc
	v_cmp_gt_u32_e32 vcc, s50, v185
	v_cvt_f32_i32_e32 v184, v183
	v_or_b32_e32 v185, 3, v182
	v_sub_u32_e32 v185, v227, v185
	v_cndmask_b32_e32 v211, v1, v186, vcc
	v_cvt_f32_i32_e32 v186, v185
	v_cmp_gt_u32_e32 vcc, s50, v183
	v_or_b32_e32 v183, 4, v182
	v_sub_u32_e32 v183, v227, v183
	v_or_b32_e32 v150, s57, v226
	v_cndmask_b32_e32 v212, v1, v184, vcc
	v_cvt_f32_i32_e32 v184, v183
	v_mad_u32_u24 v162, v150, s49, v131
	v_lshl_add_u32 v178, s52, 6, v148
	v_cmp_gt_u32_e32 vcc, s50, v185
	v_or_b32_e32 v185, 5, v182
	ds_read_b128 v[150:153], v162
	ds_read_b128 v[154:157], v162 offset:64
	ds_read_b128 v[158:161], v162 offset:2304
	ds_read_b128 v[162:165], v162 offset:2368
	ds_read_b128 v[166:169], v178 offset:9216
	ds_read_b128 v[170:173], v178 offset:11520
	ds_read_b128 v[174:177], v178 offset:13824
	ds_read_b128 v[178:181], v178 offset:16128
	v_cndmask_b32_e32 v213, v1, v186, vcc
	v_sub_u32_e32 v185, v227, v185
	v_cmp_gt_u32_e32 vcc, s50, v183
	v_or_b32_e32 v183, 6, v182
	v_cvt_f32_i32_e32 v186, v185
	v_sub_u32_e32 v183, v227, v183
	v_or_b32_e32 v182, 7, v182
	v_cndmask_b32_e32 v230, v1, v184, vcc
	v_cvt_f32_i32_e32 v184, v183
	v_sub_u32_e32 v182, v227, v182
	v_cmp_gt_u32_e32 vcc, s50, v185
	v_cvt_f32_i32_e32 v185, v182
	s_nop 0
	v_cndmask_b32_e32 v231, v1, v186, vcc
	v_cmp_gt_u32_e32 vcc, s50, v183
	s_nop 1
	v_cndmask_b32_e32 v232, v1, v184, vcc
	v_cmp_gt_u32_e32 vcc, s50, v182
	s_nop 1
	v_cndmask_b32_e32 v233, v1, v185, vcc
	s_setprio 1
	s_waitcnt lgkmcnt(7)
	v_mfma_f32_16x16x32_bf16 v[182:185], v[150:153], v[2:5], 0
	v_mfma_f32_16x16x32_bf16 v[190:193], v[150:153], v[10:13], 0
	v_mfma_f32_16x16x32_bf16 v[198:201], v[150:153], v[18:21], 0
	v_mfma_f32_16x16x32_bf16 v[150:153], v[150:153], v[26:29], 0
	s_waitcnt lgkmcnt(6)
	v_mfma_f32_16x16x32_bf16 v[182:185], v[154:157], v[6:9], v[182:185]
	s_waitcnt lgkmcnt(5)
	v_mfma_f32_16x16x32_bf16 v[186:189], v[158:161], v[2:5], 0
	v_mfma_f32_16x16x32_bf16 v[190:193], v[154:157], v[14:17], v[190:193]
	v_mfma_f32_16x16x32_bf16 v[194:197], v[158:161], v[10:13], 0
	v_mfma_f32_16x16x32_bf16 v[198:201], v[154:157], v[22:25], v[198:201]
	v_mfma_f32_16x16x32_bf16 v[202:205], v[158:161], v[18:21], 0
	v_mfma_f32_16x16x32_bf16 v[150:153], v[154:157], v[30:33], v[150:153]
	v_mfma_f32_16x16x32_bf16 v[154:157], v[158:161], v[26:29], 0
	s_waitcnt lgkmcnt(4)
	v_mfma_f32_16x16x32_bf16 v[186:189], v[162:165], v[6:9], v[186:189]
	v_mfma_f32_16x16x32_bf16 v[194:197], v[162:165], v[14:17], v[194:197]
	v_mfma_f32_16x16x32_bf16 v[202:205], v[162:165], v[22:25], v[202:205]
	v_mfma_f32_16x16x32_bf16 v[154:157], v[162:165], v[30:33], v[154:157]
	s_setprio 0
	v_fma_f32 v158, -v215, v210, v182
	v_fma_f32 v162, -v216, v210, v190
	v_exp_f32_e32 v163, v158
	v_fma_f32 v158, -v215, v211, v183
	v_exp_f32_e32 v162, v162
	v_fma_f32 v164, -v216, v211, v191
	v_exp_f32_e32 v165, v158
	v_fma_f32 v158, -v215, v212, v184
	v_exp_f32_e32 v164, v164
	v_fma_f32 v182, -v216, v212, v192
	v_exp_f32_e32 v183, v158
	v_fma_f32 v158, -v215, v213, v185
	v_exp_f32_e32 v182, v182
	v_fma_f32 v184, -v216, v213, v193
	v_exp_f32_e32 v185, v158
	v_fma_f32 v158, -v215, v230, v186
	v_exp_f32_e32 v184, v184
	v_fma_f32 v186, -v216, v230, v194
	v_exp_f32_e32 v207, v158
	v_fma_f32 v158, -v215, v231, v187
	v_exp_f32_e32 v206, v186
	v_fma_f32 v186, -v216, v231, v195
	v_add_f32_e32 v190, 0, v162
	v_add_f32_e32 v191, 0, v163
	v_exp_f32_e32 v187, v158
	v_fma_f32 v158, -v215, v232, v188
	v_exp_f32_e32 v186, v186
	v_fma_f32 v188, -v216, v232, v196
	v_add_f32_e32 v190, v164, v190
	v_add_f32_e32 v191, v165, v191
	v_exp_f32_e32 v209, v158
	v_fma_f32 v158, -v215, v233, v189
	v_exp_f32_e32 v208, v188
	v_fma_f32 v188, -v216, v233, v197
	v_add_f32_e32 v190, v182, v190
	v_add_f32_e32 v191, v183, v191
	v_exp_f32_e32 v189, v158
	v_exp_f32_e32 v188, v188
	v_add_f32_e32 v190, v184, v190
	v_add_f32_e32 v191, v185, v191
	v_fma_f32 v150, -v218, v210, v150
	v_add_f32_e32 v190, v206, v190
	v_add_f32_e32 v191, v207, v191
	v_cvt_pk_bf16_f32 v162, v162, v164
	v_add_f32_e32 v190, v186, v190
	v_add_f32_e32 v191, v187, v191
	v_cvt_pk_bf16_f32 v164, v206, v186
	v_add_f32_e32 v190, v208, v190
	v_add_f32_e32 v191, v209, v191
	v_exp_f32_e32 v186, v150
	v_fma_f32 v150, -v218, v211, v151
	v_cvt_pk_bf16_f32 v158, v163, v165
	v_add_f32_e32 v190, v188, v190
	v_add_f32_e32 v191, v189, v191
	v_cvt_pk_bf16_f32 v165, v208, v188
	v_exp_f32_e32 v188, v150
	v_fma_f32 v150, -v218, v212, v152
	v_add_f32_e32 v122, v122, v190
	v_add_f32_e32 v123, v123, v191
	v_cvt_pk_bf16_f32 v163, v182, v184
	v_fma_f32 v182, -v217, v210, v198
	v_exp_f32_e32 v190, v150
	v_fma_f32 v150, -v218, v213, v153
	v_cvt_pk_bf16_f32 v160, v207, v187
	v_exp_f32_e32 v187, v182
	v_fma_f32 v182, -v217, v211, v199
	v_exp_f32_e32 v192, v150
	v_fma_f32 v150, -v218, v230, v154
	v_cvt_pk_bf16_f32 v161, v209, v189
	v_exp_f32_e32 v189, v182
	v_fma_f32 v182, -v217, v212, v200
	v_exp_f32_e32 v194, v150
	v_fma_f32 v150, -v218, v231, v155
	v_exp_f32_e32 v191, v182
	v_fma_f32 v182, -v217, v213, v201
	v_exp_f32_e32 v196, v150
	v_fma_f32 v150, -v218, v232, v156
	v_exp_f32_e32 v193, v182
	v_fma_f32 v182, -v217, v230, v202
	v_exp_f32_e32 v198, v150
	v_fma_f32 v150, -v218, v233, v157
	v_exp_f32_e32 v195, v182
	v_fma_f32 v182, -v217, v231, v203
	v_exp_f32_e32 v200, v150
	v_add_f32_e32 v150, 0, v186
	v_add_f32_e32 v151, 0, v187
	v_exp_f32_e32 v197, v182
	v_fma_f32 v182, -v217, v232, v204
	v_add_f32_e32 v150, v188, v150
	v_add_f32_e32 v151, v189, v151
	v_exp_f32_e32 v199, v182
	v_fma_f32 v182, -v217, v233, v205
	v_add_f32_e32 v150, v190, v150
	v_add_f32_e32 v151, v191, v151
	v_exp_f32_e32 v201, v182
	v_add_f32_e32 v150, v192, v150
	v_add_f32_e32 v151, v193, v151
	v_cvt_pk_bf16_f32 v159, v183, v185
	v_add_f32_e32 v150, v194, v150
	v_add_f32_e32 v151, v195, v151
	v_cvt_pk_bf16_f32 v182, v187, v189
	v_add_f32_e32 v150, v196, v150
	v_add_f32_e32 v151, v197, v151
	v_cvt_pk_bf16_f32 v183, v191, v193
	v_add_f32_e32 v150, v198, v150
	v_add_f32_e32 v151, v199, v151
	v_cvt_pk_bf16_f32 v184, v195, v197
	v_add_f32_e32 v150, v200, v150
	v_add_f32_e32 v151, v201, v151
	v_cvt_pk_bf16_f32 v185, v199, v201
	v_add_f32_e32 v120, v120, v150
	v_add_f32_e32 v121, v121, v151
	v_cvt_pk_bf16_f32 v150, v186, v188
	v_cvt_pk_bf16_f32 v151, v190, v192
	v_cvt_pk_bf16_f32 v152, v194, v196
	v_cvt_pk_bf16_f32 v153, v198, v200
	s_setprio 1
	s_waitcnt lgkmcnt(3)
	v_mfma_f32_16x16x32_bf16 v[94:97], v[166:169], v[158:161], v[94:97]
	s_waitcnt lgkmcnt(2)
	v_mfma_f32_16x16x32_bf16 v[90:93], v[170:173], v[158:161], v[90:93]
	s_waitcnt lgkmcnt(1)
	v_mfma_f32_16x16x32_bf16 v[86:89], v[174:177], v[158:161], v[86:89]
	s_waitcnt lgkmcnt(0)
	v_mfma_f32_16x16x32_bf16 v[82:85], v[178:181], v[158:161], v[82:85]
	v_mfma_f32_16x16x32_bf16 v[78:81], v[166:169], v[162:165], v[78:81]
	v_mfma_f32_16x16x32_bf16 v[74:77], v[170:173], v[162:165], v[74:77]
	v_mfma_f32_16x16x32_bf16 v[70:73], v[174:177], v[162:165], v[70:73]
	v_mfma_f32_16x16x32_bf16 v[66:69], v[178:181], v[162:165], v[66:69]
	v_mfma_f32_16x16x32_bf16 v[62:65], v[166:169], v[182:185], v[62:65]
	v_mfma_f32_16x16x32_bf16 v[58:61], v[170:173], v[182:185], v[58:61]
	v_mfma_f32_16x16x32_bf16 v[54:57], v[174:177], v[182:185], v[54:57]
	v_mfma_f32_16x16x32_bf16 v[50:53], v[178:181], v[182:185], v[50:53]
	v_mfma_f32_16x16x32_bf16 v[46:49], v[166:169], v[150:153], v[46:49]
	v_mfma_f32_16x16x32_bf16 v[42:45], v[170:173], v[150:153], v[42:45]
	v_mfma_f32_16x16x32_bf16 v[38:41], v[174:177], v[150:153], v[38:41]
	v_mfma_f32_16x16x32_bf16 v[34:37], v[178:181], v[150:153], v[34:37]
	s_setprio 0
	s_branch .LBB0_2493

.LBB0_2515:
	s_or_b32 s52, s53, s20
	s_lshl_b32 s57, s52, 4
	s_cmp_ge_i32 s57, s24
	s_cbranch_scc1 .LBB0_2514
	v_or_b32_e32 v57, s53, v226
	v_mad_u32_u24 v57, v57, s49, v46
	ds_read_b128 v[58:61], v57
	ds_read_b128 v[62:65], v57 offset:64
	ds_read_b128 v[66:69], v57 offset:2304
	ds_read_b128 v[70:73], v57 offset:2368
	v_subrev_u32_e32 v57, s52, v48
	v_lshl_add_u32 v57, v57, 4, v49
	v_cvt_f32_u32_e32 v74, v57
	v_xad_u32 v75, s52, -1, v48
	v_lshl_add_u32 v75, v75, 4, v49
	v_cvt_f32_u32_e32 v76, v75
	v_cmp_gt_u32_e32 vcc, 2.0, v57
	s_nop 1
	v_cndmask_b32_e32 v57, v56, v74, vcc
	v_subrev_u32_e32 v74, s52, v50
	v_cmp_gt_u32_e32 vcc, 2.0, v75
	v_lshl_add_u32 v74, v74, 4, v49
	v_cvt_f32_u32_e32 v75, v74
	v_cndmask_b32_e32 v98, v56, v76, vcc
	v_subrev_u32_e32 v76, s52, v51
	v_lshl_add_u32 v76, v76, 4, v49
	v_cvt_f32_u32_e32 v77, v76
	v_cmp_gt_u32_e32 vcc, 2.0, v74
	v_subrev_u32_e32 v74, s52, v52
	v_lshl_add_u32 v74, v74, 4, v49
	v_cndmask_b32_e32 v99, v56, v75, vcc
	v_cmp_gt_u32_e32 vcc, 2.0, v76
	v_cvt_f32_u32_e32 v75, v74
	v_subrev_u32_e32 v76, s52, v53
	v_lshl_add_u32 v76, v76, 4, v49
	v_cndmask_b32_e32 v100, v56, v77, vcc
	v_cvt_f32_u32_e32 v77, v76
	v_cmp_gt_u32_e32 vcc, 2.0, v74
	v_subrev_u32_e32 v74, s52, v54
	v_lshl_add_u32 v74, v74, 4, v49
	v_cndmask_b32_e32 v101, v56, v75, vcc
	v_cmp_gt_u32_e32 vcc, 2.0, v76
	v_subrev_u32_e32 v76, s52, v55
	v_cvt_f32_u32_e32 v75, v74
	v_lshl_add_u32 v76, v76, 4, v49
	v_cndmask_b32_e32 v102, v56, v77, vcc
	v_cvt_f32_u32_e32 v77, v76
	v_cmp_gt_u32_e32 vcc, 2.0, v74
	s_nop 1
	v_cndmask_b32_e32 v103, v56, v75, vcc
	v_cmp_gt_u32_e32 vcc, 2.0, v76
	s_nop 1
	v_cndmask_b32_e32 v104, v56, v77, vcc
	s_setprio 1
	s_waitcnt vmcnt(7) lgkmcnt(3)
	v_mfma_f32_16x16x32_bf16 v[74:77], v[58:61], v[2:5], 0
	s_waitcnt vmcnt(5)
	v_mfma_f32_16x16x32_bf16 v[82:85], v[58:61], v[10:13], 0
	s_waitcnt vmcnt(3)
	v_mfma_f32_16x16x32_bf16 v[90:93], v[58:61], v[18:21], 0
	s_waitcnt vmcnt(1)
	v_mfma_f32_16x16x32_bf16 v[58:61], v[58:61], v[26:29], 0
	s_waitcnt lgkmcnt(2)
	v_mfma_f32_16x16x32_bf16 v[74:77], v[62:65], v[6:9], v[74:77]
	s_waitcnt lgkmcnt(1)
	v_mfma_f32_16x16x32_bf16 v[78:81], v[66:69], v[2:5], 0
	v_mfma_f32_16x16x32_bf16 v[82:85], v[62:65], v[14:17], v[82:85]
	v_mfma_f32_16x16x32_bf16 v[86:89], v[66:69], v[10:13], 0
	v_mfma_f32_16x16x32_bf16 v[90:93], v[62:65], v[22:25], v[90:93]
	v_mfma_f32_16x16x32_bf16 v[94:97], v[66:69], v[18:21], 0
	s_waitcnt vmcnt(0)
	v_mfma_f32_16x16x32_bf16 v[58:61], v[62:65], v[30:33], v[58:61]
	v_mfma_f32_16x16x32_bf16 v[62:65], v[66:69], v[26:29], 0
	s_waitcnt lgkmcnt(0)
	v_mfma_f32_16x16x32_bf16 v[78:81], v[70:73], v[6:9], v[78:81]
	v_mfma_f32_16x16x32_bf16 v[86:89], v[70:73], v[14:17], v[86:89]
	v_mfma_f32_16x16x32_bf16 v[94:97], v[70:73], v[22:25], v[94:97]
	v_mfma_f32_16x16x32_bf16 v[62:65], v[70:73], v[30:33], v[62:65]
	s_setprio 0
	v_fma_f32 v66, -v215, v57, v74
	v_exp_f32_e32 v67, v66
	v_fma_f32 v66, -v215, v98, v75
	v_exp_f32_e32 v69, v66
	v_fma_f32 v66, -v215, v99, v76
	v_exp_f32_e32 v71, v66
	v_fma_f32 v66, -v215, v100, v77
	v_exp_f32_e32 v73, v66
	v_fma_f32 v66, -v215, v101, v78
	v_exp_f32_e32 v75, v66
	v_fma_f32 v66, -v215, v102, v79
	v_exp_f32_e32 v77, v66
	v_fma_f32 v66, -v215, v103, v80
	v_exp_f32_e32 v79, v66
	v_fma_f32 v66, -v215, v104, v81
	v_exp_f32_e32 v81, v66
	v_fma_f32 v66, -v216, v57, v82
	v_exp_f32_e32 v66, v66
	v_fma_f32 v68, -v216, v98, v83
	v_exp_f32_e32 v68, v68
	v_fma_f32 v70, -v216, v99, v84
	v_exp_f32_e32 v70, v70
	v_fma_f32 v72, -v216, v100, v85
	v_exp_f32_e32 v72, v72
	v_fma_f32 v74, -v216, v101, v86
	v_exp_f32_e32 v74, v74
	v_fma_f32 v76, -v216, v102, v87
	v_add_f32_e32 v66, 0, v66
	v_add_f32_e32 v67, 0, v67
	v_exp_f32_e32 v76, v76
	v_fma_f32 v78, -v216, v103, v88
	v_add_f32_e32 v66, v68, v66
	v_add_f32_e32 v67, v69, v67
	v_exp_f32_e32 v78, v78
	v_fma_f32 v80, -v216, v104, v89
	v_add_f32_e32 v66, v70, v66
	v_add_f32_e32 v67, v71, v67
	v_exp_f32_e32 v80, v80
	v_add_f32_e32 v66, v72, v66
	v_add_f32_e32 v67, v73, v67
	s_nop 0
	v_add_f32_e32 v66, v74, v66
	v_add_f32_e32 v67, v75, v67
	s_nop 0
	v_add_f32_e32 v66, v76, v66
	v_add_f32_e32 v67, v77, v67
	s_nop 0
	v_add_f32_e32 v66, v78, v66
	v_add_f32_e32 v67, v79, v67
	s_nop 0
	v_add_f32_e32 v66, v80, v66
	v_add_f32_e32 v67, v81, v67
	s_nop 0
	v_add_f32_e32 v44, v44, v66
	v_add_f32_e32 v45, v45, v67
	v_fma_f32 v66, -v217, v57, v90
	v_exp_f32_e32 v67, v66
	v_fma_f32 v66, -v217, v98, v91
	v_exp_f32_e32 v69, v66
	v_fma_f32 v66, -v217, v99, v92
	v_exp_f32_e32 v71, v66
	v_fma_f32 v66, -v217, v100, v93
	v_exp_f32_e32 v73, v66
	v_fma_f32 v66, -v217, v101, v94
	v_exp_f32_e32 v75, v66
	v_fma_f32 v66, -v217, v102, v95
	v_exp_f32_e32 v77, v66
	v_fma_f32 v66, -v217, v103, v96
	v_exp_f32_e32 v79, v66
	v_fma_f32 v66, -v217, v104, v97
	v_fma_f32 v57, -v218, v57, v58
	v_exp_f32_e32 v81, v66
	v_exp_f32_e32 v66, v57
	v_fma_f32 v57, -v218, v98, v59
	v_exp_f32_e32 v68, v57
	v_fma_f32 v57, -v218, v99, v60
	v_exp_f32_e32 v70, v57
	v_fma_f32 v57, -v218, v100, v61
	v_exp_f32_e32 v72, v57
	v_fma_f32 v57, -v218, v101, v62
	v_exp_f32_e32 v74, v57
	v_fma_f32 v57, -v218, v102, v63
	v_add_f32_e32 v58, 0, v66
	v_add_f32_e32 v59, 0, v67
	v_exp_f32_e32 v76, v57
	v_fma_f32 v57, -v218, v103, v64
	v_add_f32_e32 v58, v68, v58
	v_add_f32_e32 v59, v69, v59
	v_exp_f32_e32 v78, v57
	v_fma_f32 v57, -v218, v104, v65
	v_add_f32_e32 v58, v70, v58
	v_add_f32_e32 v59, v71, v59
	v_exp_f32_e32 v80, v57
	v_add_f32_e32 v58, v72, v58
	v_add_f32_e32 v59, v73, v59
	s_nop 0
	v_add_f32_e32 v58, v74, v58
	v_add_f32_e32 v59, v75, v59
	s_nop 0
	v_add_f32_e32 v58, v76, v58
	v_add_f32_e32 v59, v77, v59
	s_nop 0
	v_add_f32_e32 v58, v78, v58
	v_add_f32_e32 v59, v79, v59
	s_nop 0
	v_add_f32_e32 v58, v80, v58
	v_add_f32_e32 v59, v81, v59
	s_nop 0
	v_add_f32_e32 v42, v42, v58
	v_add_f32_e32 v43, v43, v59
	s_branch .LBB0_2514

.LBB0_2523:
	v_readlane_b32 s16, v254, 60
	s_and_b64 vcc, exec, s[18:19]
	s_waitcnt lgkmcnt(0)
	v_add_u32_e32 v1, s16, v131
	s_barrier
	s_cbranch_vccz .LBB0_2535
	v_add_f32_e32 v38, v40, v38
	v_add_f32_e32 v39, v41, v39
	v_add_f32_e32 v34, v36, v34
	v_add_f32_e32 v35, v37, v35
	v_div_scale_f32 v40, s[16:17], v39, v39, 1.0
	v_rcp_f32_e32 v41, v40
	v_div_scale_f32 v42, vcc, 1.0, v39, 1.0
	v_div_scale_f32 v36, s[18:19], v35, v35, 1.0
	v_fma_f32 v43, -v40, v41, 1.0
	v_fmac_f32_e32 v41, v43, v41
	v_mul_f32_e32 v43, v42, v41
	v_fma_f32 v44, -v40, v43, v42
	v_fmac_f32_e32 v43, v44, v41
	v_fma_f32 v40, -v40, v43, v42
	v_div_fmas_f32 v40, v40, v41, v43
	v_div_scale_f32 v41, s[16:17], v38, v38, 1.0
	v_rcp_f32_e32 v42, v41
	v_div_fixup_f32 v40, v40, v39, 1.0
	v_cmp_lt_f32_e32 vcc, 0, v39
	v_rcp_f32_e32 v37, v36
	v_fma_f32 v39, -v41, v42, 1.0
	v_cndmask_b32_e32 v150, 0, v40, vcc
	v_fmac_f32_e32 v42, v39, v42
	v_div_scale_f32 v39, vcc, 1.0, v38, 1.0
	v_mul_f32_e32 v40, v39, v42
	v_fma_f32 v43, -v41, v40, v39
	v_fmac_f32_e32 v40, v43, v42
	v_fma_f32 v39, -v41, v40, v39
	v_div_fmas_f32 v39, v39, v42, v40
	v_div_fixup_f32 v39, v39, v38, 1.0
	v_cmp_lt_f32_e32 vcc, 0, v38
	v_fma_f32 v38, -v36, v37, 1.0
	v_fmac_f32_e32 v37, v38, v37
	v_cndmask_b32_e32 v152, 0, v39, vcc
	v_div_scale_f32 v38, vcc, 1.0, v35, 1.0
	v_mul_f32_e32 v39, v38, v37
	v_fma_f32 v40, -v36, v39, v38
	v_fmac_f32_e32 v39, v40, v37
	v_fma_f32 v36, -v36, v39, v38
	v_div_fmas_f32 v36, v36, v37, v39
	v_div_scale_f32 v37, s[18:19], v34, v34, 1.0
	v_rcp_f32_e32 v38, v37
	v_div_fixup_f32 v36, v36, v35, 1.0
	v_cmp_lt_f32_e32 vcc, 0, v35
	v_mov_b32_e32 v99, 0
	v_fma_f32 v35, -v37, v38, 1.0
	v_cndmask_b32_e32 v154, 0, v36, vcc
	v_fmac_f32_e32 v38, v35, v38
	v_div_scale_f32 v35, vcc, 1.0, v34, 1.0
	v_mul_f32_e32 v36, v35, v38
	v_fma_f32 v39, -v37, v36, v35
	v_fmac_f32_e32 v36, v39, v38
	v_fma_f32 v35, -v37, v36, v35
	v_div_fmas_f32 v35, v35, v38, v36
	v_div_fixup_f32 v35, v35, v34, 1.0
	v_cmp_lt_f32_e32 vcc, 0, v34
	s_mov_b32 s16, 0xffffff8
	v_mov_b32_e32 v98, v99
	v_cndmask_b32_e32 v156, 0, v35, vcc
	v_mul_u32_u24_e32 v161, 0x210, v226
	v_mul_lo_u32 v163, v160, s16
	v_mov_b32_e32 v100, v99
	v_mov_b32_e32 v101, v99
	v_mov_b64_e32 v[66:67], v[98:99]
	v_mov_b64_e32 v[70:71], v[98:99]
	v_mov_b64_e32 v[74:75], v[98:99]
	v_mov_b64_e32 v[78:79], v[98:99]
	v_mov_b64_e32 v[82:83], v[98:99]
	v_mov_b64_e32 v[86:87], v[98:99]
	v_mov_b64_e32 v[90:91], v[98:99]
	v_mov_b64_e32 v[94:95], v[98:99]
	v_mov_b64_e32 v[62:63], v[98:99]
	v_mov_b64_e32 v[58:59], v[98:99]
	v_mov_b64_e32 v[54:55], v[98:99]
	v_mov_b64_e32 v[50:51], v[98:99]
	v_mov_b64_e32 v[46:47], v[98:99]
	v_mov_b64_e32 v[42:43], v[98:99]
	v_mov_b64_e32 v[38:39], v[98:99]
	v_mov_b64_e32 v[34:35], v[98:99]
	s_mov_b32 s17, 0
	s_movk_i32 s49, 0x90
	v_mul_u32_u24_e32 v162, 0x90, v226
	v_subrev_u32_e32 v164, 31, v227
	v_add_u32_e32 v165, 0xffffffe, v163
	v_add_u32_e32 v166, 0xffffffd, v163
	v_add_u32_e32 v167, 0xffffffc, v163
	v_add_u32_e32 v168, 0xffffffb, v163
	v_add_u32_e32 v169, 0xffffffa, v163
	v_add_u32_e32 v170, 0xffffff9, v163
	v_add3_u32 v171, v1, v161, v144
	v_mov_b32_e32 v157, v156
	v_mov_b32_e32 v155, v154
	v_mov_b32_e32 v153, v152
	v_mov_b32_e32 v151, v150
	v_add_u32_e32 v172, v145, v230
	v_mov_b32_e32 v173, 0x49742400
	v_mov_b64_e32 v[68:69], v[100:101]
	v_mov_b64_e32 v[72:73], v[100:101]
	v_mov_b64_e32 v[76:77], v[100:101]
	v_mov_b64_e32 v[80:81], v[100:101]
	v_mov_b64_e32 v[84:85], v[100:101]
	v_mov_b64_e32 v[88:89], v[100:101]
	v_mov_b64_e32 v[92:93], v[100:101]
	v_mov_b64_e32 v[96:97], v[100:101]
	v_mov_b64_e32 v[64:65], v[100:101]
	v_mov_b64_e32 v[60:61], v[100:101]
	v_mov_b64_e32 v[56:57], v[100:101]
	v_mov_b64_e32 v[52:53], v[100:101]
	v_mov_b64_e32 v[48:49], v[100:101]
	v_mov_b64_e32 v[44:45], v[100:101]
	v_mov_b64_e32 v[40:41], v[100:101]
	v_mov_b64_e32 v[36:37], v[100:101]
	s_mov_b32 s50, 0

.LBB0_2689:
	s_lshl_b32 s21, s20, 5
	v_or_b32_e32 v151, s21, v226
	v_mad_u32_u24 v151, v151, s52, v148
	ds_read_b128 v[152:155], v151
	ds_read_b128 v[156:159], v151 offset:64
	ds_read_b128 v[160:163], v151 offset:2304
	ds_read_b128 v[164:167], v151 offset:2368
	v_lshl_add_u32 v151, s20, 6, v149
	ds_read_b128 v[168:171], v151 offset:9216
	ds_read_b128 v[172:175], v151 offset:11520
	ds_read_b128 v[176:179], v151 offset:13824
	ds_read_b128 v[182:185], v151 offset:16128
	v_add_u32_e32 v151, s21, v150
	v_sub_u32_e32 v180, v227, v151
	v_cmp_gt_u32_e32 vcc, 2.0, v180
	v_cvt_f32_i32_e32 v180, v180
	v_xad_u32 v186, v151, -1, v227
	v_cvt_f32_i32_e32 v187, v186
	s_and_b64 vcc, s[16:17], vcc
	v_cndmask_b32_e32 v180, v233, v180, vcc
	v_cmp_gt_u32_e32 vcc, 2.0, v186
	v_or_b32_e32 v186, 2, v151
	s_and_b64 vcc, s[16:17], vcc
	v_sub_u32_e32 v186, v227, v186
	v_cndmask_b32_e32 v234, v233, v187, vcc
	v_cmp_gt_u32_e32 vcc, 2.0, v186
	v_cvt_f32_i32_e32 v186, v186
	v_or_b32_e32 v187, 3, v151
	v_sub_u32_e32 v187, v227, v187
	v_cvt_f32_i32_e32 v188, v187
	s_and_b64 vcc, s[16:17], vcc
	v_cndmask_b32_e32 v235, v233, v186, vcc
	v_cmp_gt_u32_e32 vcc, 2.0, v187
	v_or_b32_e32 v186, 4, v151
	s_and_b64 vcc, s[16:17], vcc
	v_sub_u32_e32 v186, v227, v186
	v_cndmask_b32_e32 v236, v233, v188, vcc
	v_cmp_gt_u32_e32 vcc, 2.0, v186
	v_cvt_f32_i32_e32 v186, v186
	v_or_b32_e32 v187, 5, v151
	v_sub_u32_e32 v187, v227, v187
	v_cvt_f32_i32_e32 v188, v187
	s_and_b64 vcc, s[16:17], vcc
	v_cndmask_b32_e32 v237, v233, v186, vcc
	v_cmp_gt_u32_e32 vcc, 2.0, v187
	v_or_b32_e32 v186, 6, v151
	s_and_b64 vcc, s[16:17], vcc
	v_sub_u32_e32 v186, v227, v186
	v_cndmask_b32_e32 v238, v233, v188, vcc
	v_cmp_gt_u32_e32 vcc, 2.0, v186
	v_cvt_f32_i32_e32 v186, v186
	v_or_b32_e32 v151, 7, v151
	v_sub_u32_e32 v151, v227, v151
	v_cvt_f32_i32_e32 v187, v151
	s_and_b64 vcc, s[16:17], vcc
	v_cndmask_b32_e32 v239, v233, v186, vcc
	v_cmp_gt_u32_e32 vcc, 2.0, v151
	s_and_b64 vcc, s[16:17], vcc
	s_nop 0
	v_cndmask_b32_e32 v151, v233, v187, vcc
	s_setprio 1
	s_waitcnt lgkmcnt(7)
	v_mfma_f32_16x16x32_bf16 v[186:189], v[152:155], v[2:5], 0
	v_mfma_f32_16x16x32_bf16 v[194:197], v[152:155], v[10:13], 0
	v_mfma_f32_16x16x32_bf16 v[202:205], v[152:155], v[18:21], 0
	v_mfma_f32_16x16x32_bf16 v[152:155], v[152:155], v[26:29], 0
	s_waitcnt lgkmcnt(6)
	v_mfma_f32_16x16x32_bf16 v[186:189], v[156:159], v[6:9], v[186:189]
	s_waitcnt lgkmcnt(5)
	v_mfma_f32_16x16x32_bf16 v[190:193], v[160:163], v[2:5], 0
	v_mfma_f32_16x16x32_bf16 v[194:197], v[156:159], v[14:17], v[194:197]
	v_mfma_f32_16x16x32_bf16 v[198:201], v[160:163], v[10:13], 0
	v_mfma_f32_16x16x32_bf16 v[202:205], v[156:159], v[22:25], v[202:205]
	v_mfma_f32_16x16x32_bf16 v[206:209], v[160:163], v[18:21], 0
	v_mfma_f32_16x16x32_bf16 v[152:155], v[156:159], v[30:33], v[152:155]
	v_mfma_f32_16x16x32_bf16 v[156:159], v[160:163], v[26:29], 0
	s_waitcnt lgkmcnt(4)
	v_mfma_f32_16x16x32_bf16 v[190:193], v[164:167], v[6:9], v[190:193]
	v_mfma_f32_16x16x32_bf16 v[198:201], v[164:167], v[14:17], v[198:201]
	v_mfma_f32_16x16x32_bf16 v[206:209], v[164:167], v[22:25], v[206:209]
	v_mfma_f32_16x16x32_bf16 v[156:159], v[164:167], v[30:33], v[156:159]
	s_setprio 0
	v_fma_f32 v160, -v215, v180, v186
	v_fma_f32 v164, -v216, v180, v194
	v_exp_f32_e32 v165, v160
	v_fma_f32 v160, -v215, v234, v187
	v_exp_f32_e32 v164, v164
	v_fma_f32 v166, -v216, v234, v195
	v_exp_f32_e32 v167, v160
	v_fma_f32 v160, -v215, v235, v188
	v_exp_f32_e32 v166, v166
	v_fma_f32 v186, -v216, v235, v196
	v_exp_f32_e32 v187, v160
	v_fma_f32 v160, -v215, v236, v189
	v_exp_f32_e32 v186, v186
	v_fma_f32 v188, -v216, v236, v197
	v_exp_f32_e32 v189, v160
	v_fma_f32 v160, -v215, v237, v190
	v_exp_f32_e32 v188, v188
	v_fma_f32 v190, -v216, v237, v198
	v_exp_f32_e32 v211, v160
	v_fma_f32 v160, -v215, v238, v191
	v_exp_f32_e32 v210, v190
	v_fma_f32 v190, -v216, v238, v199
	v_add_f32_e32 v194, 0, v164
	v_add_f32_e32 v195, 0, v165
	v_exp_f32_e32 v191, v160
	v_fma_f32 v160, -v215, v239, v192
	v_exp_f32_e32 v190, v190
	v_fma_f32 v192, -v216, v239, v200
	v_add_f32_e32 v194, v166, v194
	v_add_f32_e32 v195, v167, v195
	v_exp_f32_e32 v213, v160
	v_fma_f32 v160, -v215, v151, v193
	v_exp_f32_e32 v212, v192
	v_fma_f32 v192, -v216, v151, v201
	v_add_f32_e32 v194, v186, v194
	v_add_f32_e32 v195, v187, v195
	v_exp_f32_e32 v193, v160
	v_exp_f32_e32 v192, v192
	v_add_f32_e32 v194, v188, v194
	v_add_f32_e32 v195, v189, v195
	v_fma_f32 v152, -v218, v180, v152
	v_add_f32_e32 v194, v210, v194
	v_add_f32_e32 v195, v211, v195
	v_cvt_pk_bf16_f32 v164, v164, v166
	v_add_f32_e32 v194, v190, v194
	v_add_f32_e32 v195, v191, v195
	v_cvt_pk_bf16_f32 v166, v210, v190
	v_add_f32_e32 v194, v212, v194
	v_add_f32_e32 v195, v213, v195
	v_exp_f32_e32 v190, v152
	v_fma_f32 v152, -v218, v234, v153
	v_cvt_pk_bf16_f32 v160, v165, v167
	v_add_f32_e32 v194, v192, v194
	v_add_f32_e32 v195, v193, v195
	v_cvt_pk_bf16_f32 v165, v186, v188
	v_cvt_pk_bf16_f32 v167, v212, v192
	v_fma_f32 v186, -v217, v180, v202
	v_exp_f32_e32 v192, v152
	v_fma_f32 v152, -v218, v235, v154
	v_cvt_pk_bf16_f32 v162, v211, v191
	v_add_f32_e32 v122, v122, v194
	v_add_f32_e32 v123, v123, v195
	v_exp_f32_e32 v191, v186
	v_fma_f32 v186, -v217, v234, v203
	v_exp_f32_e32 v194, v152
	v_fma_f32 v152, -v218, v236, v155
	v_cvt_pk_bf16_f32 v163, v213, v193
	v_exp_f32_e32 v193, v186
	v_fma_f32 v186, -v217, v235, v204
	v_exp_f32_e32 v196, v152
	v_fma_f32 v152, -v218, v237, v156
	v_exp_f32_e32 v195, v186
	v_fma_f32 v186, -v217, v236, v205
	v_exp_f32_e32 v198, v152
	v_fma_f32 v152, -v218, v238, v157
	v_exp_f32_e32 v197, v186
	v_fma_f32 v186, -v217, v237, v206
	v_exp_f32_e32 v200, v152
	v_fma_f32 v152, -v218, v239, v158
	v_exp_f32_e32 v199, v186
	v_fma_f32 v186, -v217, v238, v207
	v_exp_f32_e32 v202, v152
	v_add_f32_e32 v152, 0, v190
	v_add_f32_e32 v153, 0, v191
	v_exp_f32_e32 v201, v186
	v_fma_f32 v186, -v217, v239, v208
	v_add_f32_e32 v152, v192, v152
	v_add_f32_e32 v153, v193, v153
	v_exp_f32_e32 v203, v186
	v_fma_f32 v186, -v217, v151, v209
	v_fma_f32 v151, -v218, v151, v159
	v_add_f32_e32 v152, v194, v152
	v_add_f32_e32 v153, v195, v153
	v_exp_f32_e32 v205, v186
	v_exp_f32_e32 v204, v151
	v_add_f32_e32 v152, v196, v152
	v_add_f32_e32 v153, v197, v153
	v_cvt_pk_bf16_f32 v161, v187, v189
	v_add_f32_e32 v152, v198, v152
	v_add_f32_e32 v153, v199, v153
	v_cvt_pk_bf16_f32 v186, v191, v193
	v_add_f32_e32 v152, v200, v152
	v_add_f32_e32 v153, v201, v153
	v_cvt_pk_bf16_f32 v187, v195, v197
	v_add_f32_e32 v152, v202, v152
	v_add_f32_e32 v153, v203, v153
	v_cvt_pk_bf16_f32 v188, v199, v201
	v_add_f32_e32 v152, v204, v152
	v_add_f32_e32 v153, v205, v153
	v_cvt_pk_bf16_f32 v189, v203, v205
	v_add_f32_e32 v120, v120, v152
	v_add_f32_e32 v121, v121, v153
	v_cvt_pk_bf16_f32 v152, v190, v192
	v_cvt_pk_bf16_f32 v153, v194, v196
	v_cvt_pk_bf16_f32 v154, v198, v200
	v_cvt_pk_bf16_f32 v155, v202, v204
	s_setprio 1
	s_waitcnt lgkmcnt(3)
	v_mfma_f32_16x16x32_bf16 v[34:37], v[168:171], v[160:163], v[34:37]
	s_waitcnt lgkmcnt(2)
	v_mfma_f32_16x16x32_bf16 v[38:41], v[172:175], v[160:163], v[38:41]
	s_waitcnt lgkmcnt(1)
	v_mfma_f32_16x16x32_bf16 v[42:45], v[176:179], v[160:163], v[42:45]
	s_waitcnt lgkmcnt(0)
	v_mfma_f32_16x16x32_bf16 v[46:49], v[182:185], v[160:163], v[46:49]
	v_mfma_f32_16x16x32_bf16 v[50:53], v[168:171], v[164:167], v[50:53]
	v_mfma_f32_16x16x32_bf16 v[54:57], v[172:175], v[164:167], v[54:57]
	v_mfma_f32_16x16x32_bf16 v[58:61], v[176:179], v[164:167], v[58:61]
	v_mfma_f32_16x16x32_bf16 v[62:65], v[182:185], v[164:167], v[62:65]
	v_mfma_f32_16x16x32_bf16 v[66:69], v[168:171], v[186:189], v[66:69]
	v_mfma_f32_16x16x32_bf16 v[70:73], v[172:175], v[186:189], v[70:73]
	v_mfma_f32_16x16x32_bf16 v[74:77], v[176:179], v[186:189], v[74:77]
	v_mfma_f32_16x16x32_bf16 v[78:81], v[182:185], v[186:189], v[78:81]
	v_mfma_f32_16x16x32_bf16 v[82:85], v[168:171], v[152:155], v[82:85]
	v_mfma_f32_16x16x32_bf16 v[86:89], v[172:175], v[152:155], v[86:89]
	v_mfma_f32_16x16x32_bf16 v[90:93], v[176:179], v[152:155], v[90:93]
	v_mfma_f32_16x16x32_bf16 v[94:97], v[182:185], v[152:155], v[94:97]
	s_setprio 0
	s_mov_b32 s20, 1
	s_and_b64 vcc, exec, s[18:19]
	s_mov_b64 s[18:19], 0
	s_cbranch_vccnz .LBB0_2689

.LBB0_2706:
	s_lshl_b32 s57, s52, 5
	s_or_b32 s53, s57, s16
	s_cmp_gt_i32 s53, s46
	s_cselect_b64 s[64:65], -1, 0
	s_or_b32 s59, s53, 31
	s_cmp_lt_i32 s59, s24
	s_cselect_b64 s[66:67], -1, 0
	s_or_b64 s[64:65], s[64:65], s[66:67]
	s_and_b64 vcc, exec, s[64:65]
	s_cbranch_vccnz .LBB0_2705
	v_or_b32_e32 v151, s57, v226
	v_mad_u32_u24 v151, v151, s49, v148
	ds_read_b128 v[152:155], v151
	ds_read_b128 v[156:159], v151 offset:64
	ds_read_b128 v[160:163], v151 offset:2304
	ds_read_b128 v[164:167], v151 offset:2368
	v_lshl_add_u32 v151, s52, 6, v150
	ds_read_b128 v[168:171], v151 offset:9216
	ds_read_b128 v[172:175], v151 offset:11520
	ds_read_b128 v[176:179], v151 offset:13824
	ds_read_b128 v[180:183], v151 offset:16128
	v_add_u32_e32 v151, s53, v144
	v_sub_u32_e32 v184, v227, v151
	v_cvt_f32_i32_e32 v185, v184
	v_xad_u32 v186, v151, -1, v227
	v_cvt_f32_i32_e32 v187, v186
	v_cmp_gt_u32_e32 vcc, s50, v184
	v_or_b32_e32 v184, 2, v151
	v_sub_u32_e32 v184, v227, v184
	v_cndmask_b32_e32 v212, v131, v185, vcc
	v_cmp_gt_u32_e32 vcc, s50, v186
	v_cvt_f32_i32_e32 v185, v184
	v_or_b32_e32 v186, 3, v151
	v_sub_u32_e32 v186, v227, v186
	v_cndmask_b32_e32 v213, v131, v187, vcc
	v_cvt_f32_i32_e32 v187, v186
	v_cmp_gt_u32_e32 vcc, s50, v184
	v_or_b32_e32 v184, 4, v151
	v_sub_u32_e32 v184, v227, v184
	v_cndmask_b32_e32 v224, v131, v185, vcc
	v_cvt_f32_i32_e32 v185, v184
	v_cmp_gt_u32_e32 vcc, s50, v186
	v_or_b32_e32 v186, 5, v151
	v_sub_u32_e32 v186, v227, v186
	v_cndmask_b32_e32 v225, v131, v187, vcc
	v_cmp_gt_u32_e32 vcc, s50, v184
	v_or_b32_e32 v184, 6, v151
	v_cvt_f32_i32_e32 v187, v186
	v_sub_u32_e32 v184, v227, v184
	v_or_b32_e32 v151, 7, v151
	v_cndmask_b32_e32 v228, v131, v185, vcc
	v_cvt_f32_i32_e32 v185, v184
	v_sub_u32_e32 v151, v227, v151
	v_cmp_gt_u32_e32 vcc, s50, v186
	v_cvt_f32_i32_e32 v186, v151
	s_nop 0
	v_cndmask_b32_e32 v229, v131, v187, vcc
	v_cmp_gt_u32_e32 vcc, s50, v184
	s_nop 1
	v_cndmask_b32_e32 v230, v131, v185, vcc
	v_cmp_gt_u32_e32 vcc, s50, v151
	s_nop 1
	v_cndmask_b32_e32 v151, v131, v186, vcc
	s_setprio 1
	s_waitcnt lgkmcnt(7)
	v_mfma_f32_16x16x32_bf16 v[184:187], v[152:155], v[2:5], 0
	v_mfma_f32_16x16x32_bf16 v[192:195], v[152:155], v[10:13], 0
	v_mfma_f32_16x16x32_bf16 v[200:203], v[152:155], v[18:21], 0
	v_mfma_f32_16x16x32_bf16 v[152:155], v[152:155], v[26:29], 0
	s_waitcnt lgkmcnt(6)
	v_mfma_f32_16x16x32_bf16 v[184:187], v[156:159], v[6:9], v[184:187]
	s_waitcnt lgkmcnt(5)
	v_mfma_f32_16x16x32_bf16 v[188:191], v[160:163], v[2:5], 0
	v_mfma_f32_16x16x32_bf16 v[192:195], v[156:159], v[14:17], v[192:195]
	v_mfma_f32_16x16x32_bf16 v[196:199], v[160:163], v[10:13], 0
	v_mfma_f32_16x16x32_bf16 v[200:203], v[156:159], v[22:25], v[200:203]
	v_mfma_f32_16x16x32_bf16 v[204:207], v[160:163], v[18:21], 0
	v_mfma_f32_16x16x32_bf16 v[152:155], v[156:159], v[30:33], v[152:155]
	v_mfma_f32_16x16x32_bf16 v[156:159], v[160:163], v[26:29], 0
	s_waitcnt lgkmcnt(4)
	v_mfma_f32_16x16x32_bf16 v[188:191], v[164:167], v[6:9], v[188:191]
	v_mfma_f32_16x16x32_bf16 v[196:199], v[164:167], v[14:17], v[196:199]
	v_mfma_f32_16x16x32_bf16 v[204:207], v[164:167], v[22:25], v[204:207]
	v_mfma_f32_16x16x32_bf16 v[156:159], v[164:167], v[30:33], v[156:159]
	s_setprio 0
	v_fma_f32 v160, -v215, v212, v184
	v_fma_f32 v164, -v216, v212, v192
	v_exp_f32_e32 v165, v160
	v_fma_f32 v160, -v215, v213, v185
	v_exp_f32_e32 v164, v164
	v_fma_f32 v166, -v216, v213, v193
	v_exp_f32_e32 v167, v160
	v_fma_f32 v160, -v215, v224, v186
	v_exp_f32_e32 v166, v166
	v_fma_f32 v184, -v216, v224, v194
	v_exp_f32_e32 v185, v160
	v_fma_f32 v160, -v215, v225, v187
	v_exp_f32_e32 v184, v184
	v_fma_f32 v186, -v216, v225, v195
	v_exp_f32_e32 v187, v160
	v_fma_f32 v160, -v215, v228, v188
	v_exp_f32_e32 v186, v186
	v_fma_f32 v188, -v216, v228, v196
	v_exp_f32_e32 v209, v160
	v_fma_f32 v160, -v215, v229, v189
	v_exp_f32_e32 v208, v188
	v_fma_f32 v188, -v216, v229, v197
	v_add_f32_e32 v192, 0, v164
	v_add_f32_e32 v193, 0, v165
	v_exp_f32_e32 v189, v160
	v_fma_f32 v160, -v215, v230, v190
	v_exp_f32_e32 v188, v188
	v_fma_f32 v190, -v216, v230, v198
	v_add_f32_e32 v192, v166, v192
	v_add_f32_e32 v193, v167, v193
	v_exp_f32_e32 v211, v160
	v_fma_f32 v160, -v215, v151, v191
	v_exp_f32_e32 v210, v190
	v_fma_f32 v190, -v216, v151, v199
	v_add_f32_e32 v192, v184, v192
	v_add_f32_e32 v193, v185, v193
	v_exp_f32_e32 v191, v160
	v_exp_f32_e32 v190, v190
	v_add_f32_e32 v192, v186, v192
	v_add_f32_e32 v193, v187, v193
	v_fma_f32 v152, -v218, v212, v152
	v_add_f32_e32 v192, v208, v192
	v_add_f32_e32 v193, v209, v193
	v_cvt_pk_bf16_f32 v164, v164, v166
	v_add_f32_e32 v192, v188, v192
	v_add_f32_e32 v193, v189, v193
	v_cvt_pk_bf16_f32 v166, v208, v188
	v_add_f32_e32 v192, v210, v192
	v_add_f32_e32 v193, v211, v193
	v_exp_f32_e32 v188, v152
	v_fma_f32 v152, -v218, v213, v153
	v_cvt_pk_bf16_f32 v160, v165, v167
	v_add_f32_e32 v192, v190, v192
	v_add_f32_e32 v193, v191, v193
	v_cvt_pk_bf16_f32 v165, v184, v186
	v_cvt_pk_bf16_f32 v167, v210, v190
	v_fma_f32 v184, -v217, v212, v200
	v_exp_f32_e32 v190, v152
	v_fma_f32 v152, -v218, v224, v154
	v_cvt_pk_bf16_f32 v162, v209, v189
	v_add_f32_e32 v122, v122, v192
	v_add_f32_e32 v123, v123, v193
	v_exp_f32_e32 v189, v184
	v_fma_f32 v184, -v217, v213, v201
	v_exp_f32_e32 v192, v152
	v_fma_f32 v152, -v218, v225, v155
	v_cvt_pk_bf16_f32 v163, v211, v191
	v_exp_f32_e32 v191, v184
	v_fma_f32 v184, -v217, v224, v202
	v_exp_f32_e32 v194, v152
	v_fma_f32 v152, -v218, v228, v156
	v_exp_f32_e32 v193, v184
	v_fma_f32 v184, -v217, v225, v203
	v_exp_f32_e32 v196, v152
	v_fma_f32 v152, -v218, v229, v157
	v_exp_f32_e32 v195, v184
	v_fma_f32 v184, -v217, v228, v204
	v_exp_f32_e32 v198, v152
	v_fma_f32 v152, -v218, v230, v158
	v_exp_f32_e32 v197, v184
	v_fma_f32 v184, -v217, v229, v205
	v_exp_f32_e32 v200, v152
	v_add_f32_e32 v152, 0, v188
	v_add_f32_e32 v153, 0, v189
	v_exp_f32_e32 v199, v184
	v_fma_f32 v184, -v217, v230, v206
	v_add_f32_e32 v152, v190, v152
	v_add_f32_e32 v153, v191, v153
	v_exp_f32_e32 v201, v184
	v_fma_f32 v184, -v217, v151, v207
	v_fma_f32 v151, -v218, v151, v159
	v_add_f32_e32 v152, v192, v152
	v_add_f32_e32 v153, v193, v153
	v_exp_f32_e32 v203, v184
	v_exp_f32_e32 v202, v151
	v_add_f32_e32 v152, v194, v152
	v_add_f32_e32 v153, v195, v153
	v_cvt_pk_bf16_f32 v161, v185, v187
	v_add_f32_e32 v152, v196, v152
	v_add_f32_e32 v153, v197, v153
	v_cvt_pk_bf16_f32 v184, v189, v191
	v_add_f32_e32 v152, v198, v152
	v_add_f32_e32 v153, v199, v153
	v_cvt_pk_bf16_f32 v185, v193, v195
	v_add_f32_e32 v152, v200, v152
	v_add_f32_e32 v153, v201, v153
	v_cvt_pk_bf16_f32 v186, v197, v199
	v_add_f32_e32 v152, v202, v152
	v_add_f32_e32 v153, v203, v153
	v_cvt_pk_bf16_f32 v187, v201, v203
	v_add_f32_e32 v120, v120, v152
	v_add_f32_e32 v121, v121, v153
	v_cvt_pk_bf16_f32 v152, v188, v190
	v_cvt_pk_bf16_f32 v153, v192, v194
	v_cvt_pk_bf16_f32 v154, v196, v198
	v_cvt_pk_bf16_f32 v155, v200, v202
	s_setprio 1
	s_waitcnt lgkmcnt(3)
	v_mfma_f32_16x16x32_bf16 v[94:97], v[168:171], v[160:163], v[94:97]
	s_waitcnt lgkmcnt(2)
	v_mfma_f32_16x16x32_bf16 v[90:93], v[172:175], v[160:163], v[90:93]
	s_waitcnt lgkmcnt(1)
	v_mfma_f32_16x16x32_bf16 v[86:89], v[176:179], v[160:163], v[86:89]
	s_waitcnt lgkmcnt(0)
	v_mfma_f32_16x16x32_bf16 v[82:85], v[180:183], v[160:163], v[82:85]
	v_mfma_f32_16x16x32_bf16 v[78:81], v[168:171], v[164:167], v[78:81]
	v_mfma_f32_16x16x32_bf16 v[74:77], v[172:175], v[164:167], v[74:77]
	v_mfma_f32_16x16x32_bf16 v[70:73], v[176:179], v[164:167], v[70:73]
	v_mfma_f32_16x16x32_bf16 v[66:69], v[180:183], v[164:167], v[66:69]
	v_mfma_f32_16x16x32_bf16 v[62:65], v[168:171], v[184:187], v[62:65]
	v_mfma_f32_16x16x32_bf16 v[58:61], v[172:175], v[184:187], v[58:61]
	v_mfma_f32_16x16x32_bf16 v[54:57], v[176:179], v[184:187], v[54:57]
	v_mfma_f32_16x16x32_bf16 v[50:53], v[180:183], v[184:187], v[50:53]
	v_mfma_f32_16x16x32_bf16 v[46:49], v[168:171], v[152:155], v[46:49]
	v_mfma_f32_16x16x32_bf16 v[42:45], v[172:175], v[152:155], v[42:45]
	v_mfma_f32_16x16x32_bf16 v[38:41], v[176:179], v[152:155], v[38:41]
	v_mfma_f32_16x16x32_bf16 v[34:37], v[180:183], v[152:155], v[34:37]
	s_setprio 0
	s_branch .LBB0_2705

.LBB0_2729:
	s_or_b32 s51, s52, s20
	s_lshl_b32 s53, s51, 4
	s_cmp_ge_i32 s53, s24
	s_cbranch_scc1 .LBB0_2728
	v_or_b32_e32 v57, s52, v226
	v_mad_u32_u24 v57, v57, s48, v46
	ds_read_b128 v[58:61], v57
	ds_read_b128 v[62:65], v57 offset:64
	ds_read_b128 v[66:69], v57 offset:2304
	ds_read_b128 v[70:73], v57 offset:2368
	v_subrev_u32_e32 v57, s51, v48
	v_lshl_add_u32 v57, v57, 4, v49
	v_cvt_f32_u32_e32 v74, v57
	v_xad_u32 v75, s51, -1, v48
	v_lshl_add_u32 v75, v75, 4, v49
	v_cvt_f32_u32_e32 v76, v75
	v_cmp_gt_u32_e32 vcc, 2.0, v57
	s_nop 1
	v_cndmask_b32_e32 v57, v56, v74, vcc
	v_subrev_u32_e32 v74, s51, v50
	v_cmp_gt_u32_e32 vcc, 2.0, v75
	v_lshl_add_u32 v74, v74, 4, v49
	v_cvt_f32_u32_e32 v75, v74
	v_cndmask_b32_e32 v98, v56, v76, vcc
	v_subrev_u32_e32 v76, s51, v51
	v_lshl_add_u32 v76, v76, 4, v49
	v_cvt_f32_u32_e32 v77, v76
	v_cmp_gt_u32_e32 vcc, 2.0, v74
	v_subrev_u32_e32 v74, s51, v52
	v_lshl_add_u32 v74, v74, 4, v49
	v_cndmask_b32_e32 v99, v56, v75, vcc
	v_cmp_gt_u32_e32 vcc, 2.0, v76
	v_cvt_f32_u32_e32 v75, v74
	v_subrev_u32_e32 v76, s51, v53
	v_lshl_add_u32 v76, v76, 4, v49
	v_cndmask_b32_e32 v100, v56, v77, vcc
	v_cvt_f32_u32_e32 v77, v76
	v_cmp_gt_u32_e32 vcc, 2.0, v74
	v_subrev_u32_e32 v74, s51, v54
	v_lshl_add_u32 v74, v74, 4, v49
	v_cndmask_b32_e32 v101, v56, v75, vcc
	v_cmp_gt_u32_e32 vcc, 2.0, v76
	v_subrev_u32_e32 v76, s51, v55
	v_cvt_f32_u32_e32 v75, v74
	v_lshl_add_u32 v76, v76, 4, v49
	v_cndmask_b32_e32 v102, v56, v77, vcc
	v_cvt_f32_u32_e32 v77, v76
	v_cmp_gt_u32_e32 vcc, 2.0, v74
	s_nop 1
	v_cndmask_b32_e32 v103, v56, v75, vcc
	v_cmp_gt_u32_e32 vcc, 2.0, v76
	s_nop 1
	v_cndmask_b32_e32 v104, v56, v77, vcc
	s_setprio 1
	s_waitcnt vmcnt(7) lgkmcnt(3)
	v_mfma_f32_16x16x32_bf16 v[74:77], v[58:61], v[2:5], 0
	s_waitcnt vmcnt(5)
	v_mfma_f32_16x16x32_bf16 v[82:85], v[58:61], v[10:13], 0
	s_waitcnt vmcnt(3)
	v_mfma_f32_16x16x32_bf16 v[90:93], v[58:61], v[18:21], 0
	s_waitcnt vmcnt(1)
	v_mfma_f32_16x16x32_bf16 v[58:61], v[58:61], v[26:29], 0
	s_waitcnt lgkmcnt(2)
	v_mfma_f32_16x16x32_bf16 v[74:77], v[62:65], v[6:9], v[74:77]
	s_waitcnt lgkmcnt(1)
	v_mfma_f32_16x16x32_bf16 v[78:81], v[66:69], v[2:5], 0
	v_mfma_f32_16x16x32_bf16 v[82:85], v[62:65], v[14:17], v[82:85]
	v_mfma_f32_16x16x32_bf16 v[86:89], v[66:69], v[10:13], 0
	v_mfma_f32_16x16x32_bf16 v[90:93], v[62:65], v[22:25], v[90:93]
	v_mfma_f32_16x16x32_bf16 v[94:97], v[66:69], v[18:21], 0
	s_waitcnt vmcnt(0)
	v_mfma_f32_16x16x32_bf16 v[58:61], v[62:65], v[30:33], v[58:61]
	v_mfma_f32_16x16x32_bf16 v[62:65], v[66:69], v[26:29], 0
	s_waitcnt lgkmcnt(0)
	v_mfma_f32_16x16x32_bf16 v[78:81], v[70:73], v[6:9], v[78:81]
	v_mfma_f32_16x16x32_bf16 v[86:89], v[70:73], v[14:17], v[86:89]
	v_mfma_f32_16x16x32_bf16 v[94:97], v[70:73], v[22:25], v[94:97]
	v_mfma_f32_16x16x32_bf16 v[62:65], v[70:73], v[30:33], v[62:65]
	s_setprio 0
	v_fma_f32 v66, -v215, v57, v74
	v_exp_f32_e32 v67, v66
	v_fma_f32 v66, -v215, v98, v75
	v_exp_f32_e32 v69, v66
	v_fma_f32 v66, -v215, v99, v76
	v_exp_f32_e32 v71, v66
	v_fma_f32 v66, -v215, v100, v77
	v_exp_f32_e32 v73, v66
	v_fma_f32 v66, -v215, v101, v78
	v_exp_f32_e32 v75, v66
	v_fma_f32 v66, -v215, v102, v79
	v_exp_f32_e32 v77, v66
	v_fma_f32 v66, -v215, v103, v80
	v_exp_f32_e32 v79, v66
	v_fma_f32 v66, -v215, v104, v81
	v_exp_f32_e32 v81, v66
	v_fma_f32 v66, -v216, v57, v82
	v_exp_f32_e32 v66, v66
	v_fma_f32 v68, -v216, v98, v83
	v_exp_f32_e32 v68, v68
	v_fma_f32 v70, -v216, v99, v84
	v_exp_f32_e32 v70, v70
	v_fma_f32 v72, -v216, v100, v85
	v_exp_f32_e32 v72, v72
	v_fma_f32 v74, -v216, v101, v86
	v_exp_f32_e32 v74, v74
	v_fma_f32 v76, -v216, v102, v87
	v_add_f32_e32 v66, 0, v66
	v_add_f32_e32 v67, 0, v67
	v_exp_f32_e32 v76, v76
	v_fma_f32 v78, -v216, v103, v88
	v_add_f32_e32 v66, v68, v66
	v_add_f32_e32 v67, v69, v67
	v_exp_f32_e32 v78, v78
	v_fma_f32 v80, -v216, v104, v89
	v_add_f32_e32 v66, v70, v66
	v_add_f32_e32 v67, v71, v67
	v_exp_f32_e32 v80, v80
	v_add_f32_e32 v66, v72, v66
	v_add_f32_e32 v67, v73, v67
	s_nop 0
	v_add_f32_e32 v66, v74, v66
	v_add_f32_e32 v67, v75, v67
	s_nop 0
	v_add_f32_e32 v66, v76, v66
	v_add_f32_e32 v67, v77, v67
	s_nop 0
	v_add_f32_e32 v66, v78, v66
	v_add_f32_e32 v67, v79, v67
	s_nop 0
	v_add_f32_e32 v66, v80, v66
	v_add_f32_e32 v67, v81, v67
	s_nop 0
	v_add_f32_e32 v44, v44, v66
	v_add_f32_e32 v45, v45, v67
	v_fma_f32 v66, -v217, v57, v90
	v_exp_f32_e32 v67, v66
	v_fma_f32 v66, -v217, v98, v91
	v_exp_f32_e32 v69, v66
	v_fma_f32 v66, -v217, v99, v92
	v_exp_f32_e32 v71, v66
	v_fma_f32 v66, -v217, v100, v93
	v_exp_f32_e32 v73, v66
	v_fma_f32 v66, -v217, v101, v94
	v_exp_f32_e32 v75, v66
	v_fma_f32 v66, -v217, v102, v95
	v_exp_f32_e32 v77, v66
	v_fma_f32 v66, -v217, v103, v96
	v_exp_f32_e32 v79, v66
	v_fma_f32 v66, -v217, v104, v97
	v_fma_f32 v57, -v218, v57, v58
	v_exp_f32_e32 v81, v66
	v_exp_f32_e32 v66, v57
	v_fma_f32 v57, -v218, v98, v59
	v_exp_f32_e32 v68, v57
	v_fma_f32 v57, -v218, v99, v60
	v_exp_f32_e32 v70, v57
	v_fma_f32 v57, -v218, v100, v61
	v_exp_f32_e32 v72, v57
	v_fma_f32 v57, -v218, v101, v62
	v_exp_f32_e32 v74, v57
	v_fma_f32 v57, -v218, v102, v63
	v_add_f32_e32 v58, 0, v66
	v_add_f32_e32 v59, 0, v67
	v_exp_f32_e32 v76, v57
	v_fma_f32 v57, -v218, v103, v64
	v_add_f32_e32 v58, v68, v58
	v_add_f32_e32 v59, v69, v59
	v_exp_f32_e32 v78, v57
	v_fma_f32 v57, -v218, v104, v65
	v_add_f32_e32 v58, v70, v58
	v_add_f32_e32 v59, v71, v59
	v_exp_f32_e32 v80, v57
	v_add_f32_e32 v58, v72, v58
	v_add_f32_e32 v59, v73, v59
	s_nop 0
	v_add_f32_e32 v58, v74, v58
	v_add_f32_e32 v59, v75, v59
	s_nop 0
	v_add_f32_e32 v58, v76, v58
	v_add_f32_e32 v59, v77, v59
	s_nop 0
	v_add_f32_e32 v58, v78, v58
	v_add_f32_e32 v59, v79, v59
	s_nop 0
	v_add_f32_e32 v58, v80, v58
	v_add_f32_e32 v59, v81, v59
	s_nop 0
	v_add_f32_e32 v42, v42, v58
	v_add_f32_e32 v43, v43, v59
	s_branch .LBB0_2728

.LBB0_2737:
	v_readlane_b32 s16, v254, 60
	s_and_b64 vcc, exec, s[18:19]
	s_waitcnt lgkmcnt(0)
	v_add_u32_e32 v1, s16, v131
	s_barrier
	s_cbranch_vccz .LBB0_2749
	v_add_f32_e32 v38, v40, v38
	v_add_f32_e32 v39, v41, v39
	v_add_f32_e32 v34, v36, v34
	v_add_f32_e32 v35, v37, v35
	v_div_scale_f32 v40, s[16:17], v39, v39, 1.0
	v_rcp_f32_e32 v41, v40
	v_div_scale_f32 v42, vcc, 1.0, v39, 1.0
	v_div_scale_f32 v36, s[18:19], v35, v35, 1.0
	v_fma_f32 v43, -v40, v41, 1.0
	v_fmac_f32_e32 v41, v43, v41
	v_mul_f32_e32 v43, v42, v41
	v_fma_f32 v44, -v40, v43, v42
	v_fmac_f32_e32 v43, v44, v41
	v_fma_f32 v40, -v40, v43, v42
	v_div_fmas_f32 v40, v40, v41, v43
	v_div_scale_f32 v41, s[16:17], v38, v38, 1.0
	v_rcp_f32_e32 v42, v41
	v_div_fixup_f32 v40, v40, v39, 1.0
	v_cmp_lt_f32_e32 vcc, 0, v39
	v_rcp_f32_e32 v37, v36
	v_fma_f32 v39, -v41, v42, 1.0
	v_cndmask_b32_e32 v150, 0, v40, vcc
	v_fmac_f32_e32 v42, v39, v42
	v_div_scale_f32 v39, vcc, 1.0, v38, 1.0
	v_mul_f32_e32 v40, v39, v42
	v_fma_f32 v43, -v41, v40, v39
	v_fmac_f32_e32 v40, v43, v42
	v_fma_f32 v39, -v41, v40, v39
	v_div_fmas_f32 v39, v39, v42, v40
	v_div_fixup_f32 v39, v39, v38, 1.0
	v_cmp_lt_f32_e32 vcc, 0, v38
	v_fma_f32 v38, -v36, v37, 1.0
	v_fmac_f32_e32 v37, v38, v37
	v_cndmask_b32_e32 v152, 0, v39, vcc
	v_div_scale_f32 v38, vcc, 1.0, v35, 1.0
	v_mul_f32_e32 v39, v38, v37
	v_fma_f32 v40, -v36, v39, v38
	v_fmac_f32_e32 v39, v40, v37
	v_fma_f32 v36, -v36, v39, v38
	v_div_fmas_f32 v36, v36, v37, v39
	v_div_scale_f32 v37, s[18:19], v34, v34, 1.0
	v_rcp_f32_e32 v38, v37
	v_div_fixup_f32 v36, v36, v35, 1.0
	v_cmp_lt_f32_e32 vcc, 0, v35
	v_mov_b32_e32 v99, 0
	v_fma_f32 v35, -v37, v38, 1.0
	v_cndmask_b32_e32 v154, 0, v36, vcc
	v_fmac_f32_e32 v38, v35, v38
	v_div_scale_f32 v35, vcc, 1.0, v34, 1.0
	v_mul_f32_e32 v36, v35, v38
	v_fma_f32 v39, -v37, v36, v35
	v_fmac_f32_e32 v36, v39, v38
	v_fma_f32 v35, -v37, v36, v35
	v_div_fmas_f32 v35, v35, v38, v36
	v_div_fixup_f32 v35, v35, v34, 1.0
	v_cmp_lt_f32_e32 vcc, 0, v34
	s_mov_b32 s16, 0xffffff8
	v_mov_b32_e32 v98, v99
	v_cndmask_b32_e32 v156, 0, v35, vcc
	v_mul_u32_u24_e32 v125, 0x210, v226
	v_mul_lo_u32 v162, v160, s16
	v_mov_b32_e32 v100, v99
	v_mov_b32_e32 v101, v99
	v_mov_b64_e32 v[66:67], v[98:99]
	v_mov_b64_e32 v[70:71], v[98:99]
	v_mov_b64_e32 v[74:75], v[98:99]
	v_mov_b64_e32 v[78:79], v[98:99]
	v_mov_b64_e32 v[82:83], v[98:99]
	v_mov_b64_e32 v[86:87], v[98:99]
	v_mov_b64_e32 v[90:91], v[98:99]
	v_mov_b64_e32 v[94:95], v[98:99]
	v_mov_b64_e32 v[62:63], v[98:99]
	v_mov_b64_e32 v[58:59], v[98:99]
	v_mov_b64_e32 v[54:55], v[98:99]
	v_mov_b64_e32 v[50:51], v[98:99]
	v_mov_b64_e32 v[46:47], v[98:99]
	v_mov_b64_e32 v[42:43], v[98:99]
	v_mov_b64_e32 v[38:39], v[98:99]
	v_mov_b64_e32 v[34:35], v[98:99]
	s_mov_b32 s17, 0
	s_movk_i32 s48, 0x90
	v_mul_u32_u24_e32 v161, 0x90, v226
	v_subrev_u32_e32 v163, 31, v227
	v_add_u32_e32 v164, 0xffffffe, v162
	v_add_u32_e32 v165, 0xffffffd, v162
	v_add_u32_e32 v166, 0xffffffc, v162
	v_add_u32_e32 v167, 0xffffffb, v162
	v_add_u32_e32 v168, 0xffffffa, v162
	v_add_u32_e32 v169, 0xffffff9, v162
	v_add3_u32 v170, v1, v125, v144
	v_mov_b32_e32 v157, v156
	v_mov_b32_e32 v155, v154
	v_mov_b32_e32 v153, v152
	v_mov_b32_e32 v151, v150
	v_add_u32_e32 v171, v145, v230
	v_mov_b32_e32 v172, 0x49742400
	v_mov_b64_e32 v[68:69], v[100:101]
	v_mov_b64_e32 v[72:73], v[100:101]
	v_mov_b64_e32 v[76:77], v[100:101]
	v_mov_b64_e32 v[80:81], v[100:101]
	v_mov_b64_e32 v[84:85], v[100:101]
	v_mov_b64_e32 v[88:89], v[100:101]
	v_mov_b64_e32 v[92:93], v[100:101]
	v_mov_b64_e32 v[96:97], v[100:101]
	v_mov_b64_e32 v[64:65], v[100:101]
	v_mov_b64_e32 v[60:61], v[100:101]
	v_mov_b64_e32 v[56:57], v[100:101]
	v_mov_b64_e32 v[52:53], v[100:101]
	v_mov_b64_e32 v[48:49], v[100:101]
	v_mov_b64_e32 v[44:45], v[100:101]
	v_mov_b64_e32 v[40:41], v[100:101]
	v_mov_b64_e32 v[36:37], v[100:101]
	s_mov_b32 s49, 0

.LBB0_2903:
	s_lshl_b32 s21, s20, 5
	v_or_b32_e32 v151, s21, v226
	v_mad_u32_u24 v151, v151, s46, v148
	ds_read_b128 v[152:155], v151
	ds_read_b128 v[156:159], v151 offset:64
	ds_read_b128 v[160:163], v151 offset:2304
	ds_read_b128 v[164:167], v151 offset:2368
	v_lshl_add_u32 v151, s20, 6, v149
	ds_read_b128 v[168:171], v151 offset:9216
	ds_read_b128 v[172:175], v151 offset:11520
	ds_read_b128 v[176:179], v151 offset:13824
	ds_read_b128 v[182:185], v151 offset:16128
	v_add_u32_e32 v151, s21, v150
	v_sub_u32_e32 v180, v227, v151
	v_cmp_gt_u32_e32 vcc, 2.0, v180
	v_cvt_f32_i32_e32 v180, v180
	v_xad_u32 v186, v151, -1, v227
	v_cvt_f32_i32_e32 v187, v186
	s_and_b64 vcc, s[16:17], vcc
	v_cndmask_b32_e32 v180, v236, v180, vcc
	v_cmp_gt_u32_e32 vcc, 2.0, v186
	v_or_b32_e32 v186, 2, v151
	s_and_b64 vcc, s[16:17], vcc
	v_sub_u32_e32 v186, v227, v186
	v_cndmask_b32_e32 v237, v236, v187, vcc
	v_cmp_gt_u32_e32 vcc, 2.0, v186
	v_cvt_f32_i32_e32 v186, v186
	v_or_b32_e32 v187, 3, v151
	v_sub_u32_e32 v187, v227, v187
	v_cvt_f32_i32_e32 v188, v187
	s_and_b64 vcc, s[16:17], vcc
	v_cndmask_b32_e32 v238, v236, v186, vcc
	v_cmp_gt_u32_e32 vcc, 2.0, v187
	v_or_b32_e32 v186, 4, v151
	s_and_b64 vcc, s[16:17], vcc
	v_sub_u32_e32 v186, v227, v186
	v_cndmask_b32_e32 v239, v236, v188, vcc
	v_cmp_gt_u32_e32 vcc, 2.0, v186
	v_cvt_f32_i32_e32 v186, v186
	v_or_b32_e32 v187, 5, v151
	v_sub_u32_e32 v187, v227, v187
	v_cvt_f32_i32_e32 v188, v187
	s_and_b64 vcc, s[16:17], vcc
	v_cndmask_b32_e32 v240, v236, v186, vcc
	v_cmp_gt_u32_e32 vcc, 2.0, v187
	v_or_b32_e32 v186, 6, v151
	s_and_b64 vcc, s[16:17], vcc
	v_sub_u32_e32 v186, v227, v186
	v_cndmask_b32_e32 v241, v236, v188, vcc
	v_cmp_gt_u32_e32 vcc, 2.0, v186
	v_cvt_f32_i32_e32 v186, v186
	v_or_b32_e32 v151, 7, v151
	v_sub_u32_e32 v151, v227, v151
	v_cvt_f32_i32_e32 v187, v151
	s_and_b64 vcc, s[16:17], vcc
	v_cndmask_b32_e32 v242, v236, v186, vcc
	v_cmp_gt_u32_e32 vcc, 2.0, v151
	s_and_b64 vcc, s[16:17], vcc
	s_nop 0
	v_cndmask_b32_e32 v151, v236, v187, vcc
	s_setprio 1
	s_waitcnt lgkmcnt(7)
	v_mfma_f32_16x16x32_bf16 v[186:189], v[152:155], v[2:5], 0
	v_mfma_f32_16x16x32_bf16 v[194:197], v[152:155], v[10:13], 0
	v_mfma_f32_16x16x32_bf16 v[202:205], v[152:155], v[18:21], 0
	v_mfma_f32_16x16x32_bf16 v[152:155], v[152:155], v[26:29], 0
	s_waitcnt lgkmcnt(6)
	v_mfma_f32_16x16x32_bf16 v[186:189], v[156:159], v[6:9], v[186:189]
	s_waitcnt lgkmcnt(5)
	v_mfma_f32_16x16x32_bf16 v[190:193], v[160:163], v[2:5], 0
	v_mfma_f32_16x16x32_bf16 v[194:197], v[156:159], v[14:17], v[194:197]
	v_mfma_f32_16x16x32_bf16 v[198:201], v[160:163], v[10:13], 0
	v_mfma_f32_16x16x32_bf16 v[202:205], v[156:159], v[22:25], v[202:205]
	v_mfma_f32_16x16x32_bf16 v[206:209], v[160:163], v[18:21], 0
	v_mfma_f32_16x16x32_bf16 v[152:155], v[156:159], v[30:33], v[152:155]
	v_mfma_f32_16x16x32_bf16 v[156:159], v[160:163], v[26:29], 0
	s_waitcnt lgkmcnt(4)
	v_mfma_f32_16x16x32_bf16 v[190:193], v[164:167], v[6:9], v[190:193]
	v_mfma_f32_16x16x32_bf16 v[198:201], v[164:167], v[14:17], v[198:201]
	v_mfma_f32_16x16x32_bf16 v[206:209], v[164:167], v[22:25], v[206:209]
	v_mfma_f32_16x16x32_bf16 v[156:159], v[164:167], v[30:33], v[156:159]
	s_setprio 0
	v_fma_f32 v160, -v215, v180, v186
	v_fma_f32 v164, -v216, v180, v194
	v_exp_f32_e32 v165, v160
	v_fma_f32 v160, -v215, v237, v187
	v_exp_f32_e32 v164, v164
	v_fma_f32 v166, -v216, v237, v195
	v_exp_f32_e32 v167, v160
	v_fma_f32 v160, -v215, v238, v188
	v_exp_f32_e32 v166, v166
	v_fma_f32 v186, -v216, v238, v196
	v_exp_f32_e32 v187, v160
	v_fma_f32 v160, -v215, v239, v189
	v_exp_f32_e32 v186, v186
	v_fma_f32 v188, -v216, v239, v197
	v_exp_f32_e32 v189, v160
	v_fma_f32 v160, -v215, v240, v190
	v_exp_f32_e32 v188, v188
	v_fma_f32 v190, -v216, v240, v198
	v_exp_f32_e32 v211, v160
	v_fma_f32 v160, -v215, v241, v191
	v_exp_f32_e32 v210, v190
	v_fma_f32 v190, -v216, v241, v199
	v_add_f32_e32 v194, 0, v164
	v_add_f32_e32 v195, 0, v165
	v_exp_f32_e32 v191, v160
	v_fma_f32 v160, -v215, v242, v192
	v_exp_f32_e32 v190, v190
	v_fma_f32 v192, -v216, v242, v200
	v_add_f32_e32 v194, v166, v194
	v_add_f32_e32 v195, v167, v195
	v_exp_f32_e32 v213, v160
	v_fma_f32 v160, -v215, v151, v193
	v_exp_f32_e32 v212, v192
	v_fma_f32 v192, -v216, v151, v201
	v_add_f32_e32 v194, v186, v194
	v_add_f32_e32 v195, v187, v195
	v_exp_f32_e32 v193, v160
	v_exp_f32_e32 v192, v192
	v_add_f32_e32 v194, v188, v194
	v_add_f32_e32 v195, v189, v195
	v_fma_f32 v152, -v218, v180, v152
	v_add_f32_e32 v194, v210, v194
	v_add_f32_e32 v195, v211, v195
	v_cvt_pk_bf16_f32 v164, v164, v166
	v_add_f32_e32 v194, v190, v194
	v_add_f32_e32 v195, v191, v195
	v_cvt_pk_bf16_f32 v166, v210, v190
	v_add_f32_e32 v194, v212, v194
	v_add_f32_e32 v195, v213, v195
	v_exp_f32_e32 v190, v152
	v_fma_f32 v152, -v218, v237, v153
	v_cvt_pk_bf16_f32 v160, v165, v167
	v_add_f32_e32 v194, v192, v194
	v_add_f32_e32 v195, v193, v195
	v_cvt_pk_bf16_f32 v165, v186, v188
	v_cvt_pk_bf16_f32 v167, v212, v192
	v_fma_f32 v186, -v217, v180, v202
	v_exp_f32_e32 v192, v152
	v_fma_f32 v152, -v218, v238, v154
	v_cvt_pk_bf16_f32 v162, v211, v191
	v_add_f32_e32 v122, v122, v194
	v_add_f32_e32 v123, v123, v195
	v_exp_f32_e32 v191, v186
	v_fma_f32 v186, -v217, v237, v203
	v_exp_f32_e32 v194, v152
	v_fma_f32 v152, -v218, v239, v155
	v_cvt_pk_bf16_f32 v163, v213, v193
	v_exp_f32_e32 v193, v186
	v_fma_f32 v186, -v217, v238, v204
	v_exp_f32_e32 v196, v152
	v_fma_f32 v152, -v218, v240, v156
	v_exp_f32_e32 v195, v186
	v_fma_f32 v186, -v217, v239, v205
	v_exp_f32_e32 v198, v152
	v_fma_f32 v152, -v218, v241, v157
	v_exp_f32_e32 v197, v186
	v_fma_f32 v186, -v217, v240, v206
	v_exp_f32_e32 v200, v152
	v_fma_f32 v152, -v218, v242, v158
	v_exp_f32_e32 v199, v186
	v_fma_f32 v186, -v217, v241, v207
	v_exp_f32_e32 v202, v152
	v_add_f32_e32 v152, 0, v190
	v_add_f32_e32 v153, 0, v191
	v_exp_f32_e32 v201, v186
	v_fma_f32 v186, -v217, v242, v208
	v_add_f32_e32 v152, v192, v152
	v_add_f32_e32 v153, v193, v153
	v_exp_f32_e32 v203, v186
	v_fma_f32 v186, -v217, v151, v209
	v_fma_f32 v151, -v218, v151, v159
	v_add_f32_e32 v152, v194, v152
	v_add_f32_e32 v153, v195, v153
	v_exp_f32_e32 v205, v186
	v_exp_f32_e32 v204, v151
	v_add_f32_e32 v152, v196, v152
	v_add_f32_e32 v153, v197, v153
	v_cvt_pk_bf16_f32 v161, v187, v189
	v_add_f32_e32 v152, v198, v152
	v_add_f32_e32 v153, v199, v153
	v_cvt_pk_bf16_f32 v186, v191, v193
	v_add_f32_e32 v152, v200, v152
	v_add_f32_e32 v153, v201, v153
	v_cvt_pk_bf16_f32 v187, v195, v197
	v_add_f32_e32 v152, v202, v152
	v_add_f32_e32 v153, v203, v153
	v_cvt_pk_bf16_f32 v188, v199, v201
	v_add_f32_e32 v152, v204, v152
	v_add_f32_e32 v153, v205, v153
	v_cvt_pk_bf16_f32 v189, v203, v205
	v_add_f32_e32 v120, v120, v152
	v_add_f32_e32 v121, v121, v153
	v_cvt_pk_bf16_f32 v152, v190, v192
	v_cvt_pk_bf16_f32 v153, v194, v196
	v_cvt_pk_bf16_f32 v154, v198, v200
	v_cvt_pk_bf16_f32 v155, v202, v204
	s_setprio 1
	s_waitcnt lgkmcnt(3)
	v_mfma_f32_16x16x32_bf16 v[34:37], v[168:171], v[160:163], v[34:37]
	s_waitcnt lgkmcnt(2)
	v_mfma_f32_16x16x32_bf16 v[38:41], v[172:175], v[160:163], v[38:41]
	s_waitcnt lgkmcnt(1)
	v_mfma_f32_16x16x32_bf16 v[42:45], v[176:179], v[160:163], v[42:45]
	s_waitcnt lgkmcnt(0)
	v_mfma_f32_16x16x32_bf16 v[46:49], v[182:185], v[160:163], v[46:49]
	v_mfma_f32_16x16x32_bf16 v[50:53], v[168:171], v[164:167], v[50:53]
	v_mfma_f32_16x16x32_bf16 v[54:57], v[172:175], v[164:167], v[54:57]
	v_mfma_f32_16x16x32_bf16 v[58:61], v[176:179], v[164:167], v[58:61]
	v_mfma_f32_16x16x32_bf16 v[62:65], v[182:185], v[164:167], v[62:65]
	v_mfma_f32_16x16x32_bf16 v[66:69], v[168:171], v[186:189], v[66:69]
	v_mfma_f32_16x16x32_bf16 v[70:73], v[172:175], v[186:189], v[70:73]
	v_mfma_f32_16x16x32_bf16 v[74:77], v[176:179], v[186:189], v[74:77]
	v_mfma_f32_16x16x32_bf16 v[78:81], v[182:185], v[186:189], v[78:81]
	v_mfma_f32_16x16x32_bf16 v[82:85], v[168:171], v[152:155], v[82:85]
	v_mfma_f32_16x16x32_bf16 v[86:89], v[172:175], v[152:155], v[86:89]
	v_mfma_f32_16x16x32_bf16 v[90:93], v[176:179], v[152:155], v[90:93]
	v_mfma_f32_16x16x32_bf16 v[94:97], v[182:185], v[152:155], v[94:97]
	s_setprio 0
	s_mov_b32 s20, 1
	s_and_b64 vcc, exec, s[18:19]
	s_mov_b64 s[18:19], 0
	s_cbranch_vccnz .LBB0_2903

.LBB0_2920:
	s_lshl_b32 s49, s47, 5
	s_or_b32 s48, s49, s16
	s_cmp_gt_i32 s48, s41
	s_cselect_b64 s[50:51], -1, 0
	s_or_b32 s52, s48, 31
	s_cmp_lt_i32 s52, s24
	s_cselect_b64 s[52:53], -1, 0
	s_or_b64 s[50:51], s[50:51], s[52:53]
	s_and_b64 vcc, exec, s[50:51]
	s_cbranch_vccnz .LBB0_2919
	v_add_u32_e32 v184, s48, v144
	v_sub_u32_e32 v185, v227, v184
	v_cvt_f32_i32_e32 v186, v185
	v_xad_u32 v187, v184, -1, v227
	v_cvt_f32_i32_e32 v188, v187
	v_cmp_gt_u32_e32 vcc, s45, v185
	v_or_b32_e32 v185, 2, v184
	v_sub_u32_e32 v185, v227, v185
	v_cndmask_b32_e32 v212, v150, v186, vcc
	v_cmp_gt_u32_e32 vcc, s45, v187
	v_cvt_f32_i32_e32 v186, v185
	v_or_b32_e32 v187, 3, v184
	v_sub_u32_e32 v187, v227, v187
	v_cndmask_b32_e32 v213, v150, v188, vcc
	v_cvt_f32_i32_e32 v188, v187
	v_cmp_gt_u32_e32 vcc, s45, v185
	v_or_b32_e32 v185, 4, v184
	v_sub_u32_e32 v185, v227, v185
	v_or_b32_e32 v152, s49, v226
	v_cndmask_b32_e32 v228, v150, v186, vcc
	v_cvt_f32_i32_e32 v186, v185
	v_mad_u32_u24 v164, v152, s43, v148
	v_lshl_add_u32 v180, s47, 6, v151
	v_cmp_gt_u32_e32 vcc, s45, v187
	v_or_b32_e32 v187, 5, v184
	ds_read_b128 v[152:155], v164
	ds_read_b128 v[156:159], v164 offset:64
	ds_read_b128 v[160:163], v164 offset:2304
	ds_read_b128 v[164:167], v164 offset:2368
	ds_read_b128 v[168:171], v180 offset:9216
	ds_read_b128 v[172:175], v180 offset:11520
	ds_read_b128 v[176:179], v180 offset:13824
	ds_read_b128 v[180:183], v180 offset:16128
	v_cndmask_b32_e32 v229, v150, v188, vcc
	v_sub_u32_e32 v187, v227, v187
	v_cmp_gt_u32_e32 vcc, s45, v185
	v_or_b32_e32 v185, 6, v184
	v_cvt_f32_i32_e32 v188, v187
	v_sub_u32_e32 v185, v227, v185
	v_or_b32_e32 v184, 7, v184
	v_cndmask_b32_e32 v230, v150, v186, vcc
	v_cvt_f32_i32_e32 v186, v185
	v_sub_u32_e32 v184, v227, v184
	v_cmp_gt_u32_e32 vcc, s45, v187
	v_cvt_f32_i32_e32 v187, v184
	s_nop 0
	v_cndmask_b32_e32 v231, v150, v188, vcc
	v_cmp_gt_u32_e32 vcc, s45, v185
	s_nop 1
	v_cndmask_b32_e32 v232, v150, v186, vcc
	v_cmp_gt_u32_e32 vcc, s45, v184
	s_nop 1
	v_cndmask_b32_e32 v233, v150, v187, vcc
	s_setprio 1
	s_waitcnt lgkmcnt(7)
	v_mfma_f32_16x16x32_bf16 v[184:187], v[152:155], v[2:5], 0
	v_mfma_f32_16x16x32_bf16 v[192:195], v[152:155], v[10:13], 0
	v_mfma_f32_16x16x32_bf16 v[200:203], v[152:155], v[18:21], 0
	v_mfma_f32_16x16x32_bf16 v[152:155], v[152:155], v[26:29], 0
	s_waitcnt lgkmcnt(6)
	v_mfma_f32_16x16x32_bf16 v[184:187], v[156:159], v[6:9], v[184:187]
	s_waitcnt lgkmcnt(5)
	v_mfma_f32_16x16x32_bf16 v[188:191], v[160:163], v[2:5], 0
	v_mfma_f32_16x16x32_bf16 v[192:195], v[156:159], v[14:17], v[192:195]
	v_mfma_f32_16x16x32_bf16 v[196:199], v[160:163], v[10:13], 0
	v_mfma_f32_16x16x32_bf16 v[200:203], v[156:159], v[22:25], v[200:203]
	v_mfma_f32_16x16x32_bf16 v[204:207], v[160:163], v[18:21], 0
	v_mfma_f32_16x16x32_bf16 v[152:155], v[156:159], v[30:33], v[152:155]
	v_mfma_f32_16x16x32_bf16 v[156:159], v[160:163], v[26:29], 0
	s_waitcnt lgkmcnt(4)
	v_mfma_f32_16x16x32_bf16 v[188:191], v[164:167], v[6:9], v[188:191]
	v_mfma_f32_16x16x32_bf16 v[196:199], v[164:167], v[14:17], v[196:199]
	v_mfma_f32_16x16x32_bf16 v[204:207], v[164:167], v[22:25], v[204:207]
	v_mfma_f32_16x16x32_bf16 v[156:159], v[164:167], v[30:33], v[156:159]
	s_setprio 0
	v_fma_f32 v160, -v215, v212, v184
	v_fma_f32 v164, -v216, v212, v192
	v_exp_f32_e32 v165, v160
	v_fma_f32 v160, -v215, v213, v185
	v_exp_f32_e32 v164, v164
	v_fma_f32 v166, -v216, v213, v193
	v_exp_f32_e32 v167, v160
	v_fma_f32 v160, -v215, v228, v186
	v_exp_f32_e32 v166, v166
	v_fma_f32 v184, -v216, v228, v194
	v_exp_f32_e32 v185, v160
	v_fma_f32 v160, -v215, v229, v187
	v_exp_f32_e32 v184, v184
	v_fma_f32 v186, -v216, v229, v195
	v_exp_f32_e32 v187, v160
	v_fma_f32 v160, -v215, v230, v188
	v_exp_f32_e32 v186, v186
	v_fma_f32 v188, -v216, v230, v196
	v_exp_f32_e32 v209, v160
	v_fma_f32 v160, -v215, v231, v189
	v_exp_f32_e32 v208, v188
	v_fma_f32 v188, -v216, v231, v197
	v_add_f32_e32 v192, 0, v164
	v_add_f32_e32 v193, 0, v165
	v_exp_f32_e32 v189, v160
	v_fma_f32 v160, -v215, v232, v190
	v_exp_f32_e32 v188, v188
	v_fma_f32 v190, -v216, v232, v198
	v_add_f32_e32 v192, v166, v192
	v_add_f32_e32 v193, v167, v193
	v_exp_f32_e32 v211, v160
	v_fma_f32 v160, -v215, v233, v191
	v_exp_f32_e32 v210, v190
	v_fma_f32 v190, -v216, v233, v199
	v_add_f32_e32 v192, v184, v192
	v_add_f32_e32 v193, v185, v193
	v_exp_f32_e32 v191, v160
	v_exp_f32_e32 v190, v190
	v_add_f32_e32 v192, v186, v192
	v_add_f32_e32 v193, v187, v193
	v_fma_f32 v152, -v218, v212, v152
	v_add_f32_e32 v192, v208, v192
	v_add_f32_e32 v193, v209, v193
	v_cvt_pk_bf16_f32 v164, v164, v166
	v_add_f32_e32 v192, v188, v192
	v_add_f32_e32 v193, v189, v193
	v_cvt_pk_bf16_f32 v166, v208, v188
	v_add_f32_e32 v192, v210, v192
	v_add_f32_e32 v193, v211, v193
	v_exp_f32_e32 v188, v152
	v_fma_f32 v152, -v218, v213, v153
	v_cvt_pk_bf16_f32 v160, v165, v167
	v_add_f32_e32 v192, v190, v192
	v_add_f32_e32 v193, v191, v193
	v_cvt_pk_bf16_f32 v167, v210, v190
	v_exp_f32_e32 v190, v152
	v_fma_f32 v152, -v218, v228, v154
	v_add_f32_e32 v122, v122, v192
	v_add_f32_e32 v123, v123, v193
	v_cvt_pk_bf16_f32 v165, v184, v186
	v_fma_f32 v184, -v217, v212, v200
	v_exp_f32_e32 v192, v152
	v_fma_f32 v152, -v218, v229, v155
	v_cvt_pk_bf16_f32 v162, v209, v189
	v_exp_f32_e32 v189, v184
	v_fma_f32 v184, -v217, v213, v201
	v_exp_f32_e32 v194, v152
	v_fma_f32 v152, -v218, v230, v156
	v_cvt_pk_bf16_f32 v163, v211, v191
	v_exp_f32_e32 v191, v184
	v_fma_f32 v184, -v217, v228, v202
	v_exp_f32_e32 v196, v152
	v_fma_f32 v152, -v218, v231, v157
	v_exp_f32_e32 v193, v184
	v_fma_f32 v184, -v217, v229, v203
	v_exp_f32_e32 v198, v152
	v_fma_f32 v152, -v218, v232, v158
	v_exp_f32_e32 v195, v184
	v_fma_f32 v184, -v217, v230, v204
	v_exp_f32_e32 v200, v152
	v_fma_f32 v152, -v218, v233, v159
	v_exp_f32_e32 v197, v184
	v_fma_f32 v184, -v217, v231, v205
	v_exp_f32_e32 v202, v152
	v_add_f32_e32 v152, 0, v188
	v_add_f32_e32 v153, 0, v189
	v_exp_f32_e32 v199, v184
	v_fma_f32 v184, -v217, v232, v206
	v_add_f32_e32 v152, v190, v152
	v_add_f32_e32 v153, v191, v153
	v_exp_f32_e32 v201, v184
	v_fma_f32 v184, -v217, v233, v207
	v_add_f32_e32 v152, v192, v152
	v_add_f32_e32 v153, v193, v153
	v_exp_f32_e32 v203, v184
	v_add_f32_e32 v152, v194, v152
	v_add_f32_e32 v153, v195, v153
	v_cvt_pk_bf16_f32 v161, v185, v187
	v_add_f32_e32 v152, v196, v152
	v_add_f32_e32 v153, v197, v153
	v_cvt_pk_bf16_f32 v184, v189, v191
	v_add_f32_e32 v152, v198, v152
	v_add_f32_e32 v153, v199, v153
	v_cvt_pk_bf16_f32 v185, v193, v195
	v_add_f32_e32 v152, v200, v152
	v_add_f32_e32 v153, v201, v153
	v_cvt_pk_bf16_f32 v186, v197, v199
	v_add_f32_e32 v152, v202, v152
	v_add_f32_e32 v153, v203, v153
	v_cvt_pk_bf16_f32 v187, v201, v203
	v_add_f32_e32 v120, v120, v152
	v_add_f32_e32 v121, v121, v153
	v_cvt_pk_bf16_f32 v152, v188, v190
	v_cvt_pk_bf16_f32 v153, v192, v194
	v_cvt_pk_bf16_f32 v154, v196, v198
	v_cvt_pk_bf16_f32 v155, v200, v202
	s_setprio 1
	s_waitcnt lgkmcnt(3)
	v_mfma_f32_16x16x32_bf16 v[94:97], v[168:171], v[160:163], v[94:97]
	s_waitcnt lgkmcnt(2)
	v_mfma_f32_16x16x32_bf16 v[90:93], v[172:175], v[160:163], v[90:93]
	s_waitcnt lgkmcnt(1)
	v_mfma_f32_16x16x32_bf16 v[86:89], v[176:179], v[160:163], v[86:89]
	s_waitcnt lgkmcnt(0)
	v_mfma_f32_16x16x32_bf16 v[82:85], v[180:183], v[160:163], v[82:85]
	v_mfma_f32_16x16x32_bf16 v[78:81], v[168:171], v[164:167], v[78:81]
	v_mfma_f32_16x16x32_bf16 v[74:77], v[172:175], v[164:167], v[74:77]
	v_mfma_f32_16x16x32_bf16 v[70:73], v[176:179], v[164:167], v[70:73]
	v_mfma_f32_16x16x32_bf16 v[66:69], v[180:183], v[164:167], v[66:69]
	v_mfma_f32_16x16x32_bf16 v[62:65], v[168:171], v[184:187], v[62:65]
	v_mfma_f32_16x16x32_bf16 v[58:61], v[172:175], v[184:187], v[58:61]
	v_mfma_f32_16x16x32_bf16 v[54:57], v[176:179], v[184:187], v[54:57]
	v_mfma_f32_16x16x32_bf16 v[50:53], v[180:183], v[184:187], v[50:53]
	v_mfma_f32_16x16x32_bf16 v[46:49], v[168:171], v[152:155], v[46:49]
	v_mfma_f32_16x16x32_bf16 v[42:45], v[172:175], v[152:155], v[42:45]
	v_mfma_f32_16x16x32_bf16 v[38:41], v[176:179], v[152:155], v[38:41]
	v_mfma_f32_16x16x32_bf16 v[34:37], v[180:183], v[152:155], v[34:37]
	s_setprio 0
	s_branch .LBB0_2919

.LBB0_2938:
	s_or_b32 s41, s42, s14
	s_lshl_b32 s43, s41, 4
	s_cmp_ge_i32 s43, s3
	s_cbranch_scc1 .LBB0_2937
	v_or_b32_e32 v49, s42, v208
	v_mad_u32_u24 v49, v49, s20, v44
	ds_read_b128 v[50:53], v49
	ds_read_b128 v[54:57], v49 offset:64
	ds_read_b128 v[58:61], v49 offset:2304
	ds_read_b128 v[62:65], v49 offset:2368
	v_subrev_u32_e32 v49, s41, v1
	v_lshl_add_u32 v49, v49, 4, v160
	v_cvt_f32_u32_e32 v66, v49
	v_xad_u32 v67, s41, -1, v1
	v_lshl_add_u32 v67, v67, 4, v160
	v_cvt_f32_u32_e32 v68, v67
	v_cmp_gt_u32_e32 vcc, 2.0, v49
	s_nop 1
	v_cndmask_b32_e32 v49, v48, v66, vcc
	v_subrev_u32_e32 v66, s41, v161
	v_cmp_gt_u32_e32 vcc, 2.0, v67
	v_lshl_add_u32 v66, v66, 4, v160
	v_cvt_f32_u32_e32 v67, v66
	v_cndmask_b32_e32 v90, v48, v68, vcc
	v_subrev_u32_e32 v68, s41, v162
	v_lshl_add_u32 v68, v68, 4, v160
	v_cvt_f32_u32_e32 v69, v68
	v_cmp_gt_u32_e32 vcc, 2.0, v66
	v_subrev_u32_e32 v66, s41, v163
	v_lshl_add_u32 v66, v66, 4, v160
	v_cndmask_b32_e32 v91, v48, v67, vcc
	v_cmp_gt_u32_e32 vcc, 2.0, v68
	v_cvt_f32_u32_e32 v67, v66
	v_subrev_u32_e32 v68, s41, v164
	v_lshl_add_u32 v68, v68, 4, v160
	v_cndmask_b32_e32 v92, v48, v69, vcc
	v_cvt_f32_u32_e32 v69, v68
	v_cmp_gt_u32_e32 vcc, 2.0, v66
	v_subrev_u32_e32 v66, s41, v165
	v_lshl_add_u32 v66, v66, 4, v160
	v_cndmask_b32_e32 v93, v48, v67, vcc
	v_cmp_gt_u32_e32 vcc, 2.0, v68
	v_subrev_u32_e32 v68, s41, v166
	v_cvt_f32_u32_e32 v67, v66
	v_lshl_add_u32 v68, v68, 4, v160
	v_cndmask_b32_e32 v94, v48, v69, vcc
	v_cvt_f32_u32_e32 v69, v68
	v_cmp_gt_u32_e32 vcc, 2.0, v66
	s_nop 1
	v_cndmask_b32_e32 v95, v48, v67, vcc
	v_cmp_gt_u32_e32 vcc, 2.0, v68
	s_nop 1
	v_cndmask_b32_e32 v96, v48, v69, vcc
	s_setprio 1
	s_waitcnt lgkmcnt(3)
	v_mfma_f32_16x16x32_bf16 v[66:69], v[50:53], v[2:5], 0
	v_mfma_f32_16x16x32_bf16 v[74:77], v[50:53], v[10:13], 0
	v_mfma_f32_16x16x32_bf16 v[82:85], v[50:53], v[18:21], 0
	v_mfma_f32_16x16x32_bf16 v[50:53], v[50:53], v[26:29], 0
	s_waitcnt lgkmcnt(2)
	v_mfma_f32_16x16x32_bf16 v[66:69], v[54:57], v[6:9], v[66:69]
	s_waitcnt lgkmcnt(1)
	v_mfma_f32_16x16x32_bf16 v[70:73], v[58:61], v[2:5], 0
	v_mfma_f32_16x16x32_bf16 v[74:77], v[54:57], v[14:17], v[74:77]
	v_mfma_f32_16x16x32_bf16 v[78:81], v[58:61], v[10:13], 0
	v_mfma_f32_16x16x32_bf16 v[82:85], v[54:57], v[22:25], v[82:85]
	v_mfma_f32_16x16x32_bf16 v[86:89], v[58:61], v[18:21], 0
	v_mfma_f32_16x16x32_bf16 v[50:53], v[54:57], v[30:33], v[50:53]
	v_mfma_f32_16x16x32_bf16 v[54:57], v[58:61], v[26:29], 0
	s_waitcnt lgkmcnt(0)
	v_mfma_f32_16x16x32_bf16 v[70:73], v[62:65], v[6:9], v[70:73]
	v_mfma_f32_16x16x32_bf16 v[78:81], v[62:65], v[14:17], v[78:81]
	v_mfma_f32_16x16x32_bf16 v[86:89], v[62:65], v[22:25], v[86:89]
	v_mfma_f32_16x16x32_bf16 v[54:57], v[62:65], v[30:33], v[54:57]
	s_setprio 0
	v_fma_f32 v58, -v215, v49, v66
	v_exp_f32_e32 v59, v58
	v_fma_f32 v58, -v215, v90, v67
	v_exp_f32_e32 v61, v58
	v_fma_f32 v58, -v215, v91, v68
	v_exp_f32_e32 v63, v58
	v_fma_f32 v58, -v215, v92, v69
	v_exp_f32_e32 v65, v58
	v_fma_f32 v58, -v215, v93, v70
	v_exp_f32_e32 v67, v58
	v_fma_f32 v58, -v215, v94, v71
	v_exp_f32_e32 v69, v58
	v_fma_f32 v58, -v215, v95, v72
	v_exp_f32_e32 v71, v58
	v_fma_f32 v58, -v215, v96, v73
	v_exp_f32_e32 v73, v58
	v_fma_f32 v58, -v216, v49, v74
	v_exp_f32_e32 v58, v58
	v_fma_f32 v60, -v216, v90, v75
	v_exp_f32_e32 v60, v60
	v_fma_f32 v62, -v216, v91, v76
	v_exp_f32_e32 v62, v62
	v_fma_f32 v64, -v216, v92, v77
	v_exp_f32_e32 v64, v64
	v_fma_f32 v66, -v216, v93, v78
	v_exp_f32_e32 v66, v66
	v_fma_f32 v68, -v216, v94, v79
	v_add_f32_e32 v58, 0, v58
	v_add_f32_e32 v59, 0, v59
	v_exp_f32_e32 v68, v68
	v_fma_f32 v70, -v216, v95, v80
	v_add_f32_e32 v58, v60, v58
	v_add_f32_e32 v59, v61, v59
	v_exp_f32_e32 v70, v70
	v_fma_f32 v72, -v216, v96, v81
	v_add_f32_e32 v58, v62, v58
	v_add_f32_e32 v59, v63, v59
	v_exp_f32_e32 v72, v72
	v_add_f32_e32 v58, v64, v58
	v_add_f32_e32 v59, v65, v59
	s_nop 0
	v_add_f32_e32 v58, v66, v58
	v_add_f32_e32 v59, v67, v59
	s_nop 0
	v_add_f32_e32 v58, v68, v58
	v_add_f32_e32 v59, v69, v59
	s_nop 0
	v_add_f32_e32 v58, v70, v58
	v_add_f32_e32 v59, v71, v59
	s_nop 0
	v_add_f32_e32 v58, v72, v58
	v_add_f32_e32 v59, v73, v59
	s_nop 0
	v_add_f32_e32 v46, v46, v58
	v_add_f32_e32 v47, v47, v59
	v_fma_f32 v58, -v217, v49, v82
	v_exp_f32_e32 v59, v58
	v_fma_f32 v58, -v217, v90, v83
	v_exp_f32_e32 v61, v58
	v_fma_f32 v58, -v217, v91, v84
	v_exp_f32_e32 v63, v58
	v_fma_f32 v58, -v217, v92, v85
	v_exp_f32_e32 v65, v58
	v_fma_f32 v58, -v217, v93, v86
	v_exp_f32_e32 v67, v58
	v_fma_f32 v58, -v217, v94, v87
	v_exp_f32_e32 v69, v58
	v_fma_f32 v58, -v217, v95, v88
	v_exp_f32_e32 v71, v58
	v_fma_f32 v58, -v217, v96, v89
	v_fma_f32 v49, -v218, v49, v50
	v_exp_f32_e32 v73, v58
	v_exp_f32_e32 v58, v49
	v_fma_f32 v49, -v218, v90, v51
	v_exp_f32_e32 v60, v49
	v_fma_f32 v49, -v218, v91, v52
	v_exp_f32_e32 v62, v49
	v_fma_f32 v49, -v218, v92, v53
	v_exp_f32_e32 v64, v49
	v_fma_f32 v49, -v218, v93, v54
	v_exp_f32_e32 v66, v49
	v_fma_f32 v49, -v218, v94, v55
	v_add_f32_e32 v50, 0, v58
	v_add_f32_e32 v51, 0, v59
	v_exp_f32_e32 v68, v49
	v_fma_f32 v49, -v218, v95, v56
	v_add_f32_e32 v50, v60, v50
	v_add_f32_e32 v51, v61, v51
	v_exp_f32_e32 v70, v49
	v_fma_f32 v49, -v218, v96, v57
	v_add_f32_e32 v50, v62, v50
	v_add_f32_e32 v51, v63, v51
	v_exp_f32_e32 v72, v49
	v_add_f32_e32 v50, v64, v50
	v_add_f32_e32 v51, v65, v51
	s_nop 0
	v_add_f32_e32 v50, v66, v50
	v_add_f32_e32 v51, v67, v51
	s_nop 0
	v_add_f32_e32 v50, v68, v50
	v_add_f32_e32 v51, v69, v51
	s_nop 0
	v_add_f32_e32 v50, v70, v50
	v_add_f32_e32 v51, v71, v51
	s_nop 0
	v_add_f32_e32 v50, v72, v50
	v_add_f32_e32 v51, v73, v51
	s_nop 0
	v_add_f32_e32 v42, v42, v50
	v_add_f32_e32 v43, v43, v51
	s_branch .LBB0_2937

.LBB0_2944:
	s_waitcnt vmcnt(0)
	v_mov_b32_e32 v34, v47
	s_nop 1
	v_permlane16_swap_b32 v34, v47
	v_mov_b32_e32 v99, 0
	v_add_f32_e32 v45, v34, v47
	v_mov_b32_e32 v47, v45
	v_mov_b32_e32 v34, v46
	s_nop 1
	v_permlane32_swap_b32 v45, v47
	s_nop 1
	v_permlane16_swap_b32 v34, v46
	v_mov_b32_e32 v98, v99
	v_add_f32_e32 v46, v34, v46
	v_mov_b32_e32 v44, v46
	v_mov_b32_e32 v34, v43
	s_nop 1
	v_permlane32_swap_b32 v44, v46
	s_nop 1
	v_permlane16_swap_b32 v43, v34
	v_mov_b32_e32 v100, v99
	v_add_f32_e32 v43, v43, v34
	v_mov_b32_e32 v49, v43
	v_mov_b32_e32 v34, v42
	s_nop 1
	v_permlane32_swap_b32 v43, v49
	s_nop 1
	v_permlane16_swap_b32 v34, v42
	v_add_f32_e32 v44, v44, v46
	v_add_f32_e32 v45, v45, v47
	v_add_f32_e32 v42, v34, v42
	v_mov_b32_e32 v48, v42
	s_nop 1
	v_permlane32_swap_b32 v42, v48
	global_load_dwordx4 v[34:37], v[142:143], off
	global_load_dwordx4 v[38:41], v[138:139], off
	v_div_scale_f32 v46, s[14:15], v45, v45, 1.0
	v_div_scale_f32 v50, s[14:15], v44, v44, 1.0
	v_rcp_f32_e32 v51, v46
	v_rcp_f32_e32 v52, v50
	v_add_f32_e32 v42, v42, v48
	v_add_f32_e32 v43, v43, v49
	v_div_scale_f32 v47, vcc, 1.0, v45, 1.0
	v_fma_f32 v54, -v46, v51, 1.0
	v_fma_f32 v55, -v50, v52, 1.0
	v_fmac_f32_e32 v51, v54, v51
	v_div_scale_f32 v48, s[16:17], v43, v43, 1.0
	v_div_scale_f32 v53, s[14:15], 1.0, v44, 1.0
	v_fmac_f32_e32 v52, v55, v52
	v_div_scale_f32 v54, s[18:19], v42, v42, 1.0
	v_mul_f32_e32 v56, v47, v51
	v_rcp_f32_e32 v58, v48
	v_mul_f32_e32 v57, v53, v52
	v_rcp_f32_e32 v59, v54
	v_fma_f32 v60, -v46, v56, v47
	v_fma_f32 v61, -v50, v57, v53
	v_fmac_f32_e32 v56, v60, v51
	v_fmac_f32_e32 v57, v61, v52
	v_fma_f32 v46, -v46, v56, v47
	v_fma_f32 v47, -v50, v57, v53
	v_div_fmas_f32 v46, v46, v51, v56
	v_fma_f32 v50, -v48, v58, 1.0
	s_mov_b64 vcc, s[14:15]
	v_div_scale_f32 v49, s[16:17], 1.0, v43, 1.0
	v_fma_f32 v51, -v54, v59, 1.0
	v_div_fixup_f32 v46, v46, v45, 1.0
	v_div_fmas_f32 v47, v47, v52, v57
	v_fmac_f32_e32 v58, v50, v58
	v_cmp_lt_f32_e32 vcc, 0, v45
	v_div_scale_f32 v55, s[18:19], 1.0, v42, 1.0
	v_fmac_f32_e32 v59, v51, v59
	v_cndmask_b32_e32 v142, 0, v46, vcc
	v_mul_f32_e32 v46, v49, v58
	v_div_fixup_f32 v45, v47, v44, 1.0
	v_mul_f32_e32 v47, v55, v59
	v_cmp_lt_f32_e32 vcc, 0, v44
	v_fma_f32 v44, -v48, v46, v49
	v_fmac_f32_e32 v46, v44, v58
	v_cndmask_b32_e32 v150, 0, v45, vcc
	v_fma_f32 v45, -v54, v47, v55
	v_fmac_f32_e32 v47, v45, v59
	v_fma_f32 v44, -v48, v46, v49
	s_mov_b64 vcc, s[16:17]
	v_fma_f32 v45, -v54, v47, v55
	v_div_fmas_f32 v44, v44, v58, v46
	s_mov_b64 vcc, s[18:19]
	v_div_fixup_f32 v44, v44, v43, 1.0
	v_div_fmas_f32 v45, v45, v59, v47
	v_cmp_lt_f32_e32 vcc, 0, v43
	v_div_fixup_f32 v43, v45, v42, 1.0
	v_readlane_b32 s14, v254, 60
	v_cndmask_b32_e32 v152, 0, v44, vcc
	v_cmp_lt_f32_e32 vcc, 0, v42
	v_mov_b32_e32 v101, v99
	v_mov_b64_e32 v[66:67], v[98:99]
	v_cndmask_b32_e32 v154, 0, v43, vcc
	s_waitcnt vmcnt(1)
	ds_write_b128 v212, v[34:37]
	s_waitcnt vmcnt(0)
	ds_write_b128 v213, v[38:41]
	v_mul_u32_u24_e32 v34, 0x210, v208
	v_add3_u32 v159, v131, s14, v34
	v_mov_b64_e32 v[70:71], v[98:99]
	v_mov_b64_e32 v[74:75], v[98:99]
	v_mov_b64_e32 v[78:79], v[98:99]
	v_mov_b64_e32 v[82:83], v[98:99]
	v_mov_b64_e32 v[86:87], v[98:99]
	v_mov_b64_e32 v[90:91], v[98:99]
	v_mov_b64_e32 v[94:95], v[98:99]
	v_mov_b64_e32 v[62:63], v[98:99]
	v_mov_b64_e32 v[58:59], v[98:99]
	v_mov_b64_e32 v[54:55], v[98:99]
	v_mov_b64_e32 v[50:51], v[98:99]
	v_mov_b64_e32 v[46:47], v[98:99]
	v_mov_b64_e32 v[42:43], v[98:99]
	v_mov_b64_e32 v[38:39], v[98:99]
	v_mov_b64_e32 v[34:35], v[98:99]
	s_mov_b32 s21, 0
	s_movk_i32 s18, 0x90
	v_mul_u32_u24_e32 v211, 0x90, v208
	v_add_u32_e32 v167, v159, v144
	v_mov_b32_e32 v155, v154
	v_mov_b32_e32 v153, v152
	v_mov_b32_e32 v151, v150
	v_mov_b32_e32 v143, v142
	v_mov_b32_e32 v168, 0x49742400
	v_mov_b64_e32 v[68:69], v[100:101]
	v_mov_b64_e32 v[72:73], v[100:101]
	v_mov_b64_e32 v[76:77], v[100:101]
	v_mov_b64_e32 v[80:81], v[100:101]
	v_mov_b64_e32 v[84:85], v[100:101]
	v_mov_b64_e32 v[88:89], v[100:101]
	v_mov_b64_e32 v[92:93], v[100:101]
	v_mov_b64_e32 v[96:97], v[100:101]
	v_mov_b64_e32 v[64:65], v[100:101]
	v_mov_b64_e32 v[60:61], v[100:101]
	v_mov_b64_e32 v[56:57], v[100:101]
	v_mov_b64_e32 v[52:53], v[100:101]
	v_mov_b64_e32 v[48:49], v[100:101]
	v_mov_b64_e32 v[44:45], v[100:101]
	v_mov_b64_e32 v[40:41], v[100:101]
	v_mov_b64_e32 v[36:37], v[100:101]
	s_mov_b32 s19, 0
	s_waitcnt lgkmcnt(0)
	s_barrier

.LBB0_3106:
	s_lshl_b32 s7, s6, 5
	v_or_b32_e32 v141, s7, v208
	v_mad_u32_u24 v141, v141, s13, v138
	ds_read_b128 v[148:151], v141
	ds_read_b128 v[152:155], v141 offset:64
	ds_read_b128 v[156:159], v141 offset:2304
	ds_read_b128 v[160:163], v141 offset:2368
	v_lshl_add_u32 v141, s6, 6, v139
	ds_read_b128 v[164:167], v141 offset:9216
	ds_read_b128 v[168:171], v141 offset:11520
	ds_read_b128 v[176:179], v141 offset:13824
	ds_read_b128 v[180:183], v141 offset:16128
	v_add_u32_e32 v141, s7, v140
	v_sub_u32_e32 v142, v209, v141
	v_cmp_gt_u32_e32 vcc, 2.0, v142
	v_cvt_f32_i32_e32 v142, v142
	v_xad_u32 v143, v141, -1, v209
	v_cvt_f32_i32_e32 v172, v143
	s_and_b64 vcc, s[0:1], vcc
	v_cndmask_b32_e32 v174, v222, v142, vcc
	v_cmp_gt_u32_e32 vcc, 2.0, v143
	v_or_b32_e32 v142, 2, v141
	s_and_b64 vcc, s[0:1], vcc
	v_sub_u32_e32 v142, v209, v142
	v_cndmask_b32_e32 v223, v222, v172, vcc
	v_cmp_gt_u32_e32 vcc, 2.0, v142
	v_cvt_f32_i32_e32 v142, v142
	v_or_b32_e32 v143, 3, v141
	v_sub_u32_e32 v143, v209, v143
	v_cvt_f32_i32_e32 v172, v143
	s_and_b64 vcc, s[0:1], vcc
	v_cndmask_b32_e32 v226, v222, v142, vcc
	v_cmp_gt_u32_e32 vcc, 2.0, v143
	v_or_b32_e32 v142, 4, v141
	s_and_b64 vcc, s[0:1], vcc
	v_sub_u32_e32 v142, v209, v142
	v_cndmask_b32_e32 v227, v222, v172, vcc
	v_cmp_gt_u32_e32 vcc, 2.0, v142
	v_cvt_f32_i32_e32 v142, v142
	v_or_b32_e32 v143, 5, v141
	v_sub_u32_e32 v143, v209, v143
	v_cvt_f32_i32_e32 v172, v143
	s_and_b64 vcc, s[0:1], vcc
	v_cndmask_b32_e32 v228, v222, v142, vcc
	v_cmp_gt_u32_e32 vcc, 2.0, v143
	v_or_b32_e32 v142, 6, v141
	s_and_b64 vcc, s[0:1], vcc
	v_sub_u32_e32 v142, v209, v142
	v_cndmask_b32_e32 v229, v222, v172, vcc
	v_cmp_gt_u32_e32 vcc, 2.0, v142
	v_cvt_f32_i32_e32 v142, v142
	v_or_b32_e32 v141, 7, v141
	v_sub_u32_e32 v141, v209, v141
	v_cvt_f32_i32_e32 v143, v141
	s_and_b64 vcc, s[0:1], vcc
	v_cndmask_b32_e32 v230, v222, v142, vcc
	v_cmp_gt_u32_e32 vcc, 2.0, v141
	s_and_b64 vcc, s[0:1], vcc
	s_nop 0
	v_cndmask_b32_e32 v141, v222, v143, vcc
	s_setprio 1
	s_waitcnt lgkmcnt(7)
	v_mfma_f32_16x16x32_bf16 v[184:187], v[148:151], v[2:5], 0
	v_mfma_f32_16x16x32_bf16 v[192:195], v[148:151], v[10:13], 0
	v_mfma_f32_16x16x32_bf16 v[200:203], v[148:151], v[18:21], 0
	v_mfma_f32_16x16x32_bf16 v[148:151], v[148:151], v[26:29], 0
	s_waitcnt lgkmcnt(6)
	v_mfma_f32_16x16x32_bf16 v[184:187], v[152:155], v[6:9], v[184:187]
	s_waitcnt lgkmcnt(5)
	v_mfma_f32_16x16x32_bf16 v[188:191], v[156:159], v[2:5], 0
	v_mfma_f32_16x16x32_bf16 v[192:195], v[152:155], v[14:17], v[192:195]
	v_mfma_f32_16x16x32_bf16 v[196:199], v[156:159], v[10:13], 0
	v_mfma_f32_16x16x32_bf16 v[200:203], v[152:155], v[22:25], v[200:203]
	v_mfma_f32_16x16x32_bf16 v[204:207], v[156:159], v[18:21], 0
	v_mfma_f32_16x16x32_bf16 v[148:151], v[152:155], v[30:33], v[148:151]
	v_mfma_f32_16x16x32_bf16 v[152:155], v[156:159], v[26:29], 0
	s_waitcnt lgkmcnt(4)
	v_mfma_f32_16x16x32_bf16 v[188:191], v[160:163], v[6:9], v[188:191]
	v_mfma_f32_16x16x32_bf16 v[196:199], v[160:163], v[14:17], v[196:199]
	v_mfma_f32_16x16x32_bf16 v[204:207], v[160:163], v[22:25], v[204:207]
	v_mfma_f32_16x16x32_bf16 v[152:155], v[160:163], v[30:33], v[152:155]
	s_setprio 0
	v_fma_f32 v142, -v215, v174, v184
	v_exp_f32_e32 v143, v142
	v_fma_f32 v142, -v215, v223, v185
	v_exp_f32_e32 v161, v142
	v_fma_f32 v142, -v215, v226, v186
	v_exp_f32_e32 v163, v142
	v_fma_f32 v142, -v215, v227, v187
	v_exp_f32_e32 v173, v142
	v_fma_f32 v142, -v215, v228, v188
	v_exp_f32_e32 v185, v142
	v_fma_f32 v142, -v215, v229, v189
	v_exp_f32_e32 v187, v142
	v_fma_f32 v142, -v215, v230, v190
	v_exp_f32_e32 v189, v142
	v_fma_f32 v142, -v215, v141, v191
	v_exp_f32_e32 v191, v142
	v_fma_f32 v142, -v216, v174, v192
	v_exp_f32_e32 v142, v142
	v_fma_f32 v160, -v216, v223, v193
	v_exp_f32_e32 v160, v160
	v_fma_f32 v162, -v216, v226, v194
	v_exp_f32_e32 v162, v162
	v_fma_f32 v172, -v216, v227, v195
	v_exp_f32_e32 v172, v172
	v_fma_f32 v184, -v216, v228, v196
	v_exp_f32_e32 v184, v184
	v_fma_f32 v186, -v216, v229, v197
	v_add_f32_e32 v192, 0, v142
	v_add_f32_e32 v193, 0, v143
	v_exp_f32_e32 v186, v186
	v_fma_f32 v188, -v216, v230, v198
	v_add_f32_e32 v192, v160, v192
	v_add_f32_e32 v193, v161, v193
	v_exp_f32_e32 v188, v188
	v_fma_f32 v190, -v216, v141, v199
	v_add_f32_e32 v192, v162, v192
	v_add_f32_e32 v193, v163, v193
	v_exp_f32_e32 v190, v190
	v_add_f32_e32 v192, v172, v192
	v_add_f32_e32 v193, v173, v193
	v_cvt_pk_bf16_f32 v160, v142, v160
	v_fma_f32 v142, -v217, v174, v200
	v_cvt_pk_bf16_f32 v156, v143, v161
	v_add_f32_e32 v192, v184, v192
	v_add_f32_e32 v193, v185, v193
	v_exp_f32_e32 v143, v142
	v_fma_f32 v142, -v217, v223, v201
	v_cvt_pk_bf16_f32 v157, v163, v173
	v_add_f32_e32 v192, v186, v192
	v_add_f32_e32 v193, v187, v193
	v_exp_f32_e32 v173, v142
	v_fma_f32 v142, -v217, v226, v202
	v_cvt_pk_bf16_f32 v159, v189, v191
	v_add_f32_e32 v192, v188, v192
	v_add_f32_e32 v193, v189, v193
	v_exp_f32_e32 v189, v142
	v_fma_f32 v142, -v217, v227, v203
	v_add_f32_e32 v192, v190, v192
	v_add_f32_e32 v193, v191, v193
	v_exp_f32_e32 v191, v142
	v_fma_f32 v142, -v217, v228, v204
	v_add_f32_e32 v122, v122, v192
	v_add_f32_e32 v123, v123, v193
	v_exp_f32_e32 v193, v142
	v_fma_f32 v142, -v217, v229, v205
	v_exp_f32_e32 v195, v142
	v_fma_f32 v142, -v217, v230, v206
	v_exp_f32_e32 v197, v142
	v_fma_f32 v142, -v217, v141, v207
	v_exp_f32_e32 v199, v142
	v_fma_f32 v142, -v218, v174, v148
	v_fma_f32 v148, -v218, v223, v149
	v_cvt_pk_bf16_f32 v161, v162, v172
	v_exp_f32_e32 v172, v148
	v_fma_f32 v148, -v218, v226, v150
	v_cvt_pk_bf16_f32 v163, v188, v190
	v_exp_f32_e32 v142, v142
	v_exp_f32_e32 v188, v148
	v_fma_f32 v148, -v218, v227, v151
	v_exp_f32_e32 v190, v148
	v_fma_f32 v148, -v218, v228, v152
	v_exp_f32_e32 v192, v148
	v_fma_f32 v148, -v218, v229, v153
	v_exp_f32_e32 v194, v148
	v_fma_f32 v148, -v218, v230, v154
	v_exp_f32_e32 v196, v148
	v_add_f32_e32 v148, 0, v142
	v_add_f32_e32 v149, 0, v143
	v_fma_f32 v141, -v218, v141, v155
	v_add_f32_e32 v148, v172, v148
	v_add_f32_e32 v149, v173, v149
	v_exp_f32_e32 v198, v141
	v_add_f32_e32 v148, v188, v148
	v_add_f32_e32 v149, v189, v149
	v_cvt_pk_bf16_f32 v158, v185, v187
	v_add_f32_e32 v148, v190, v148
	v_add_f32_e32 v149, v191, v149
	v_cvt_pk_bf16_f32 v162, v184, v186
	v_add_f32_e32 v148, v192, v148
	v_add_f32_e32 v149, v193, v149
	v_cvt_pk_bf16_f32 v184, v143, v173
	v_add_f32_e32 v148, v194, v148
	v_add_f32_e32 v149, v195, v149
	v_cvt_pk_bf16_f32 v185, v189, v191
	v_add_f32_e32 v148, v196, v148
	v_add_f32_e32 v149, v197, v149
	v_cvt_pk_bf16_f32 v186, v193, v195
	v_add_f32_e32 v148, v198, v148
	v_add_f32_e32 v149, v199, v149
	v_cvt_pk_bf16_f32 v187, v197, v199
	v_add_f32_e32 v120, v120, v148
	v_add_f32_e32 v121, v121, v149
	v_cvt_pk_bf16_f32 v148, v142, v172
	v_cvt_pk_bf16_f32 v149, v188, v190
	v_cvt_pk_bf16_f32 v150, v192, v194
	v_cvt_pk_bf16_f32 v151, v196, v198
	s_setprio 1
	s_waitcnt lgkmcnt(3)
	v_mfma_f32_16x16x32_bf16 v[34:37], v[164:167], v[156:159], v[34:37]
	s_waitcnt lgkmcnt(2)
	v_mfma_f32_16x16x32_bf16 v[38:41], v[168:171], v[156:159], v[38:41]
	s_waitcnt lgkmcnt(1)
	v_mfma_f32_16x16x32_bf16 v[42:45], v[176:179], v[156:159], v[42:45]
	s_waitcnt lgkmcnt(0)
	v_mfma_f32_16x16x32_bf16 v[46:49], v[180:183], v[156:159], v[46:49]
	v_mfma_f32_16x16x32_bf16 v[50:53], v[164:167], v[160:163], v[50:53]
	v_mfma_f32_16x16x32_bf16 v[54:57], v[168:171], v[160:163], v[54:57]
	v_mfma_f32_16x16x32_bf16 v[58:61], v[176:179], v[160:163], v[58:61]
	v_mfma_f32_16x16x32_bf16 v[62:65], v[180:183], v[160:163], v[62:65]
	v_mfma_f32_16x16x32_bf16 v[66:69], v[164:167], v[184:187], v[66:69]
	v_mfma_f32_16x16x32_bf16 v[70:73], v[168:171], v[184:187], v[70:73]
	v_mfma_f32_16x16x32_bf16 v[74:77], v[176:179], v[184:187], v[74:77]
	v_mfma_f32_16x16x32_bf16 v[78:81], v[180:183], v[184:187], v[78:81]
	v_mfma_f32_16x16x32_bf16 v[82:85], v[164:167], v[148:151], v[82:85]
	v_mfma_f32_16x16x32_bf16 v[86:89], v[168:171], v[148:151], v[86:89]
	v_mfma_f32_16x16x32_bf16 v[90:93], v[176:179], v[148:151], v[90:93]
	v_mfma_f32_16x16x32_bf16 v[94:97], v[180:183], v[148:151], v[94:97]
	s_setprio 0
	s_mov_b32 s6, 1
	s_and_b64 vcc, exec, s[4:5]
	s_mov_b64 s[4:5], 0
	s_cbranch_vccnz .LBB0_3106

.LBB0_3123:
	s_lshl_b32 s17, s15, 5
	s_or_b32 s16, s17, s0
	s_cmp_gt_i32 s16, s10
	s_cselect_b64 s[18:19], -1, 0
	s_or_b32 s20, s16, 31
	s_cmp_lt_i32 s20, s3
	s_cselect_b64 s[20:21], -1, 0
	s_or_b64 s[18:19], s[18:19], s[20:21]
	s_and_b64 vcc, exec, s[18:19]
	s_cbranch_vccnz .LBB0_3122
	v_or_b32_e32 v131, s17, v208
	v_mad_u32_u24 v131, v131, s12, v124
	ds_read_b128 v[132:135], v131
	ds_read_b128 v[136:139], v131 offset:64
	ds_read_b128 v[140:143], v131 offset:2304
	ds_read_b128 v[148:151], v131 offset:2368
	v_lshl_add_u32 v131, s15, 6, v130
	ds_read_b128 v[152:155], v131 offset:9216
	ds_read_b128 v[156:159], v131 offset:11520
	ds_read_b128 v[160:163], v131 offset:13824
	ds_read_b128 v[164:167], v131 offset:16128
	v_add_u32_e32 v131, s16, v144
	v_sub_u32_e32 v168, v209, v131
	v_cvt_f32_i32_e32 v169, v168
	v_xad_u32 v170, v131, -1, v209
	v_cvt_f32_i32_e32 v171, v170
	v_cmp_gt_u32_e32 vcc, s13, v168
	v_or_b32_e32 v168, 2, v131
	v_sub_u32_e32 v168, v209, v168
	v_cndmask_b32_e32 v196, v1, v169, vcc
	v_cmp_gt_u32_e32 vcc, s13, v170
	v_cvt_f32_i32_e32 v169, v168
	v_or_b32_e32 v170, 3, v131
	v_sub_u32_e32 v170, v209, v170
	v_cndmask_b32_e32 v197, v1, v171, vcc
	v_cvt_f32_i32_e32 v171, v170
	v_cmp_gt_u32_e32 vcc, s13, v168
	v_or_b32_e32 v168, 4, v131
	v_sub_u32_e32 v168, v209, v168
	v_cndmask_b32_e32 v198, v1, v169, vcc
	v_cvt_f32_i32_e32 v169, v168
	v_cmp_gt_u32_e32 vcc, s13, v170
	v_or_b32_e32 v170, 5, v131
	v_sub_u32_e32 v170, v209, v170
	v_cndmask_b32_e32 v199, v1, v171, vcc
	v_cmp_gt_u32_e32 vcc, s13, v168
	v_or_b32_e32 v168, 6, v131
	v_cvt_f32_i32_e32 v171, v170
	v_sub_u32_e32 v168, v209, v168
	v_or_b32_e32 v131, 7, v131
	v_cndmask_b32_e32 v200, v1, v169, vcc
	v_cvt_f32_i32_e32 v169, v168
	v_sub_u32_e32 v131, v209, v131
	v_cmp_gt_u32_e32 vcc, s13, v170
	v_cvt_f32_i32_e32 v170, v131
	s_nop 0
	v_cndmask_b32_e32 v201, v1, v171, vcc
	v_cmp_gt_u32_e32 vcc, s13, v168
	s_nop 1
	v_cndmask_b32_e32 v202, v1, v169, vcc
	v_cmp_gt_u32_e32 vcc, s13, v131
	s_nop 1
	v_cndmask_b32_e32 v131, v1, v170, vcc
	s_setprio 1
	s_waitcnt lgkmcnt(7)
	v_mfma_f32_16x16x32_bf16 v[168:171], v[132:135], v[2:5], 0
	v_mfma_f32_16x16x32_bf16 v[176:179], v[132:135], v[10:13], 0
	v_mfma_f32_16x16x32_bf16 v[184:187], v[132:135], v[18:21], 0
	v_mfma_f32_16x16x32_bf16 v[132:135], v[132:135], v[26:29], 0
	s_waitcnt lgkmcnt(6)
	v_mfma_f32_16x16x32_bf16 v[168:171], v[136:139], v[6:9], v[168:171]
	s_waitcnt lgkmcnt(5)
	v_mfma_f32_16x16x32_bf16 v[172:175], v[140:143], v[2:5], 0
	v_mfma_f32_16x16x32_bf16 v[176:179], v[136:139], v[14:17], v[176:179]
	v_mfma_f32_16x16x32_bf16 v[180:183], v[140:143], v[10:13], 0
	v_mfma_f32_16x16x32_bf16 v[184:187], v[136:139], v[22:25], v[184:187]
	v_mfma_f32_16x16x32_bf16 v[188:191], v[140:143], v[18:21], 0
	v_mfma_f32_16x16x32_bf16 v[132:135], v[136:139], v[30:33], v[132:135]
	v_mfma_f32_16x16x32_bf16 v[136:139], v[140:143], v[26:29], 0
	s_waitcnt lgkmcnt(4)
	v_mfma_f32_16x16x32_bf16 v[172:175], v[148:151], v[6:9], v[172:175]
	v_mfma_f32_16x16x32_bf16 v[180:183], v[148:151], v[14:17], v[180:183]
	v_mfma_f32_16x16x32_bf16 v[188:191], v[148:151], v[22:25], v[188:191]
	v_mfma_f32_16x16x32_bf16 v[136:139], v[148:151], v[30:33], v[136:139]
	s_setprio 0
	v_fma_f32 v140, -v215, v196, v168
	v_fma_f32 v148, -v216, v196, v176
	v_exp_f32_e32 v149, v140
	v_fma_f32 v140, -v215, v197, v169
	v_exp_f32_e32 v148, v148
	v_fma_f32 v150, -v216, v197, v177
	v_exp_f32_e32 v151, v140
	v_fma_f32 v140, -v215, v198, v170
	v_exp_f32_e32 v150, v150
	v_fma_f32 v168, -v216, v198, v178
	v_exp_f32_e32 v169, v140
	v_fma_f32 v140, -v215, v199, v171
	v_exp_f32_e32 v168, v168
	v_fma_f32 v170, -v216, v199, v179
	v_exp_f32_e32 v171, v140
	v_fma_f32 v140, -v215, v200, v172
	v_exp_f32_e32 v170, v170
	v_fma_f32 v172, -v216, v200, v180
	v_exp_f32_e32 v193, v140
	v_fma_f32 v140, -v215, v201, v173
	v_exp_f32_e32 v192, v172
	v_fma_f32 v172, -v216, v201, v181
	v_add_f32_e32 v176, 0, v148
	v_add_f32_e32 v177, 0, v149
	v_exp_f32_e32 v173, v140
	v_fma_f32 v140, -v215, v202, v174
	v_exp_f32_e32 v172, v172
	v_fma_f32 v174, -v216, v202, v182
	v_add_f32_e32 v176, v150, v176
	v_add_f32_e32 v177, v151, v177
	v_exp_f32_e32 v195, v140
	v_fma_f32 v140, -v215, v131, v175
	v_exp_f32_e32 v194, v174
	v_fma_f32 v174, -v216, v131, v183
	v_add_f32_e32 v176, v168, v176
	v_add_f32_e32 v177, v169, v177
	v_exp_f32_e32 v175, v140
	v_exp_f32_e32 v174, v174
	v_add_f32_e32 v176, v170, v176
	v_add_f32_e32 v177, v171, v177
	v_fma_f32 v132, -v218, v196, v132
	v_add_f32_e32 v176, v192, v176
	v_add_f32_e32 v177, v193, v177
	v_cvt_pk_bf16_f32 v148, v148, v150
	v_add_f32_e32 v176, v172, v176
	v_add_f32_e32 v177, v173, v177
	v_cvt_pk_bf16_f32 v150, v192, v172
	v_add_f32_e32 v176, v194, v176
	v_add_f32_e32 v177, v195, v177
	v_exp_f32_e32 v172, v132
	v_fma_f32 v132, -v218, v197, v133
	v_cvt_pk_bf16_f32 v140, v149, v151
	v_add_f32_e32 v176, v174, v176
	v_add_f32_e32 v177, v175, v177
	v_cvt_pk_bf16_f32 v149, v168, v170
	v_cvt_pk_bf16_f32 v151, v194, v174
	v_fma_f32 v168, -v217, v196, v184
	v_exp_f32_e32 v174, v132
	v_fma_f32 v132, -v218, v198, v134
	v_cvt_pk_bf16_f32 v142, v193, v173
	v_add_f32_e32 v122, v122, v176
	v_add_f32_e32 v123, v123, v177
	v_exp_f32_e32 v173, v168
	v_fma_f32 v168, -v217, v197, v185
	v_exp_f32_e32 v176, v132
	v_fma_f32 v132, -v218, v199, v135
	v_cvt_pk_bf16_f32 v143, v195, v175
	v_exp_f32_e32 v175, v168
	v_fma_f32 v168, -v217, v198, v186
	v_exp_f32_e32 v178, v132
	v_fma_f32 v132, -v218, v200, v136
	v_exp_f32_e32 v177, v168
	v_fma_f32 v168, -v217, v199, v187
	v_exp_f32_e32 v180, v132
	v_fma_f32 v132, -v218, v201, v137
	v_exp_f32_e32 v179, v168
	v_fma_f32 v168, -v217, v200, v188
	v_exp_f32_e32 v182, v132
	v_fma_f32 v132, -v218, v202, v138
	v_exp_f32_e32 v181, v168
	v_fma_f32 v168, -v217, v201, v189
	v_exp_f32_e32 v184, v132
	v_add_f32_e32 v132, 0, v172
	v_add_f32_e32 v133, 0, v173
	v_exp_f32_e32 v183, v168
	v_fma_f32 v168, -v217, v202, v190
	v_add_f32_e32 v132, v174, v132
	v_add_f32_e32 v133, v175, v133
	v_exp_f32_e32 v185, v168
	v_fma_f32 v168, -v217, v131, v191
	v_fma_f32 v131, -v218, v131, v139
	v_add_f32_e32 v132, v176, v132
	v_add_f32_e32 v133, v177, v133
	v_exp_f32_e32 v187, v168
	v_exp_f32_e32 v186, v131
	v_add_f32_e32 v132, v178, v132
	v_add_f32_e32 v133, v179, v133
	v_cvt_pk_bf16_f32 v141, v169, v171
	v_add_f32_e32 v132, v180, v132
	v_add_f32_e32 v133, v181, v133
	v_cvt_pk_bf16_f32 v168, v173, v175
	v_add_f32_e32 v132, v182, v132
	v_add_f32_e32 v133, v183, v133
	v_cvt_pk_bf16_f32 v169, v177, v179
	v_add_f32_e32 v132, v184, v132
	v_add_f32_e32 v133, v185, v133
	v_cvt_pk_bf16_f32 v170, v181, v183
	v_add_f32_e32 v132, v186, v132
	v_add_f32_e32 v133, v187, v133
	v_cvt_pk_bf16_f32 v171, v185, v187
	v_add_f32_e32 v120, v120, v132
	v_add_f32_e32 v121, v121, v133
	v_cvt_pk_bf16_f32 v132, v172, v174
	v_cvt_pk_bf16_f32 v133, v176, v178
	v_cvt_pk_bf16_f32 v134, v180, v182
	v_cvt_pk_bf16_f32 v135, v184, v186
	s_setprio 1
	s_waitcnt lgkmcnt(3)
	v_mfma_f32_16x16x32_bf16 v[94:97], v[152:155], v[140:143], v[94:97]
	s_waitcnt lgkmcnt(2)
	v_mfma_f32_16x16x32_bf16 v[90:93], v[156:159], v[140:143], v[90:93]
	s_waitcnt lgkmcnt(1)
	v_mfma_f32_16x16x32_bf16 v[86:89], v[160:163], v[140:143], v[86:89]
	s_waitcnt lgkmcnt(0)
	v_mfma_f32_16x16x32_bf16 v[82:85], v[164:167], v[140:143], v[82:85]
	v_mfma_f32_16x16x32_bf16 v[78:81], v[152:155], v[148:151], v[78:81]
	v_mfma_f32_16x16x32_bf16 v[74:77], v[156:159], v[148:151], v[74:77]
	v_mfma_f32_16x16x32_bf16 v[70:73], v[160:163], v[148:151], v[70:73]
	v_mfma_f32_16x16x32_bf16 v[66:69], v[164:167], v[148:151], v[66:69]
	v_mfma_f32_16x16x32_bf16 v[62:65], v[152:155], v[168:171], v[62:65]
	v_mfma_f32_16x16x32_bf16 v[58:61], v[156:159], v[168:171], v[58:61]
	v_mfma_f32_16x16x32_bf16 v[54:57], v[160:163], v[168:171], v[54:57]
	v_mfma_f32_16x16x32_bf16 v[50:53], v[164:167], v[168:171], v[50:53]
	v_mfma_f32_16x16x32_bf16 v[46:49], v[152:155], v[132:135], v[46:49]
	v_mfma_f32_16x16x32_bf16 v[42:45], v[156:159], v[132:135], v[42:45]
	v_mfma_f32_16x16x32_bf16 v[38:41], v[160:163], v[132:135], v[38:41]
	v_mfma_f32_16x16x32_bf16 v[34:37], v[164:167], v[132:135], v[34:37]
	s_setprio 0
	s_branch .LBB0_3122
